# K-loops: redundant s_waitcnt lgkmcnt(0) after s_setprio 1 removed at the 32 MFMA cluster starts (already waited before the barrier); on top of v_p14
# speedup vs baseline: 1.0081x; 1.0081x over previous
; #define PG8_STAGE(bufoff, gbase, voff) do { _Pragma("unroll") for (int _i = 0; _i < 2; ++_i) \
;         __builtin_amdgcn_global_load_lds((const unsigned*)((const char*)(gbase) + (voff)[_i]), (PG8_LAS unsigned*)(lds + (bufoff) + ldsw + _i * 8192), 16, 0, 0); } while (0)
; #define PG8_LDA(dst, b, h) do { _Pragma("unroll") for (int m = 0; m < 4; ++m) _Pragma("unroll") for (int k = 0; k < 2; ++k) dst[m][k] = *(const PG8_LAS bf16x8*)(lds + PG8_SA(b, h) + aoff + m * 2048 + k * 1024); } while (0)
; #define PG8_LDB(dst, b, h) do { _Pragma("unroll") for (int n = 0; n < 2; ++n) _Pragma("unroll") for (int k = 0; k < 2; ++k) dst[n][k] = *(const PG8_LAS bf16x8*)(lds + PG8_SB(b, h) + boff + n * 2048 + k * 1024); } while (0)
; #define PG8_WAIT_V(n) asm volatile("s_waitcnt vmcnt(" #n ")" ::: "memory")
; #define PG8_WAIT_L(n) asm volatile("s_waitcnt lgkmcnt(" #n ")" ::: "memory")
; #define PG8_BAR __builtin_amdgcn_s_barrier()
; #define PG8_SCHED __builtin_amdgcn_sched_barrier(0)
; template <class Epi, class Sched, bool ALIGN_EPI = false, bool SP2 = false>
; __device__ __forceinline__ void gemm_phase(PG8_LAS unsigned char* lds, const Gemm g, const Sched& S, const Epi& E) {
;     ...
;         const char* nA = has_next ? (const char*)g.A + (size_t)nxt.pm * tstep : cA; const char* nB = has_next ? (const char*)g.Bt + (size_t)nxt.pn * tstep : cB;
;         for (int t = 0; t < nt; t += 2) {
;             const bool last = (t == nt - 2);
;             const char* a1 = cA + (size_t)(t + 1) * kstep;
;             const char* a2 = last ? nA : cA + (size_t)(t + 2) * kstep; const char* b2 = last ? nB : cB + (size_t)(t + 2) * kstep;
;             const char* a3 = a2 + kstep; const char* b3 = b2 + kstep;
;             if (last && has_next) S.a_ready(nxt);
;             if constexpr (SP2) {
;             PG8_LDB(B0, 0, 0); PG8_LDB(B1, 0, 1); PG8_SCHED; PG8_LDA(At, 0, 0); PG8_STAGE(PG8_SA(1, 1), a1 + hstep, voffA);
;             PG8_WAIT_V(8); PG8_WAIT_L(0); PG8_BAR; PG8_MMA(0, 0, At, B0); PG8_MMA(0, 1, At, B1); PG8_BAR; PG8_SCHED;
;             PG8_LDA(At, 0, 1); PG8_STAGE(PG8_SB(0, 0), b2, voffB); PG8_STAGE(PG8_SB(0, 1), b2 + hstep, voffB); PG8_STAGE(PG8_SA(0, 0), a2, voffA);
;             PG8_WAIT_V(8); PG8_WAIT_L(0); PG8_BAR; PG8_MMA(1, 0, At, B0); PG8_MMA(1, 1, At, B1); PG8_BAR; PG8_SCHED;
.LBB0_341:
	ds_read_b128 v[146:149], v159
	ds_read_b128 v[150:153], v159 offset:1024
	ds_read_b128 v[164:167], v159 offset:2048
	ds_read_b128 v[168:171], v159 offset:3072
	ds_read_b128 v[172:175], v160
	ds_read_b128 v[176:179], v160 offset:1024
	ds_read_b128 v[180:183], v160 offset:2048
	ds_read_b128 v[184:187], v160 offset:3072
	s_add_u32 s14, s10, 0xfff80080
	s_addc_u32 s15, s11, -1
	s_cmp_eq_u32 s48, 28
	s_cselect_b32 s87, s7, s15
	s_cselect_b32 s86, s9, s14
	s_cselect_b32 s15, s12, s47
	s_cselect_b32 s14, s45, s46
	v_lshl_add_u64 v[154:155], s[10:11], 0, v[136:137]
	s_add_i32 m0, s91, 0xc000
	ds_read_b128 v[188:191], v161
	ds_read_b128 v[192:195], v161 offset:1024
	ds_read_b128 v[196:199], v161 offset:2048
	ds_read_b128 v[200:203], v161 offset:3072
	ds_read_b128 v[204:207], v161 offset:4096
	ds_read_b128 v[208:211], v161 offset:5120
	ds_read_b128 v[212:215], v161 offset:6144
	ds_read_b128 v[216:219], v161 offset:7168
	global_load_lds_dwordx4 v[154:155], off
	v_lshl_add_u64 v[154:155], s[10:11], 0, v[138:139]
	s_add_i32 m0, s91, 0xe000
	s_nop 0
	global_load_lds_dwordx4 v[154:155], off
	s_waitcnt vmcnt(8)
	s_waitcnt lgkmcnt(0)
	s_barrier
	s_setprio 1
	v_mfma_f32_16x16x32_bf16 v[124:127], v[146:149], v[188:191], v[124:127]
	v_mfma_f32_16x16x32_bf16 v[120:123], v[164:167], v[188:191], v[120:123]
	v_mfma_f32_16x16x32_bf16 v[108:111], v[146:149], v[196:199], v[108:111]
	v_mfma_f32_16x16x32_bf16 v[104:107], v[164:167], v[196:199], v[104:107]
	v_mfma_f32_16x16x32_bf16 v[92:95], v[146:149], v[204:207], v[92:95]
	v_mfma_f32_16x16x32_bf16 v[88:91], v[164:167], v[204:207], v[88:91]
	v_mfma_f32_16x16x32_bf16 v[76:79], v[146:149], v[212:215], v[76:79]
	v_mfma_f32_16x16x32_bf16 v[72:75], v[164:167], v[212:215], v[72:75]
	v_mfma_f32_16x16x32_bf16 v[124:127], v[150:153], v[192:195], v[124:127]
	v_mfma_f32_16x16x32_bf16 v[120:123], v[168:171], v[192:195], v[120:123]
	v_mfma_f32_16x16x32_bf16 v[108:111], v[150:153], v[200:203], v[108:111]
	v_mfma_f32_16x16x32_bf16 v[104:107], v[168:171], v[200:203], v[104:107]
	v_mfma_f32_16x16x32_bf16 v[92:95], v[150:153], v[208:211], v[92:95]
	v_mfma_f32_16x16x32_bf16 v[88:91], v[168:171], v[208:211], v[88:91]
	v_mfma_f32_16x16x32_bf16 v[76:79], v[150:153], v[216:219], v[76:79]
	v_mfma_f32_16x16x32_bf16 v[72:75], v[168:171], v[216:219], v[72:75]
	s_setprio 0
	s_setprio 1
	v_mfma_f32_16x16x32_bf16 v[116:119], v[172:175], v[188:191], v[116:119]
	v_mfma_f32_16x16x32_bf16 v[112:115], v[180:183], v[188:191], v[112:115]
	v_mfma_f32_16x16x32_bf16 v[100:103], v[172:175], v[196:199], v[100:103]
	v_mfma_f32_16x16x32_bf16 v[96:99], v[180:183], v[196:199], v[96:99]
	v_mfma_f32_16x16x32_bf16 v[84:87], v[172:175], v[204:207], v[84:87]
	v_mfma_f32_16x16x32_bf16 v[80:83], v[180:183], v[204:207], v[80:83]
	v_mfma_f32_16x16x32_bf16 v[68:71], v[172:175], v[212:215], v[68:71]
	v_mfma_f32_16x16x32_bf16 v[64:67], v[180:183], v[212:215], v[64:67]
	v_mfma_f32_16x16x32_bf16 v[116:119], v[176:179], v[192:195], v[116:119]
	v_mfma_f32_16x16x32_bf16 v[112:115], v[184:187], v[192:195], v[112:115]
	v_mfma_f32_16x16x32_bf16 v[100:103], v[176:179], v[200:203], v[100:103]
	v_mfma_f32_16x16x32_bf16 v[96:99], v[184:187], v[200:203], v[96:99]
	v_mfma_f32_16x16x32_bf16 v[84:87], v[176:179], v[208:211], v[84:87]
	v_mfma_f32_16x16x32_bf16 v[80:83], v[184:187], v[208:211], v[80:83]
	v_mfma_f32_16x16x32_bf16 v[68:71], v[176:179], v[216:219], v[68:71]
	v_mfma_f32_16x16x32_bf16 v[64:67], v[184:187], v[216:219], v[64:67]
	s_setprio 0
	s_barrier
	s_add_i32 s49, s42, s85
	v_lshl_add_u64 v[154:155], s[14:15], 0, v[130:131]
	s_mov_b32 m0, s49
	ds_read_b128 v[188:191], v161 offset:16384
	ds_read_b128 v[192:195], v161 offset:17408
	ds_read_b128 v[196:199], v161 offset:18432
	ds_read_b128 v[200:203], v161 offset:19456
	ds_read_b128 v[204:207], v161 offset:20480
	ds_read_b128 v[208:211], v161 offset:21504
	ds_read_b128 v[212:215], v161 offset:22528
	ds_read_b128 v[216:219], v161 offset:23552
	global_load_lds_dwordx4 v[154:155], off
	s_add_i32 m0, s49, 0x2000
	s_add_u32 s50, s14, 0x80000
	v_lshl_add_u64 v[220:221], s[14:15], 0, v[134:135]
	s_addc_u32 s51, s15, 0
	s_add_i32 s49, s43, s85
	global_load_lds_dwordx4 v[220:221], off
	v_lshl_add_u64 v[222:223], s[50:51], 0, v[130:131]
	s_mov_b32 m0, s49
	v_lshl_add_u64 v[224:225], s[86:87], 0, v[132:133]
	global_load_lds_dwordx4 v[222:223], off
	v_lshl_add_u64 v[222:223], s[50:51], 0, v[134:135]
	s_add_i32 m0, s49, 0x2000
	s_nop 0
	global_load_lds_dwordx4 v[222:223], off
	v_lshl_add_u64 v[222:223], s[86:87], 0, v[128:129]
	s_mov_b32 m0, s91
	s_nop 0
	global_load_lds_dwordx4 v[222:223], off
	s_mov_b32 m0, s93
	s_nop 0
	global_load_lds_dwordx4 v[224:225], off
	s_waitcnt vmcnt(8)
	s_waitcnt lgkmcnt(0)
	s_barrier
; #define PG8_STAGE(bufoff, gbase, voff) do { _Pragma("unroll") for (int _i = 0; _i < 2; ++_i) \
;         __builtin_amdgcn_global_load_lds((const unsigned*)((const char*)(gbase) + (voff)[_i]), (PG8_LAS unsigned*)(lds + (bufoff) + ldsw + _i * 8192), 16, 0, 0); } while (0)
; #define PG8_LDA(dst, b, h) do { _Pragma("unroll") for (int m = 0; m < 4; ++m) _Pragma("unroll") for (int k = 0; k < 2; ++k) dst[m][k] = *(const PG8_LAS bf16x8*)(lds + PG8_SA(b, h) + aoff + m * 2048 + k * 1024); } while (0)
; #define PG8_LDB(dst, b, h) do { _Pragma("unroll") for (int n = 0; n < 2; ++n) _Pragma("unroll") for (int k = 0; k < 2; ++k) dst[n][k] = *(const PG8_LAS bf16x8*)(lds + PG8_SB(b, h) + boff + n * 2048 + k * 1024); } while (0)
; #define PG8_MMA(ai, bj, At, Bt) do { __builtin_amdgcn_s_setprio(1); _Pragma("unroll") for (int m = 0; m < 4; ++m) _Pragma("unroll") for (int n = 0; n < 2; ++n) _Pragma("unroll") for (int k = 0; k < 2; ++k) \
;         acc[ai][bj][m][n] = __builtin_amdgcn_mfma_f32_16x16x32_bf16(Bt[n][k], At[m][k], acc[ai][bj][m][n], 0, 0, 0); __builtin_amdgcn_s_setprio(0); } while (0)
; #define PG8_WAIT_V(n) asm volatile("s_waitcnt vmcnt(" #n ")" ::: "memory")
; #define PG8_WAIT_L(n) asm volatile("s_waitcnt lgkmcnt(" #n ")" ::: "memory")
; #define PG8_BAR __builtin_amdgcn_s_barrier()
; #define PG8_SCHED __builtin_amdgcn_sched_barrier(0)
; template <class Epi, class Sched, bool ALIGN_EPI = false, bool SP2 = false>
; __device__ __forceinline__ void gemm_phase(PG8_LAS unsigned char* lds, const Gemm g, const Sched& S, const Epi& E) {
;     ...
;             PG8_WAIT_V(8); PG8_WAIT_L(0); PG8_BAR; PG8_MMA(1, 0, At, B0); PG8_MMA(1, 1, At, B1); PG8_BAR; PG8_SCHED;
;             PG8_LDB(B0, 1, 0); PG8_LDB(B1, 1, 1); PG8_SCHED; PG8_LDA(At, 1, 0); PG8_STAGE(PG8_SA(0, 1), a2 + hstep, voffA);
;             PG8_WAIT_V(8); PG8_WAIT_L(0); PG8_BAR; PG8_MMA(0, 0, At, B0); PG8_MMA(0, 1, At, B1); PG8_BAR; PG8_SCHED;
	s_setprio 1
	v_mfma_f32_16x16x32_bf16 v[60:63], v[146:149], v[188:191], v[60:63]
	v_mfma_f32_16x16x32_bf16 v[56:59], v[164:167], v[188:191], v[56:59]
	v_mfma_f32_16x16x32_bf16 v[44:47], v[146:149], v[196:199], v[44:47]
	v_mfma_f32_16x16x32_bf16 v[40:43], v[164:167], v[196:199], v[40:43]
	v_mfma_f32_16x16x32_bf16 v[28:31], v[146:149], v[204:207], v[28:31]
	v_mfma_f32_16x16x32_bf16 v[24:27], v[164:167], v[204:207], v[24:27]
	v_mfma_f32_16x16x32_bf16 v[12:15], v[146:149], v[212:215], v[12:15]
	v_mfma_f32_16x16x32_bf16 v[8:11], v[164:167], v[212:215], v[8:11]
	v_mfma_f32_16x16x32_bf16 v[60:63], v[150:153], v[192:195], v[60:63]
	v_mfma_f32_16x16x32_bf16 v[56:59], v[168:171], v[192:195], v[56:59]
	v_mfma_f32_16x16x32_bf16 v[44:47], v[150:153], v[200:203], v[44:47]
	v_mfma_f32_16x16x32_bf16 v[40:43], v[168:171], v[200:203], v[40:43]
	v_mfma_f32_16x16x32_bf16 v[28:31], v[150:153], v[208:211], v[28:31]
	v_mfma_f32_16x16x32_bf16 v[24:27], v[168:171], v[208:211], v[24:27]
	v_mfma_f32_16x16x32_bf16 v[12:15], v[150:153], v[216:219], v[12:15]
	v_mfma_f32_16x16x32_bf16 v[8:11], v[168:171], v[216:219], v[8:11]
	s_setprio 0
	s_setprio 1
	v_mfma_f32_16x16x32_bf16 v[52:55], v[172:175], v[188:191], v[52:55]
	v_mfma_f32_16x16x32_bf16 v[48:51], v[180:183], v[188:191], v[48:51]
	v_mfma_f32_16x16x32_bf16 v[36:39], v[172:175], v[196:199], v[36:39]
	v_mfma_f32_16x16x32_bf16 v[32:35], v[180:183], v[196:199], v[32:35]
	v_mfma_f32_16x16x32_bf16 v[20:23], v[172:175], v[204:207], v[20:23]
	v_mfma_f32_16x16x32_bf16 v[16:19], v[180:183], v[204:207], v[16:19]
	v_mfma_f32_16x16x32_bf16 v[4:7], v[172:175], v[212:215], v[4:7]
	v_mfma_f32_16x16x32_bf16 v[0:3], v[180:183], v[212:215], v[0:3]
	v_mfma_f32_16x16x32_bf16 v[52:55], v[176:179], v[192:195], v[52:55]
	v_mfma_f32_16x16x32_bf16 v[48:51], v[184:187], v[192:195], v[48:51]
	v_mfma_f32_16x16x32_bf16 v[36:39], v[176:179], v[200:203], v[36:39]
	v_mfma_f32_16x16x32_bf16 v[32:35], v[184:187], v[200:203], v[32:35]
	v_mfma_f32_16x16x32_bf16 v[20:23], v[176:179], v[208:211], v[20:23]
	v_mfma_f32_16x16x32_bf16 v[16:19], v[184:187], v[208:211], v[16:19]
	v_mfma_f32_16x16x32_bf16 v[4:7], v[176:179], v[216:219], v[4:7]
	v_mfma_f32_16x16x32_bf16 v[0:3], v[184:187], v[216:219], v[0:3]
	s_setprio 0
	s_barrier
	s_add_i32 s49, 0, 0x18000
	v_add_u32_e32 v163, s49, v158
	s_add_i32 s69, 0, 0x1c000
	ds_read_b128 v[146:149], v163
	ds_read_b128 v[150:153], v163 offset:1024
	ds_read_b128 v[164:167], v163 offset:2048
	ds_read_b128 v[168:171], v163 offset:3072
	v_add_u32_e32 v163, s69, v158
	ds_read_b128 v[172:175], v163
	ds_read_b128 v[176:179], v163 offset:1024
	ds_read_b128 v[180:183], v163 offset:2048
	ds_read_b128 v[184:187], v163 offset:3072
	s_add_u32 s50, s86, 0x80000
	s_addc_u32 s51, s87, 0
	s_mov_b32 m0, s95
	v_lshl_add_u64 v[226:227], s[50:51], 0, v[128:129]
	ds_read_b128 v[188:191], v161 offset:32768
	ds_read_b128 v[192:195], v161 offset:33792
	ds_read_b128 v[196:199], v161 offset:34816
	ds_read_b128 v[200:203], v161 offset:35840
	ds_read_b128 v[204:207], v161 offset:36864
	ds_read_b128 v[208:211], v161 offset:37888
	ds_read_b128 v[212:215], v161 offset:38912
	ds_read_b128 v[216:219], v161 offset:39936
	global_load_lds_dwordx4 v[226:227], off
	v_lshl_add_u64 v[226:227], s[50:51], 0, v[132:133]
	s_mov_b32 m0, s97
	s_nop 0
	global_load_lds_dwordx4 v[226:227], off
	s_waitcnt vmcnt(8)
	s_waitcnt lgkmcnt(0)
	s_barrier
	s_setprio 1
	v_mfma_f32_16x16x32_bf16 v[124:127], v[146:149], v[188:191], v[124:127]
	v_mfma_f32_16x16x32_bf16 v[120:123], v[164:167], v[188:191], v[120:123]
	v_mfma_f32_16x16x32_bf16 v[108:111], v[146:149], v[196:199], v[108:111]
	v_mfma_f32_16x16x32_bf16 v[104:107], v[164:167], v[196:199], v[104:107]
	v_mfma_f32_16x16x32_bf16 v[92:95], v[146:149], v[204:207], v[92:95]
	v_mfma_f32_16x16x32_bf16 v[88:91], v[164:167], v[204:207], v[88:91]
	v_mfma_f32_16x16x32_bf16 v[76:79], v[146:149], v[212:215], v[76:79]
	v_mfma_f32_16x16x32_bf16 v[72:75], v[164:167], v[212:215], v[72:75]
	v_mfma_f32_16x16x32_bf16 v[124:127], v[150:153], v[192:195], v[124:127]
	v_mfma_f32_16x16x32_bf16 v[120:123], v[168:171], v[192:195], v[120:123]
	v_mfma_f32_16x16x32_bf16 v[108:111], v[150:153], v[200:203], v[108:111]
	v_mfma_f32_16x16x32_bf16 v[104:107], v[168:171], v[200:203], v[104:107]
	v_mfma_f32_16x16x32_bf16 v[92:95], v[150:153], v[208:211], v[92:95]
	v_mfma_f32_16x16x32_bf16 v[88:91], v[168:171], v[208:211], v[88:91]
	v_mfma_f32_16x16x32_bf16 v[76:79], v[150:153], v[216:219], v[76:79]
	v_mfma_f32_16x16x32_bf16 v[72:75], v[168:171], v[216:219], v[72:75]
	s_setprio 0
	s_setprio 1
	v_mfma_f32_16x16x32_bf16 v[116:119], v[172:175], v[188:191], v[116:119]
	v_mfma_f32_16x16x32_bf16 v[112:115], v[180:183], v[188:191], v[112:115]
	v_mfma_f32_16x16x32_bf16 v[100:103], v[172:175], v[196:199], v[100:103]
	v_mfma_f32_16x16x32_bf16 v[96:99], v[180:183], v[196:199], v[96:99]
	v_mfma_f32_16x16x32_bf16 v[84:87], v[172:175], v[204:207], v[84:87]
	v_mfma_f32_16x16x32_bf16 v[80:83], v[180:183], v[204:207], v[80:83]
	v_mfma_f32_16x16x32_bf16 v[68:71], v[172:175], v[212:215], v[68:71]
	v_mfma_f32_16x16x32_bf16 v[64:67], v[180:183], v[212:215], v[64:67]
	v_mfma_f32_16x16x32_bf16 v[116:119], v[176:179], v[192:195], v[116:119]
	v_mfma_f32_16x16x32_bf16 v[112:115], v[184:187], v[192:195], v[112:115]
	v_mfma_f32_16x16x32_bf16 v[100:103], v[176:179], v[200:203], v[100:103]
	v_mfma_f32_16x16x32_bf16 v[96:99], v[184:187], v[200:203], v[96:99]
	v_mfma_f32_16x16x32_bf16 v[84:87], v[176:179], v[208:211], v[84:87]
	v_mfma_f32_16x16x32_bf16 v[80:83], v[184:187], v[208:211], v[80:83]
	v_mfma_f32_16x16x32_bf16 v[68:71], v[176:179], v[216:219], v[68:71]
	v_mfma_f32_16x16x32_bf16 v[64:67], v[184:187], v[216:219], v[64:67]
	s_setprio 0
	s_barrier
; #define PG8_STAGE(bufoff, gbase, voff) do { _Pragma("unroll") for (int _i = 0; _i < 2; ++_i) \
;         __builtin_amdgcn_global_load_lds((const unsigned*)((const char*)(gbase) + (voff)[_i]), (PG8_LAS unsigned*)(lds + (bufoff) + ldsw + _i * 8192), 16, 0, 0); } while (0)
; #define PG8_LDA(dst, b, h) do { _Pragma("unroll") for (int m = 0; m < 4; ++m) _Pragma("unroll") for (int k = 0; k < 2; ++k) dst[m][k] = *(const PG8_LAS bf16x8*)(lds + PG8_SA(b, h) + aoff + m * 2048 + k * 1024); } while (0)
; #define PG8_MMA(ai, bj, At, Bt) do { __builtin_amdgcn_s_setprio(1); _Pragma("unroll") for (int m = 0; m < 4; ++m) _Pragma("unroll") for (int n = 0; n < 2; ++n) _Pragma("unroll") for (int k = 0; k < 2; ++k) \
;         acc[ai][bj][m][n] = __builtin_amdgcn_mfma_f32_16x16x32_bf16(Bt[n][k], At[m][k], acc[ai][bj][m][n], 0, 0, 0); __builtin_amdgcn_s_setprio(0); } while (0)
; #define PG8_WAIT_V(n) asm volatile("s_waitcnt vmcnt(" #n ")" ::: "memory")
; #define PG8_WAIT_L(n) asm volatile("s_waitcnt lgkmcnt(" #n ")" ::: "memory")
; #define PG8_BAR __builtin_amdgcn_s_barrier()
; #define PG8_SCHED __builtin_amdgcn_sched_barrier(0)
; template <class Epi, class Sched, bool ALIGN_EPI = false, bool SP2 = false>
; __device__ __forceinline__ void gemm_phase(PG8_LAS unsigned char* lds, const Gemm g, const Sched& S, const Epi& E) {
;     ...
;             PG8_LDA(At, 1, 1); PG8_STAGE(PG8_SB(1, 0), b3, voffB); PG8_STAGE(PG8_SB(1, 1), b3 + hstep, voffB); PG8_STAGE(PG8_SA(1, 0), a3, voffA);
;             PG8_WAIT_V(8); PG8_WAIT_L(0); PG8_BAR; PG8_MMA(1, 0, At, B0); PG8_MMA(1, 1, At, B1); PG8_BAR; PG8_SCHED;
;     ...
;         if constexpr (ALIGN_EPI) { if (wr == 0) PG8_BAR; }
	s_add_i32 s49, s49, s85
	v_lshl_add_u64 v[154:155], v[154:155], 0, s[82:83]
	s_mov_b32 m0, s49
	ds_read_b128 v[188:191], v161 offset:49152
	ds_read_b128 v[192:195], v161 offset:50176
	ds_read_b128 v[196:199], v161 offset:51200
	ds_read_b128 v[200:203], v161 offset:52224
	ds_read_b128 v[204:207], v161 offset:53248
	ds_read_b128 v[208:211], v161 offset:54272
	ds_read_b128 v[212:215], v161 offset:55296
	ds_read_b128 v[216:219], v161 offset:56320
	global_load_lds_dwordx4 v[154:155], off
	s_add_i32 m0, s49, 0x2000
	s_add_u32 s14, s14, 0x80080
	v_lshl_add_u64 v[154:155], v[220:221], 0, s[82:83]
	s_addc_u32 s15, s15, 0
	s_add_i32 s49, s69, s85
	global_load_lds_dwordx4 v[154:155], off
	v_lshl_add_u64 v[154:155], s[14:15], 0, v[130:131]
	s_mov_b32 m0, s49
	s_nop 0
	global_load_lds_dwordx4 v[154:155], off
	v_lshl_add_u64 v[154:155], s[14:15], 0, v[134:135]
	s_add_i32 m0, s49, 0x2000
	s_nop 0
	global_load_lds_dwordx4 v[154:155], off
	v_lshl_add_u64 v[154:155], v[222:223], 0, s[82:83]
	s_mov_b32 m0, s39
	s_nop 0
	global_load_lds_dwordx4 v[154:155], off
	v_lshl_add_u64 v[154:155], v[224:225], 0, s[82:83]
	s_mov_b32 m0, s40
	s_nop 0
	global_load_lds_dwordx4 v[154:155], off
	s_waitcnt vmcnt(8)
	s_waitcnt lgkmcnt(0)
	s_barrier
	s_setprio 1
	v_mfma_f32_16x16x32_bf16 v[60:63], v[146:149], v[188:191], v[60:63]
	v_mfma_f32_16x16x32_bf16 v[56:59], v[164:167], v[188:191], v[56:59]
	v_mfma_f32_16x16x32_bf16 v[44:47], v[146:149], v[196:199], v[44:47]
	v_mfma_f32_16x16x32_bf16 v[40:43], v[164:167], v[196:199], v[40:43]
	v_mfma_f32_16x16x32_bf16 v[28:31], v[146:149], v[204:207], v[28:31]
	v_mfma_f32_16x16x32_bf16 v[24:27], v[164:167], v[204:207], v[24:27]
	v_mfma_f32_16x16x32_bf16 v[12:15], v[146:149], v[212:215], v[12:15]
	v_mfma_f32_16x16x32_bf16 v[8:11], v[164:167], v[212:215], v[8:11]
	v_mfma_f32_16x16x32_bf16 v[60:63], v[150:153], v[192:195], v[60:63]
	v_mfma_f32_16x16x32_bf16 v[56:59], v[168:171], v[192:195], v[56:59]
	v_mfma_f32_16x16x32_bf16 v[44:47], v[150:153], v[200:203], v[44:47]
	v_mfma_f32_16x16x32_bf16 v[40:43], v[168:171], v[200:203], v[40:43]
	v_mfma_f32_16x16x32_bf16 v[28:31], v[150:153], v[208:211], v[28:31]
	v_mfma_f32_16x16x32_bf16 v[24:27], v[168:171], v[208:211], v[24:27]
	v_mfma_f32_16x16x32_bf16 v[12:15], v[150:153], v[216:219], v[12:15]
	v_mfma_f32_16x16x32_bf16 v[8:11], v[168:171], v[216:219], v[8:11]
	s_setprio 0
	s_setprio 1
	v_mfma_f32_16x16x32_bf16 v[52:55], v[172:175], v[188:191], v[52:55]
	v_mfma_f32_16x16x32_bf16 v[48:51], v[180:183], v[188:191], v[48:51]
	v_mfma_f32_16x16x32_bf16 v[36:39], v[172:175], v[196:199], v[36:39]
	v_mfma_f32_16x16x32_bf16 v[32:35], v[180:183], v[196:199], v[32:35]
	v_mfma_f32_16x16x32_bf16 v[20:23], v[172:175], v[204:207], v[20:23]
	v_mfma_f32_16x16x32_bf16 v[16:19], v[180:183], v[204:207], v[16:19]
	v_mfma_f32_16x16x32_bf16 v[4:7], v[172:175], v[212:215], v[4:7]
	v_mfma_f32_16x16x32_bf16 v[0:3], v[180:183], v[212:215], v[0:3]
	v_mfma_f32_16x16x32_bf16 v[52:55], v[176:179], v[192:195], v[52:55]
	v_mfma_f32_16x16x32_bf16 v[48:51], v[184:187], v[192:195], v[48:51]
	v_mfma_f32_16x16x32_bf16 v[36:39], v[176:179], v[200:203], v[36:39]
	v_mfma_f32_16x16x32_bf16 v[32:35], v[184:187], v[200:203], v[32:35]
	v_mfma_f32_16x16x32_bf16 v[20:23], v[176:179], v[208:211], v[20:23]
	v_mfma_f32_16x16x32_bf16 v[16:19], v[184:187], v[208:211], v[16:19]
	v_mfma_f32_16x16x32_bf16 v[4:7], v[176:179], v[216:219], v[4:7]
	v_mfma_f32_16x16x32_bf16 v[0:3], v[184:187], v[216:219], v[0:3]
	s_setprio 0
	s_barrier
	s_add_i32 s48, s48, 2
	s_add_u32 s10, s10, 0x100
	s_addc_u32 s11, s11, 0
	s_add_u32 s46, s46, 0x100
	s_addc_u32 s47, s47, 0
	s_cmp_gt_u32 s48, 29
	s_cbranch_scc0 .LBB0_341
	s_and_b64 vcc, exec, s[88:89]
	s_cbranch_vccz .LBB0_344
	s_barrier

; #define PG8_STAGE(bufoff, gbase, voff) do { _Pragma("unroll") for (int _i = 0; _i < 2; ++_i) \
;         __builtin_amdgcn_global_load_lds((const unsigned*)((const char*)(gbase) + (voff)[_i]), (PG8_LAS unsigned*)(lds + (bufoff) + ldsw + _i * 8192), 16, 0, 0); } while (0)
; #define PG8_LDA(dst, b, h) do { _Pragma("unroll") for (int m = 0; m < 4; ++m) _Pragma("unroll") for (int k = 0; k < 2; ++k) dst[m][k] = *(const PG8_LAS bf16x8*)(lds + PG8_SA(b, h) + aoff + m * 2048 + k * 1024); } while (0)
; #define PG8_LDB(dst, b, h) do { _Pragma("unroll") for (int n = 0; n < 2; ++n) _Pragma("unroll") for (int k = 0; k < 2; ++k) dst[n][k] = *(const PG8_LAS bf16x8*)(lds + PG8_SB(b, h) + boff + n * 2048 + k * 1024); } while (0)
; #define PG8_WAIT_V(n) asm volatile("s_waitcnt vmcnt(" #n ")" ::: "memory")
; #define PG8_WAIT_L(n) asm volatile("s_waitcnt lgkmcnt(" #n ")" ::: "memory")
; #define PG8_BAR __builtin_amdgcn_s_barrier()
; #define PG8_SCHED __builtin_amdgcn_sched_barrier(0)
; template <class Epi, class Sched, bool ALIGN_EPI = false, bool SP2 = false>
; __device__ __forceinline__ void gemm_phase(PG8_LAS unsigned char* lds, const Gemm g, const Sched& S, const Epi& E) {
;     ...
;         const char* nA = has_next ? (const char*)g.A + (size_t)nxt.pm * tstep : cA; const char* nB = has_next ? (const char*)g.Bt + (size_t)nxt.pn * tstep : cB;
;         for (int t = 0; t < nt; t += 2) {
;             const bool last = (t == nt - 2);
;             const char* a1 = cA + (size_t)(t + 1) * kstep;
;             const char* a2 = last ? nA : cA + (size_t)(t + 2) * kstep; const char* b2 = last ? nB : cB + (size_t)(t + 2) * kstep;
;             const char* a3 = a2 + kstep; const char* b3 = b2 + kstep;
;             if (last && has_next) S.a_ready(nxt);
;             if constexpr (SP2) {
;             PG8_LDB(B0, 0, 0); PG8_LDB(B1, 0, 1); PG8_SCHED; PG8_LDA(At, 0, 0); PG8_STAGE(PG8_SA(1, 1), a1 + hstep, voffA);
;             PG8_WAIT_V(8); PG8_WAIT_L(0); PG8_BAR; PG8_MMA(0, 0, At, B0); PG8_MMA(0, 1, At, B1); PG8_BAR; PG8_SCHED;
;             PG8_LDA(At, 0, 1); PG8_STAGE(PG8_SB(0, 0), b2, voffB); PG8_STAGE(PG8_SB(0, 1), b2 + hstep, voffB); PG8_STAGE(PG8_SA(0, 0), a2, voffA);
;             PG8_WAIT_V(8); PG8_WAIT_L(0); PG8_BAR; PG8_MMA(1, 0, At, B0); PG8_MMA(1, 1, At, B1); PG8_BAR; PG8_SCHED;
.LBB0_919:
	ds_read_b128 v[128:131], v187
	ds_read_b128 v[132:135], v187 offset:1024
	ds_read_b128 v[154:157], v187 offset:2048
	ds_read_b128 v[158:161], v187 offset:3072
	ds_read_b128 v[162:165], v188
	ds_read_b128 v[166:169], v188 offset:1024
	ds_read_b128 v[170:173], v188 offset:2048
	ds_read_b128 v[174:177], v188 offset:3072
	s_add_i32 s46, s6, 2
	s_add_u32 s47, s0, 0x80
	s_addc_u32 s7, s1, 0
	s_cmp_eq_u32 s93, s6
	s_cselect_b32 s6, s16, s47
	s_cselect_b32 s7, s17, s7
	s_cselect_b32 s49, s19, s45
	s_cselect_b32 s48, s18, s44
	v_lshl_add_u64 v[182:183], s[0:1], 0, v[146:147]
	s_add_i32 m0, s85, 0xc000
	ds_read_b128 v[178:181], v189
	ds_read_b128 v[192:195], v189 offset:1024
	ds_read_b128 v[196:199], v189 offset:2048
	ds_read_b128 v[200:203], v189 offset:3072
	ds_read_b128 v[204:207], v189 offset:4096
	ds_read_b128 v[208:211], v189 offset:5120
	ds_read_b128 v[212:215], v189 offset:6144
	ds_read_b128 v[216:219], v189 offset:7168
	global_load_lds_dwordx4 v[182:183], off
	v_lshl_add_u64 v[182:183], s[0:1], 0, v[148:149]
	s_add_i32 m0, s85, 0xe000
	s_nop 0
	global_load_lds_dwordx4 v[182:183], off
	s_waitcnt vmcnt(8)
	s_waitcnt lgkmcnt(0)
	s_barrier
	s_setprio 1
	v_mfma_f32_16x16x32_bf16 v[120:123], v[128:131], v[178:181], v[120:123]
	v_mfma_f32_16x16x32_bf16 v[124:127], v[154:157], v[178:181], v[124:127]
	v_mfma_f32_16x16x32_bf16 v[108:111], v[128:131], v[196:199], v[108:111]
	v_mfma_f32_16x16x32_bf16 v[104:107], v[154:157], v[196:199], v[104:107]
	v_mfma_f32_16x16x32_bf16 v[92:95], v[128:131], v[204:207], v[92:95]
	v_mfma_f32_16x16x32_bf16 v[88:91], v[154:157], v[204:207], v[88:91]
	v_mfma_f32_16x16x32_bf16 v[76:79], v[128:131], v[212:215], v[76:79]
	v_mfma_f32_16x16x32_bf16 v[72:75], v[154:157], v[212:215], v[72:75]
	v_mfma_f32_16x16x32_bf16 v[120:123], v[132:135], v[192:195], v[120:123]
	v_mfma_f32_16x16x32_bf16 v[124:127], v[158:161], v[192:195], v[124:127]
	v_mfma_f32_16x16x32_bf16 v[108:111], v[132:135], v[200:203], v[108:111]
	v_mfma_f32_16x16x32_bf16 v[104:107], v[158:161], v[200:203], v[104:107]
	v_mfma_f32_16x16x32_bf16 v[92:95], v[132:135], v[208:211], v[92:95]
	v_mfma_f32_16x16x32_bf16 v[88:91], v[158:161], v[208:211], v[88:91]
	v_mfma_f32_16x16x32_bf16 v[76:79], v[132:135], v[216:219], v[76:79]
	v_mfma_f32_16x16x32_bf16 v[72:75], v[158:161], v[216:219], v[72:75]
	s_setprio 0
	s_setprio 1
	v_mfma_f32_16x16x32_bf16 v[116:119], v[162:165], v[178:181], v[116:119]
	v_mfma_f32_16x16x32_bf16 v[112:115], v[170:173], v[178:181], v[112:115]
	v_mfma_f32_16x16x32_bf16 v[100:103], v[162:165], v[196:199], v[100:103]
	v_mfma_f32_16x16x32_bf16 v[96:99], v[170:173], v[196:199], v[96:99]
	v_mfma_f32_16x16x32_bf16 v[84:87], v[162:165], v[204:207], v[84:87]
	v_mfma_f32_16x16x32_bf16 v[80:83], v[170:173], v[204:207], v[80:83]
	v_mfma_f32_16x16x32_bf16 v[68:71], v[162:165], v[212:215], v[68:71]
	v_mfma_f32_16x16x32_bf16 v[64:67], v[170:173], v[212:215], v[64:67]
	v_mfma_f32_16x16x32_bf16 v[116:119], v[166:169], v[192:195], v[116:119]
	v_mfma_f32_16x16x32_bf16 v[112:115], v[174:177], v[192:195], v[112:115]
	v_mfma_f32_16x16x32_bf16 v[100:103], v[166:169], v[200:203], v[100:103]
	v_mfma_f32_16x16x32_bf16 v[96:99], v[174:177], v[200:203], v[96:99]
	v_mfma_f32_16x16x32_bf16 v[84:87], v[166:169], v[208:211], v[84:87]
	v_mfma_f32_16x16x32_bf16 v[80:83], v[174:177], v[208:211], v[80:83]
	v_mfma_f32_16x16x32_bf16 v[68:71], v[166:169], v[216:219], v[68:71]
	v_mfma_f32_16x16x32_bf16 v[64:67], v[174:177], v[216:219], v[64:67]
	s_setprio 0
	s_barrier
	s_add_i32 s47, s3, s84
	v_lshl_add_u64 v[182:183], s[48:49], 0, v[138:139]
	s_mov_b32 m0, s47
	ds_read_b128 v[178:181], v189 offset:16384
	ds_read_b128 v[192:195], v189 offset:17408
	ds_read_b128 v[196:199], v189 offset:18432
	ds_read_b128 v[200:203], v189 offset:19456
	ds_read_b128 v[204:207], v189 offset:20480
	ds_read_b128 v[208:211], v189 offset:21504
	ds_read_b128 v[212:215], v189 offset:22528
	ds_read_b128 v[216:219], v189 offset:23552
	global_load_lds_dwordx4 v[182:183], off
	s_add_i32 m0, s47, 0x2000
	v_lshl_add_u64 v[220:221], s[48:49], 0, v[142:143]
	s_add_u32 s48, s48, s10
	s_addc_u32 s49, s49, s11
	s_add_i32 s47, s8, s84
	global_load_lds_dwordx4 v[220:221], off
	v_lshl_add_u64 v[222:223], s[48:49], 0, v[138:139]
	s_mov_b32 m0, s47
	v_lshl_add_u64 v[224:225], s[48:49], 0, v[142:143]
	global_load_lds_dwordx4 v[222:223], off
	s_add_i32 m0, s47, 0x2000
	v_lshl_add_u64 v[226:227], s[6:7], 0, v[136:137]
	global_load_lds_dwordx4 v[224:225], off
	s_mov_b32 m0, s85
	v_lshl_add_u64 v[228:229], s[6:7], 0, v[140:141]
	global_load_lds_dwordx4 v[226:227], off
	s_mov_b32 m0, s86
	s_nop 0
	global_load_lds_dwordx4 v[228:229], off
	s_waitcnt vmcnt(8)
	s_waitcnt lgkmcnt(0)
	s_barrier
; #define PG8_STAGE(bufoff, gbase, voff) do { _Pragma("unroll") for (int _i = 0; _i < 2; ++_i) \
;         __builtin_amdgcn_global_load_lds((const unsigned*)((const char*)(gbase) + (voff)[_i]), (PG8_LAS unsigned*)(lds + (bufoff) + ldsw + _i * 8192), 16, 0, 0); } while (0)
; #define PG8_LDA(dst, b, h) do { _Pragma("unroll") for (int m = 0; m < 4; ++m) _Pragma("unroll") for (int k = 0; k < 2; ++k) dst[m][k] = *(const PG8_LAS bf16x8*)(lds + PG8_SA(b, h) + aoff + m * 2048 + k * 1024); } while (0)
; #define PG8_LDB(dst, b, h) do { _Pragma("unroll") for (int n = 0; n < 2; ++n) _Pragma("unroll") for (int k = 0; k < 2; ++k) dst[n][k] = *(const PG8_LAS bf16x8*)(lds + PG8_SB(b, h) + boff + n * 2048 + k * 1024); } while (0)
; #define PG8_MMA(ai, bj, At, Bt) do { __builtin_amdgcn_s_setprio(1); _Pragma("unroll") for (int m = 0; m < 4; ++m) _Pragma("unroll") for (int n = 0; n < 2; ++n) _Pragma("unroll") for (int k = 0; k < 2; ++k) \
;         acc[ai][bj][m][n] = __builtin_amdgcn_mfma_f32_16x16x32_bf16(Bt[n][k], At[m][k], acc[ai][bj][m][n], 0, 0, 0); __builtin_amdgcn_s_setprio(0); } while (0)
; #define PG8_WAIT_V(n) asm volatile("s_waitcnt vmcnt(" #n ")" ::: "memory")
; #define PG8_WAIT_L(n) asm volatile("s_waitcnt lgkmcnt(" #n ")" ::: "memory")
; #define PG8_BAR __builtin_amdgcn_s_barrier()
; #define PG8_SCHED __builtin_amdgcn_sched_barrier(0)
; template <class Epi, class Sched, bool ALIGN_EPI = false, bool SP2 = false>
; __device__ __forceinline__ void gemm_phase(PG8_LAS unsigned char* lds, const Gemm g, const Sched& S, const Epi& E) {
;     ...
;             PG8_WAIT_V(8); PG8_WAIT_L(0); PG8_BAR; PG8_MMA(1, 0, At, B0); PG8_MMA(1, 1, At, B1); PG8_BAR; PG8_SCHED;
;             PG8_LDB(B0, 1, 0); PG8_LDB(B1, 1, 1); PG8_SCHED; PG8_LDA(At, 1, 0); PG8_STAGE(PG8_SA(0, 1), a2 + hstep, voffA);
;             PG8_WAIT_V(8); PG8_WAIT_L(0); PG8_BAR; PG8_MMA(0, 0, At, B0); PG8_MMA(0, 1, At, B1); PG8_BAR; PG8_SCHED;
	s_setprio 1
	v_mfma_f32_16x16x32_bf16 v[60:63], v[128:131], v[178:181], v[60:63]
	v_mfma_f32_16x16x32_bf16 v[56:59], v[154:157], v[178:181], v[56:59]
	v_mfma_f32_16x16x32_bf16 v[44:47], v[128:131], v[196:199], v[44:47]
	v_mfma_f32_16x16x32_bf16 v[40:43], v[154:157], v[196:199], v[40:43]
	v_mfma_f32_16x16x32_bf16 v[28:31], v[128:131], v[204:207], v[28:31]
	v_mfma_f32_16x16x32_bf16 v[24:27], v[154:157], v[204:207], v[24:27]
	v_mfma_f32_16x16x32_bf16 v[12:15], v[128:131], v[212:215], v[12:15]
	v_mfma_f32_16x16x32_bf16 v[8:11], v[154:157], v[212:215], v[8:11]
	v_mfma_f32_16x16x32_bf16 v[60:63], v[132:135], v[192:195], v[60:63]
	v_mfma_f32_16x16x32_bf16 v[56:59], v[158:161], v[192:195], v[56:59]
	v_mfma_f32_16x16x32_bf16 v[44:47], v[132:135], v[200:203], v[44:47]
	v_mfma_f32_16x16x32_bf16 v[40:43], v[158:161], v[200:203], v[40:43]
	v_mfma_f32_16x16x32_bf16 v[28:31], v[132:135], v[208:211], v[28:31]
	v_mfma_f32_16x16x32_bf16 v[24:27], v[158:161], v[208:211], v[24:27]
	v_mfma_f32_16x16x32_bf16 v[12:15], v[132:135], v[216:219], v[12:15]
	v_mfma_f32_16x16x32_bf16 v[8:11], v[158:161], v[216:219], v[8:11]
	s_setprio 0
	s_setprio 1
	v_mfma_f32_16x16x32_bf16 v[52:55], v[162:165], v[178:181], v[52:55]
	v_mfma_f32_16x16x32_bf16 v[48:51], v[170:173], v[178:181], v[48:51]
	v_mfma_f32_16x16x32_bf16 v[36:39], v[162:165], v[196:199], v[36:39]
	v_mfma_f32_16x16x32_bf16 v[32:35], v[170:173], v[196:199], v[32:35]
	v_mfma_f32_16x16x32_bf16 v[20:23], v[162:165], v[204:207], v[20:23]
	v_mfma_f32_16x16x32_bf16 v[16:19], v[170:173], v[204:207], v[16:19]
	v_mfma_f32_16x16x32_bf16 v[4:7], v[162:165], v[212:215], v[4:7]
	v_mfma_f32_16x16x32_bf16 v[0:3], v[170:173], v[212:215], v[0:3]
	v_mfma_f32_16x16x32_bf16 v[52:55], v[166:169], v[192:195], v[52:55]
	v_mfma_f32_16x16x32_bf16 v[48:51], v[174:177], v[192:195], v[48:51]
	v_mfma_f32_16x16x32_bf16 v[36:39], v[166:169], v[200:203], v[36:39]
	v_mfma_f32_16x16x32_bf16 v[32:35], v[174:177], v[200:203], v[32:35]
	v_mfma_f32_16x16x32_bf16 v[20:23], v[166:169], v[208:211], v[20:23]
	v_mfma_f32_16x16x32_bf16 v[16:19], v[174:177], v[208:211], v[16:19]
	v_mfma_f32_16x16x32_bf16 v[4:7], v[166:169], v[216:219], v[4:7]
	v_mfma_f32_16x16x32_bf16 v[0:3], v[174:177], v[216:219], v[0:3]
	s_setprio 0
	s_barrier
	s_add_i32 s47, 0, 0x18000
	s_add_i32 s48, 0, 0x1c000
	v_add_u32_e32 v158, s47, v186
	v_add_u32_e32 v174, s48, v186
	ds_read_b128 v[128:131], v158
	ds_read_b128 v[132:135], v158 offset:1024
	ds_read_b128 v[154:157], v158 offset:2048
	ds_read_b128 v[158:161], v158 offset:3072
	ds_read_b128 v[162:165], v174
	ds_read_b128 v[166:169], v174 offset:1024
	ds_read_b128 v[170:173], v174 offset:2048
	ds_read_b128 v[174:177], v174 offset:3072
	s_add_u32 s6, s6, s10
	s_addc_u32 s7, s7, s11
	s_mov_b32 m0, s87
	v_lshl_add_u64 v[230:231], s[6:7], 0, v[136:137]
	ds_read_b128 v[178:181], v189 offset:32768
	ds_read_b128 v[192:195], v189 offset:33792
	ds_read_b128 v[196:199], v189 offset:34816
	ds_read_b128 v[200:203], v189 offset:35840
	ds_read_b128 v[204:207], v189 offset:36864
	ds_read_b128 v[208:211], v189 offset:37888
	ds_read_b128 v[212:215], v189 offset:38912
	ds_read_b128 v[216:219], v189 offset:39936
	global_load_lds_dwordx4 v[230:231], off
	v_lshl_add_u64 v[230:231], s[6:7], 0, v[140:141]
	s_mov_b32 m0, s88
	s_nop 0
	global_load_lds_dwordx4 v[230:231], off
	s_waitcnt vmcnt(8)
	s_waitcnt lgkmcnt(0)
	s_barrier
	s_setprio 1
	v_mfma_f32_16x16x32_bf16 v[120:123], v[128:131], v[178:181], v[120:123]
	v_mfma_f32_16x16x32_bf16 v[124:127], v[154:157], v[178:181], v[124:127]
	v_mfma_f32_16x16x32_bf16 v[108:111], v[128:131], v[196:199], v[108:111]
	v_mfma_f32_16x16x32_bf16 v[104:107], v[154:157], v[196:199], v[104:107]
	v_mfma_f32_16x16x32_bf16 v[92:95], v[128:131], v[204:207], v[92:95]
	v_mfma_f32_16x16x32_bf16 v[88:91], v[154:157], v[204:207], v[88:91]
	v_mfma_f32_16x16x32_bf16 v[76:79], v[128:131], v[212:215], v[76:79]
	v_mfma_f32_16x16x32_bf16 v[72:75], v[154:157], v[212:215], v[72:75]
	v_mfma_f32_16x16x32_bf16 v[120:123], v[132:135], v[192:195], v[120:123]
	v_mfma_f32_16x16x32_bf16 v[124:127], v[158:161], v[192:195], v[124:127]
	v_mfma_f32_16x16x32_bf16 v[108:111], v[132:135], v[200:203], v[108:111]
	v_mfma_f32_16x16x32_bf16 v[104:107], v[158:161], v[200:203], v[104:107]
	v_mfma_f32_16x16x32_bf16 v[92:95], v[132:135], v[208:211], v[92:95]
	v_mfma_f32_16x16x32_bf16 v[88:91], v[158:161], v[208:211], v[88:91]
	v_mfma_f32_16x16x32_bf16 v[76:79], v[132:135], v[216:219], v[76:79]
	v_mfma_f32_16x16x32_bf16 v[72:75], v[158:161], v[216:219], v[72:75]
	s_setprio 0
	s_setprio 1
	v_mfma_f32_16x16x32_bf16 v[116:119], v[162:165], v[178:181], v[116:119]
	v_mfma_f32_16x16x32_bf16 v[112:115], v[170:173], v[178:181], v[112:115]
	v_mfma_f32_16x16x32_bf16 v[100:103], v[162:165], v[196:199], v[100:103]
	v_mfma_f32_16x16x32_bf16 v[96:99], v[170:173], v[196:199], v[96:99]
	v_mfma_f32_16x16x32_bf16 v[84:87], v[162:165], v[204:207], v[84:87]
	v_mfma_f32_16x16x32_bf16 v[80:83], v[170:173], v[204:207], v[80:83]
	v_mfma_f32_16x16x32_bf16 v[68:71], v[162:165], v[212:215], v[68:71]
	v_mfma_f32_16x16x32_bf16 v[64:67], v[170:173], v[212:215], v[64:67]
	v_mfma_f32_16x16x32_bf16 v[116:119], v[166:169], v[192:195], v[116:119]
	v_mfma_f32_16x16x32_bf16 v[112:115], v[174:177], v[192:195], v[112:115]
	v_mfma_f32_16x16x32_bf16 v[100:103], v[166:169], v[200:203], v[100:103]
	v_mfma_f32_16x16x32_bf16 v[96:99], v[174:177], v[200:203], v[96:99]
	v_mfma_f32_16x16x32_bf16 v[84:87], v[166:169], v[208:211], v[84:87]
	v_mfma_f32_16x16x32_bf16 v[80:83], v[174:177], v[208:211], v[80:83]
	v_mfma_f32_16x16x32_bf16 v[68:71], v[166:169], v[216:219], v[68:71]
	v_mfma_f32_16x16x32_bf16 v[64:67], v[174:177], v[216:219], v[64:67]
	s_setprio 0
	s_barrier
; #define PG8_STAGE(bufoff, gbase, voff) do { _Pragma("unroll") for (int _i = 0; _i < 2; ++_i) \
;         __builtin_amdgcn_global_load_lds((const unsigned*)((const char*)(gbase) + (voff)[_i]), (PG8_LAS unsigned*)(lds + (bufoff) + ldsw + _i * 8192), 16, 0, 0); } while (0)
; #define PG8_LDA(dst, b, h) do { _Pragma("unroll") for (int m = 0; m < 4; ++m) _Pragma("unroll") for (int k = 0; k < 2; ++k) dst[m][k] = *(const PG8_LAS bf16x8*)(lds + PG8_SA(b, h) + aoff + m * 2048 + k * 1024); } while (0)
; #define PG8_MMA(ai, bj, At, Bt) do { __builtin_amdgcn_s_setprio(1); _Pragma("unroll") for (int m = 0; m < 4; ++m) _Pragma("unroll") for (int n = 0; n < 2; ++n) _Pragma("unroll") for (int k = 0; k < 2; ++k) \
;         acc[ai][bj][m][n] = __builtin_amdgcn_mfma_f32_16x16x32_bf16(Bt[n][k], At[m][k], acc[ai][bj][m][n], 0, 0, 0); __builtin_amdgcn_s_setprio(0); } while (0)
; #define PG8_WAIT_V(n) asm volatile("s_waitcnt vmcnt(" #n ")" ::: "memory")
; #define PG8_WAIT_L(n) asm volatile("s_waitcnt lgkmcnt(" #n ")" ::: "memory")
; #define PG8_BAR __builtin_amdgcn_s_barrier()
; #define PG8_SCHED __builtin_amdgcn_sched_barrier(0)
; template <class Epi, class Sched, bool ALIGN_EPI = false, bool SP2 = false>
; __device__ __forceinline__ void gemm_phase(PG8_LAS unsigned char* lds, const Gemm g, const Sched& S, const Epi& E) {
;     ...
;             PG8_LDA(At, 1, 1); PG8_STAGE(PG8_SB(1, 0), b3, voffB); PG8_STAGE(PG8_SB(1, 1), b3 + hstep, voffB); PG8_STAGE(PG8_SA(1, 0), a3, voffA);
;             PG8_WAIT_V(8); PG8_WAIT_L(0); PG8_BAR; PG8_MMA(1, 0, At, B0); PG8_MMA(1, 1, At, B1); PG8_BAR; PG8_SCHED;
	s_add_i32 s6, s47, s84
	v_lshl_add_u64 v[182:183], v[182:183], 0, s[64:65]
	s_mov_b32 m0, s6
	ds_read_b128 v[178:181], v189 offset:49152
	ds_read_b128 v[192:195], v189 offset:50176
	ds_read_b128 v[196:199], v189 offset:51200
	ds_read_b128 v[200:203], v189 offset:52224
	ds_read_b128 v[204:207], v189 offset:53248
	ds_read_b128 v[208:211], v189 offset:54272
	ds_read_b128 v[212:215], v189 offset:55296
	ds_read_b128 v[216:219], v189 offset:56320
	global_load_lds_dwordx4 v[182:183], off
	v_lshl_add_u64 v[182:183], v[220:221], 0, s[64:65]
	s_add_i32 m0, s6, 0x2000
	s_add_i32 s6, s48, s84
	global_load_lds_dwordx4 v[182:183], off
	v_lshl_add_u64 v[182:183], v[222:223], 0, s[64:65]
	s_mov_b32 m0, s6
	s_nop 0
	global_load_lds_dwordx4 v[182:183], off
	v_lshl_add_u64 v[182:183], v[224:225], 0, s[64:65]
	s_add_i32 m0, s6, 0x2000
	s_nop 0
	global_load_lds_dwordx4 v[182:183], off
	v_lshl_add_u64 v[182:183], v[226:227], 0, s[64:65]
	s_mov_b32 m0, s96
	s_nop 0
	global_load_lds_dwordx4 v[182:183], off
	v_lshl_add_u64 v[182:183], v[228:229], 0, s[64:65]
	s_mov_b32 m0, s97
	s_nop 0
	global_load_lds_dwordx4 v[182:183], off
	s_waitcnt vmcnt(8)
	s_waitcnt lgkmcnt(0)
	s_barrier
	s_setprio 1
	v_mfma_f32_16x16x32_bf16 v[60:63], v[128:131], v[178:181], v[60:63]
	v_mfma_f32_16x16x32_bf16 v[56:59], v[154:157], v[178:181], v[56:59]
	v_mfma_f32_16x16x32_bf16 v[44:47], v[128:131], v[196:199], v[44:47]
	v_mfma_f32_16x16x32_bf16 v[40:43], v[154:157], v[196:199], v[40:43]
	v_mfma_f32_16x16x32_bf16 v[28:31], v[128:131], v[204:207], v[28:31]
	v_mfma_f32_16x16x32_bf16 v[24:27], v[154:157], v[204:207], v[24:27]
	v_mfma_f32_16x16x32_bf16 v[12:15], v[128:131], v[212:215], v[12:15]
	v_mfma_f32_16x16x32_bf16 v[8:11], v[154:157], v[212:215], v[8:11]
	v_mfma_f32_16x16x32_bf16 v[60:63], v[132:135], v[192:195], v[60:63]
	v_mfma_f32_16x16x32_bf16 v[56:59], v[158:161], v[192:195], v[56:59]
	v_mfma_f32_16x16x32_bf16 v[44:47], v[132:135], v[200:203], v[44:47]
	v_mfma_f32_16x16x32_bf16 v[40:43], v[158:161], v[200:203], v[40:43]
	v_mfma_f32_16x16x32_bf16 v[28:31], v[132:135], v[208:211], v[28:31]
	v_mfma_f32_16x16x32_bf16 v[24:27], v[158:161], v[208:211], v[24:27]
	v_mfma_f32_16x16x32_bf16 v[12:15], v[132:135], v[216:219], v[12:15]
	v_mfma_f32_16x16x32_bf16 v[8:11], v[158:161], v[216:219], v[8:11]
	s_setprio 0
	s_setprio 1
	v_mfma_f32_16x16x32_bf16 v[52:55], v[162:165], v[178:181], v[52:55]
	v_mfma_f32_16x16x32_bf16 v[48:51], v[170:173], v[178:181], v[48:51]
	v_mfma_f32_16x16x32_bf16 v[36:39], v[162:165], v[196:199], v[36:39]
	v_mfma_f32_16x16x32_bf16 v[32:35], v[170:173], v[196:199], v[32:35]
	v_mfma_f32_16x16x32_bf16 v[20:23], v[162:165], v[204:207], v[20:23]
	v_mfma_f32_16x16x32_bf16 v[16:19], v[170:173], v[204:207], v[16:19]
	v_mfma_f32_16x16x32_bf16 v[4:7], v[162:165], v[212:215], v[4:7]
	v_mfma_f32_16x16x32_bf16 v[0:3], v[170:173], v[212:215], v[0:3]
	v_mfma_f32_16x16x32_bf16 v[52:55], v[166:169], v[192:195], v[52:55]
	v_mfma_f32_16x16x32_bf16 v[48:51], v[174:177], v[192:195], v[48:51]
	v_mfma_f32_16x16x32_bf16 v[36:39], v[166:169], v[200:203], v[36:39]
	v_mfma_f32_16x16x32_bf16 v[32:35], v[174:177], v[200:203], v[32:35]
	v_mfma_f32_16x16x32_bf16 v[20:23], v[166:169], v[208:211], v[20:23]
	v_mfma_f32_16x16x32_bf16 v[16:19], v[174:177], v[208:211], v[16:19]
	v_mfma_f32_16x16x32_bf16 v[4:7], v[166:169], v[216:219], v[4:7]
	v_mfma_f32_16x16x32_bf16 v[0:3], v[174:177], v[216:219], v[0:3]
	s_setprio 0
	s_barrier
	s_add_u32 s0, s0, 0x100
	s_addc_u32 s1, s1, 0
	s_add_u32 s44, s44, 0x100
	s_addc_u32 s45, s45, 0
	s_cmp_ge_i32 s46, s33
	s_mov_b32 s6, s46
	s_cbranch_scc0 .LBB0_919

; #define PG8_STAGE(bufoff, gbase, voff) do { _Pragma("unroll") for (int _i = 0; _i < 2; ++_i) \
;         __builtin_amdgcn_global_load_lds((const unsigned*)((const char*)(gbase) + (voff)[_i]), (PG8_LAS unsigned*)(lds + (bufoff) + ldsw + _i * 8192), 16, 0, 0); } while (0)
; #define PG8_LDA(dst, b, h) do { _Pragma("unroll") for (int m = 0; m < 4; ++m) _Pragma("unroll") for (int k = 0; k < 2; ++k) dst[m][k] = *(const PG8_LAS bf16x8*)(lds + PG8_SA(b, h) + aoff + m * 2048 + k * 1024); } while (0)
; #define PG8_LDB(dst, b, h) do { _Pragma("unroll") for (int n = 0; n < 2; ++n) _Pragma("unroll") for (int k = 0; k < 2; ++k) dst[n][k] = *(const PG8_LAS bf16x8*)(lds + PG8_SB(b, h) + boff + n * 2048 + k * 1024); } while (0)
; #define PG8_WAIT_V(n) asm volatile("s_waitcnt vmcnt(" #n ")" ::: "memory")
; #define PG8_WAIT_L(n) asm volatile("s_waitcnt lgkmcnt(" #n ")" ::: "memory")
; #define PG8_BAR __builtin_amdgcn_s_barrier()
; #define PG8_SCHED __builtin_amdgcn_sched_barrier(0)
; template <class Epi, class Sched, bool ALIGN_EPI = false, bool SP2 = false>
; __device__ __forceinline__ void gemm_phase(PG8_LAS unsigned char* lds, const Gemm g, const Sched& S, const Epi& E) {
;     ...
;         const char* nA = has_next ? (const char*)g.A + (size_t)nxt.pm * tstep : cA; const char* nB = has_next ? (const char*)g.Bt + (size_t)nxt.pn * tstep : cB;
;         for (int t = 0; t < nt; t += 2) {
;             const bool last = (t == nt - 2);
;             const char* a1 = cA + (size_t)(t + 1) * kstep;
;             const char* a2 = last ? nA : cA + (size_t)(t + 2) * kstep; const char* b2 = last ? nB : cB + (size_t)(t + 2) * kstep;
;             const char* a3 = a2 + kstep; const char* b3 = b2 + kstep;
;             if (last && has_next) S.a_ready(nxt);
;             if constexpr (SP2) {
;             PG8_LDB(B0, 0, 0); PG8_LDB(B1, 0, 1); PG8_SCHED; PG8_LDA(At, 0, 0); PG8_STAGE(PG8_SA(1, 1), a1 + hstep, voffA);
;             PG8_WAIT_V(8); PG8_WAIT_L(0); PG8_BAR; PG8_MMA(0, 0, At, B0); PG8_MMA(0, 1, At, B1); PG8_BAR; PG8_SCHED;
;             PG8_LDA(At, 0, 1); PG8_STAGE(PG8_SB(0, 0), b2, voffB); PG8_STAGE(PG8_SB(0, 1), b2 + hstep, voffB); PG8_STAGE(PG8_SA(0, 0), a2, voffA);
;             PG8_WAIT_V(8); PG8_WAIT_L(0); PG8_BAR; PG8_MMA(1, 0, At, B0); PG8_MMA(1, 1, At, B1); PG8_BAR; PG8_SCHED;
.LBB0_1440:
	ds_read_b128 v[146:149], v164
	ds_read_b128 v[168:171], v164 offset:1024
	ds_read_b128 v[172:175], v164 offset:2048
	ds_read_b128 v[176:179], v164 offset:3072
	ds_read_b128 v[180:183], v165
	ds_read_b128 v[184:187], v165 offset:1024
	ds_read_b128 v[188:191], v165 offset:2048
	ds_read_b128 v[192:195], v165 offset:3072
	s_add_u32 s56, s54, 0xfff80080
	s_addc_u32 s57, s55, -1
	s_cmp_eq_u32 s87, 28
	s_cselect_b32 s59, s47, s57
	s_cselect_b32 s58, s83, s56
	s_cselect_b32 s57, s45, s86
	s_cselect_b32 s56, s84, s85
	v_lshl_add_u64 v[228:229], s[54:55], 0, v[136:137]
	s_add_i32 m0, s65, 0xc000
	ds_read_b128 v[196:199], v166
	ds_read_b128 v[200:203], v166 offset:1024
	ds_read_b128 v[204:207], v166 offset:2048
	ds_read_b128 v[208:211], v166 offset:3072
	ds_read_b128 v[212:215], v166 offset:4096
	ds_read_b128 v[216:219], v166 offset:5120
	ds_read_b128 v[220:223], v166 offset:6144
	ds_read_b128 v[224:227], v166 offset:7168
	global_load_lds_dwordx4 v[228:229], off
	v_lshl_add_u64 v[228:229], s[54:55], 0, v[138:139]
	s_add_i32 m0, s65, 0xe000
	s_nop 0
	global_load_lds_dwordx4 v[228:229], off
	s_waitcnt vmcnt(8)
	s_waitcnt lgkmcnt(0)
	s_barrier
	s_setprio 1
	v_mfma_f32_16x16x32_bf16 v[124:127], v[146:149], v[196:199], v[124:127]
	v_mfma_f32_16x16x32_bf16 v[120:123], v[172:175], v[196:199], v[120:123]
	v_mfma_f32_16x16x32_bf16 v[108:111], v[146:149], v[204:207], v[108:111]
	v_mfma_f32_16x16x32_bf16 v[104:107], v[172:175], v[204:207], v[104:107]
	v_mfma_f32_16x16x32_bf16 v[92:95], v[146:149], v[212:215], v[92:95]
	v_mfma_f32_16x16x32_bf16 v[88:91], v[172:175], v[212:215], v[88:91]
	v_mfma_f32_16x16x32_bf16 v[76:79], v[146:149], v[220:223], v[76:79]
	v_mfma_f32_16x16x32_bf16 v[72:75], v[172:175], v[220:223], v[72:75]
	v_mfma_f32_16x16x32_bf16 v[124:127], v[168:171], v[200:203], v[124:127]
	v_mfma_f32_16x16x32_bf16 v[120:123], v[176:179], v[200:203], v[120:123]
	v_mfma_f32_16x16x32_bf16 v[108:111], v[168:171], v[208:211], v[108:111]
	v_mfma_f32_16x16x32_bf16 v[104:107], v[176:179], v[208:211], v[104:107]
	v_mfma_f32_16x16x32_bf16 v[92:95], v[168:171], v[216:219], v[92:95]
	v_mfma_f32_16x16x32_bf16 v[88:91], v[176:179], v[216:219], v[88:91]
	v_mfma_f32_16x16x32_bf16 v[76:79], v[168:171], v[224:227], v[76:79]
	v_mfma_f32_16x16x32_bf16 v[72:75], v[176:179], v[224:227], v[72:75]
	s_setprio 0
	s_setprio 1
	v_mfma_f32_16x16x32_bf16 v[116:119], v[180:183], v[196:199], v[116:119]
	v_mfma_f32_16x16x32_bf16 v[112:115], v[188:191], v[196:199], v[112:115]
	v_mfma_f32_16x16x32_bf16 v[100:103], v[180:183], v[204:207], v[100:103]
	v_mfma_f32_16x16x32_bf16 v[96:99], v[188:191], v[204:207], v[96:99]
	v_mfma_f32_16x16x32_bf16 v[84:87], v[180:183], v[212:215], v[84:87]
	v_mfma_f32_16x16x32_bf16 v[80:83], v[188:191], v[212:215], v[80:83]
	v_mfma_f32_16x16x32_bf16 v[68:71], v[180:183], v[220:223], v[68:71]
	v_mfma_f32_16x16x32_bf16 v[64:67], v[188:191], v[220:223], v[64:67]
	v_mfma_f32_16x16x32_bf16 v[116:119], v[184:187], v[200:203], v[116:119]
	v_mfma_f32_16x16x32_bf16 v[112:115], v[192:195], v[200:203], v[112:115]
	v_mfma_f32_16x16x32_bf16 v[100:103], v[184:187], v[208:211], v[100:103]
	v_mfma_f32_16x16x32_bf16 v[96:99], v[192:195], v[208:211], v[96:99]
	v_mfma_f32_16x16x32_bf16 v[84:87], v[184:187], v[216:219], v[84:87]
	v_mfma_f32_16x16x32_bf16 v[80:83], v[192:195], v[216:219], v[80:83]
	v_mfma_f32_16x16x32_bf16 v[68:71], v[184:187], v[224:227], v[68:71]
	v_mfma_f32_16x16x32_bf16 v[64:67], v[192:195], v[224:227], v[64:67]
	s_setprio 0
	s_barrier
	s_add_i32 s88, s74, s64
	v_lshl_add_u64 v[228:229], s[56:57], 0, v[130:131]
	s_mov_b32 m0, s88
	ds_read_b128 v[196:199], v166 offset:16384
	ds_read_b128 v[200:203], v166 offset:17408
	ds_read_b128 v[204:207], v166 offset:18432
	ds_read_b128 v[208:211], v166 offset:19456
	ds_read_b128 v[212:215], v166 offset:20480
	ds_read_b128 v[216:219], v166 offset:21504
	ds_read_b128 v[220:223], v166 offset:22528
	ds_read_b128 v[224:227], v166 offset:23552
	global_load_lds_dwordx4 v[228:229], off
	s_add_i32 m0, s88, 0x2000
	s_add_u32 s88, s56, 0x80000
	v_lshl_add_u64 v[230:231], s[56:57], 0, v[134:135]
	s_addc_u32 s89, s57, 0
	s_add_i32 s90, s75, s64
	global_load_lds_dwordx4 v[230:231], off
	v_lshl_add_u64 v[232:233], s[88:89], 0, v[130:131]
	s_mov_b32 m0, s90
	v_lshl_add_u64 v[234:235], s[58:59], 0, v[132:133]
	global_load_lds_dwordx4 v[232:233], off
	v_lshl_add_u64 v[232:233], s[88:89], 0, v[134:135]
	s_add_i32 m0, s90, 0x2000
	s_nop 0
	global_load_lds_dwordx4 v[232:233], off
	v_lshl_add_u64 v[232:233], s[58:59], 0, v[128:129]
	s_mov_b32 m0, s65
	s_nop 0
	global_load_lds_dwordx4 v[232:233], off
	s_mov_b32 m0, s66
	s_nop 0
	global_load_lds_dwordx4 v[234:235], off
	s_waitcnt vmcnt(8)
	s_waitcnt lgkmcnt(0)
	s_barrier
; #define PG8_STAGE(bufoff, gbase, voff) do { _Pragma("unroll") for (int _i = 0; _i < 2; ++_i) \
;         __builtin_amdgcn_global_load_lds((const unsigned*)((const char*)(gbase) + (voff)[_i]), (PG8_LAS unsigned*)(lds + (bufoff) + ldsw + _i * 8192), 16, 0, 0); } while (0)
; #define PG8_LDA(dst, b, h) do { _Pragma("unroll") for (int m = 0; m < 4; ++m) _Pragma("unroll") for (int k = 0; k < 2; ++k) dst[m][k] = *(const PG8_LAS bf16x8*)(lds + PG8_SA(b, h) + aoff + m * 2048 + k * 1024); } while (0)
; #define PG8_LDB(dst, b, h) do { _Pragma("unroll") for (int n = 0; n < 2; ++n) _Pragma("unroll") for (int k = 0; k < 2; ++k) dst[n][k] = *(const PG8_LAS bf16x8*)(lds + PG8_SB(b, h) + boff + n * 2048 + k * 1024); } while (0)
; #define PG8_MMA(ai, bj, At, Bt) do { __builtin_amdgcn_s_setprio(1); _Pragma("unroll") for (int m = 0; m < 4; ++m) _Pragma("unroll") for (int n = 0; n < 2; ++n) _Pragma("unroll") for (int k = 0; k < 2; ++k) \
;         acc[ai][bj][m][n] = __builtin_amdgcn_mfma_f32_16x16x32_bf16(Bt[n][k], At[m][k], acc[ai][bj][m][n], 0, 0, 0); __builtin_amdgcn_s_setprio(0); } while (0)
; #define PG8_WAIT_V(n) asm volatile("s_waitcnt vmcnt(" #n ")" ::: "memory")
; #define PG8_WAIT_L(n) asm volatile("s_waitcnt lgkmcnt(" #n ")" ::: "memory")
; #define PG8_BAR __builtin_amdgcn_s_barrier()
; #define PG8_SCHED __builtin_amdgcn_sched_barrier(0)
; template <class Epi, class Sched, bool ALIGN_EPI = false, bool SP2 = false>
; __device__ __forceinline__ void gemm_phase(PG8_LAS unsigned char* lds, const Gemm g, const Sched& S, const Epi& E) {
;     ...
;             PG8_WAIT_V(8); PG8_WAIT_L(0); PG8_BAR; PG8_MMA(1, 0, At, B0); PG8_MMA(1, 1, At, B1); PG8_BAR; PG8_SCHED;
;             PG8_LDB(B0, 1, 0); PG8_LDB(B1, 1, 1); PG8_SCHED; PG8_LDA(At, 1, 0); PG8_STAGE(PG8_SA(0, 1), a2 + hstep, voffA);
;             PG8_WAIT_V(8); PG8_WAIT_L(0); PG8_BAR; PG8_MMA(0, 0, At, B0); PG8_MMA(0, 1, At, B1); PG8_BAR; PG8_SCHED;
	s_setprio 1
	v_mfma_f32_16x16x32_bf16 v[60:63], v[146:149], v[196:199], v[60:63]
	v_mfma_f32_16x16x32_bf16 v[56:59], v[172:175], v[196:199], v[56:59]
	v_mfma_f32_16x16x32_bf16 v[44:47], v[146:149], v[204:207], v[44:47]
	v_mfma_f32_16x16x32_bf16 v[40:43], v[172:175], v[204:207], v[40:43]
	v_mfma_f32_16x16x32_bf16 v[28:31], v[146:149], v[212:215], v[28:31]
	v_mfma_f32_16x16x32_bf16 v[24:27], v[172:175], v[212:215], v[24:27]
	v_mfma_f32_16x16x32_bf16 v[12:15], v[146:149], v[220:223], v[12:15]
	v_mfma_f32_16x16x32_bf16 v[8:11], v[172:175], v[220:223], v[8:11]
	v_mfma_f32_16x16x32_bf16 v[60:63], v[168:171], v[200:203], v[60:63]
	v_mfma_f32_16x16x32_bf16 v[56:59], v[176:179], v[200:203], v[56:59]
	v_mfma_f32_16x16x32_bf16 v[44:47], v[168:171], v[208:211], v[44:47]
	v_mfma_f32_16x16x32_bf16 v[40:43], v[176:179], v[208:211], v[40:43]
	v_mfma_f32_16x16x32_bf16 v[28:31], v[168:171], v[216:219], v[28:31]
	v_mfma_f32_16x16x32_bf16 v[24:27], v[176:179], v[216:219], v[24:27]
	v_mfma_f32_16x16x32_bf16 v[12:15], v[168:171], v[224:227], v[12:15]
	v_mfma_f32_16x16x32_bf16 v[8:11], v[176:179], v[224:227], v[8:11]
	s_setprio 0
	s_setprio 1
	v_mfma_f32_16x16x32_bf16 v[52:55], v[180:183], v[196:199], v[52:55]
	v_mfma_f32_16x16x32_bf16 v[48:51], v[188:191], v[196:199], v[48:51]
	v_mfma_f32_16x16x32_bf16 v[36:39], v[180:183], v[204:207], v[36:39]
	v_mfma_f32_16x16x32_bf16 v[32:35], v[188:191], v[204:207], v[32:35]
	v_mfma_f32_16x16x32_bf16 v[20:23], v[180:183], v[212:215], v[20:23]
	v_mfma_f32_16x16x32_bf16 v[16:19], v[188:191], v[212:215], v[16:19]
	v_mfma_f32_16x16x32_bf16 v[4:7], v[180:183], v[220:223], v[4:7]
	v_mfma_f32_16x16x32_bf16 v[0:3], v[188:191], v[220:223], v[0:3]
	v_mfma_f32_16x16x32_bf16 v[52:55], v[184:187], v[200:203], v[52:55]
	v_mfma_f32_16x16x32_bf16 v[48:51], v[192:195], v[200:203], v[48:51]
	v_mfma_f32_16x16x32_bf16 v[36:39], v[184:187], v[208:211], v[36:39]
	v_mfma_f32_16x16x32_bf16 v[32:35], v[192:195], v[208:211], v[32:35]
	v_mfma_f32_16x16x32_bf16 v[20:23], v[184:187], v[216:219], v[20:23]
	v_mfma_f32_16x16x32_bf16 v[16:19], v[192:195], v[216:219], v[16:19]
	v_mfma_f32_16x16x32_bf16 v[4:7], v[184:187], v[224:227], v[4:7]
	v_mfma_f32_16x16x32_bf16 v[0:3], v[192:195], v[224:227], v[0:3]
	s_setprio 0
	s_barrier
	s_add_i32 s88, 0, 0x18000
	v_add_u32_e32 v167, s88, v163
	s_add_i32 s89, 0, 0x1c000
	ds_read_b128 v[146:149], v167
	ds_read_b128 v[168:171], v167 offset:1024
	ds_read_b128 v[172:175], v167 offset:2048
	ds_read_b128 v[176:179], v167 offset:3072
	v_add_u32_e32 v167, s89, v163
	ds_read_b128 v[180:183], v167
	ds_read_b128 v[184:187], v167 offset:1024
	ds_read_b128 v[188:191], v167 offset:2048
	ds_read_b128 v[192:195], v167 offset:3072
	s_add_u32 s58, s58, 0x80000
	s_addc_u32 s59, s59, 0
	s_mov_b32 m0, s67
	v_lshl_add_u64 v[236:237], s[58:59], 0, v[128:129]
	ds_read_b128 v[196:199], v166 offset:32768
	ds_read_b128 v[200:203], v166 offset:33792
	ds_read_b128 v[204:207], v166 offset:34816
	ds_read_b128 v[208:211], v166 offset:35840
	ds_read_b128 v[212:215], v166 offset:36864
	ds_read_b128 v[216:219], v166 offset:37888
	ds_read_b128 v[220:223], v166 offset:38912
	ds_read_b128 v[224:227], v166 offset:39936
	global_load_lds_dwordx4 v[236:237], off
	v_lshl_add_u64 v[236:237], s[58:59], 0, v[132:133]
	s_mov_b32 m0, s68
	s_nop 0
	global_load_lds_dwordx4 v[236:237], off
	s_waitcnt vmcnt(8)
	s_waitcnt lgkmcnt(0)
	s_barrier
	s_setprio 1
	v_mfma_f32_16x16x32_bf16 v[124:127], v[146:149], v[196:199], v[124:127]
	v_mfma_f32_16x16x32_bf16 v[120:123], v[172:175], v[196:199], v[120:123]
	v_mfma_f32_16x16x32_bf16 v[108:111], v[146:149], v[204:207], v[108:111]
	v_mfma_f32_16x16x32_bf16 v[104:107], v[172:175], v[204:207], v[104:107]
	v_mfma_f32_16x16x32_bf16 v[92:95], v[146:149], v[212:215], v[92:95]
	v_mfma_f32_16x16x32_bf16 v[88:91], v[172:175], v[212:215], v[88:91]
	v_mfma_f32_16x16x32_bf16 v[76:79], v[146:149], v[220:223], v[76:79]
	v_mfma_f32_16x16x32_bf16 v[72:75], v[172:175], v[220:223], v[72:75]
	v_mfma_f32_16x16x32_bf16 v[124:127], v[168:171], v[200:203], v[124:127]
	v_mfma_f32_16x16x32_bf16 v[120:123], v[176:179], v[200:203], v[120:123]
	v_mfma_f32_16x16x32_bf16 v[108:111], v[168:171], v[208:211], v[108:111]
	v_mfma_f32_16x16x32_bf16 v[104:107], v[176:179], v[208:211], v[104:107]
	v_mfma_f32_16x16x32_bf16 v[92:95], v[168:171], v[216:219], v[92:95]
	v_mfma_f32_16x16x32_bf16 v[88:91], v[176:179], v[216:219], v[88:91]
	v_mfma_f32_16x16x32_bf16 v[76:79], v[168:171], v[224:227], v[76:79]
	v_mfma_f32_16x16x32_bf16 v[72:75], v[176:179], v[224:227], v[72:75]
	s_setprio 0
	s_setprio 1
	v_mfma_f32_16x16x32_bf16 v[116:119], v[180:183], v[196:199], v[116:119]
	v_mfma_f32_16x16x32_bf16 v[112:115], v[188:191], v[196:199], v[112:115]
	v_mfma_f32_16x16x32_bf16 v[100:103], v[180:183], v[204:207], v[100:103]
	v_mfma_f32_16x16x32_bf16 v[96:99], v[188:191], v[204:207], v[96:99]
	v_mfma_f32_16x16x32_bf16 v[84:87], v[180:183], v[212:215], v[84:87]
	v_mfma_f32_16x16x32_bf16 v[80:83], v[188:191], v[212:215], v[80:83]
	v_mfma_f32_16x16x32_bf16 v[68:71], v[180:183], v[220:223], v[68:71]
	v_mfma_f32_16x16x32_bf16 v[64:67], v[188:191], v[220:223], v[64:67]
	v_mfma_f32_16x16x32_bf16 v[116:119], v[184:187], v[200:203], v[116:119]
	v_mfma_f32_16x16x32_bf16 v[112:115], v[192:195], v[200:203], v[112:115]
	v_mfma_f32_16x16x32_bf16 v[100:103], v[184:187], v[208:211], v[100:103]
	v_mfma_f32_16x16x32_bf16 v[96:99], v[192:195], v[208:211], v[96:99]
	v_mfma_f32_16x16x32_bf16 v[84:87], v[184:187], v[216:219], v[84:87]
	v_mfma_f32_16x16x32_bf16 v[80:83], v[192:195], v[216:219], v[80:83]
	v_mfma_f32_16x16x32_bf16 v[68:71], v[184:187], v[224:227], v[68:71]
	v_mfma_f32_16x16x32_bf16 v[64:67], v[192:195], v[224:227], v[64:67]
	s_setprio 0
	s_barrier
; #define PG8_STAGE(bufoff, gbase, voff) do { _Pragma("unroll") for (int _i = 0; _i < 2; ++_i) \
;         __builtin_amdgcn_global_load_lds((const unsigned*)((const char*)(gbase) + (voff)[_i]), (PG8_LAS unsigned*)(lds + (bufoff) + ldsw + _i * 8192), 16, 0, 0); } while (0)
; #define PG8_LDA(dst, b, h) do { _Pragma("unroll") for (int m = 0; m < 4; ++m) _Pragma("unroll") for (int k = 0; k < 2; ++k) dst[m][k] = *(const PG8_LAS bf16x8*)(lds + PG8_SA(b, h) + aoff + m * 2048 + k * 1024); } while (0)
; #define PG8_MMA(ai, bj, At, Bt) do { __builtin_amdgcn_s_setprio(1); _Pragma("unroll") for (int m = 0; m < 4; ++m) _Pragma("unroll") for (int n = 0; n < 2; ++n) _Pragma("unroll") for (int k = 0; k < 2; ++k) \
;         acc[ai][bj][m][n] = __builtin_amdgcn_mfma_f32_16x16x32_bf16(Bt[n][k], At[m][k], acc[ai][bj][m][n], 0, 0, 0); __builtin_amdgcn_s_setprio(0); } while (0)
; #define PG8_WAIT_V(n) asm volatile("s_waitcnt vmcnt(" #n ")" ::: "memory")
; #define PG8_WAIT_L(n) asm volatile("s_waitcnt lgkmcnt(" #n ")" ::: "memory")
; #define PG8_BAR __builtin_amdgcn_s_barrier()
; #define PG8_SCHED __builtin_amdgcn_sched_barrier(0)
; template <class Epi, class Sched, bool ALIGN_EPI = false, bool SP2 = false>
; __device__ __forceinline__ void gemm_phase(PG8_LAS unsigned char* lds, const Gemm g, const Sched& S, const Epi& E) {
;     ...
;             PG8_LDA(At, 1, 1); PG8_STAGE(PG8_SB(1, 0), b3, voffB); PG8_STAGE(PG8_SB(1, 1), b3 + hstep, voffB); PG8_STAGE(PG8_SA(1, 0), a3, voffA);
;             PG8_WAIT_V(8); PG8_WAIT_L(0); PG8_BAR; PG8_MMA(1, 0, At, B0); PG8_MMA(1, 1, At, B1); PG8_BAR; PG8_SCHED;
;     ...
;         if constexpr (ALIGN_EPI) { if (wr == 0) PG8_BAR; }
	s_add_i32 s58, s88, s64
	v_lshl_add_u64 v[228:229], v[228:229], 0, s[12:13]
	s_mov_b32 m0, s58
	ds_read_b128 v[196:199], v166 offset:49152
	ds_read_b128 v[200:203], v166 offset:50176
	ds_read_b128 v[204:207], v166 offset:51200
	ds_read_b128 v[208:211], v166 offset:52224
	ds_read_b128 v[212:215], v166 offset:53248
	ds_read_b128 v[216:219], v166 offset:54272
	ds_read_b128 v[220:223], v166 offset:55296
	ds_read_b128 v[224:227], v166 offset:56320
	global_load_lds_dwordx4 v[228:229], off
	s_add_i32 m0, s58, 0x2000
	s_add_u32 s56, s56, 0x80080
	v_lshl_add_u64 v[228:229], v[230:231], 0, s[12:13]
	s_addc_u32 s57, s57, 0
	s_add_i32 s58, s89, s64
	global_load_lds_dwordx4 v[228:229], off
	v_lshl_add_u64 v[228:229], s[56:57], 0, v[130:131]
	s_mov_b32 m0, s58
	s_nop 0
	global_load_lds_dwordx4 v[228:229], off
	v_lshl_add_u64 v[228:229], s[56:57], 0, v[134:135]
	s_add_i32 m0, s58, 0x2000
	s_nop 0
	global_load_lds_dwordx4 v[228:229], off
	v_lshl_add_u64 v[228:229], v[232:233], 0, s[12:13]
	s_mov_b32 m0, s71
	s_nop 0
	global_load_lds_dwordx4 v[228:229], off
	v_lshl_add_u64 v[228:229], v[234:235], 0, s[12:13]
	s_mov_b32 m0, s72
	s_nop 0
	global_load_lds_dwordx4 v[228:229], off
	s_waitcnt vmcnt(8)
	s_waitcnt lgkmcnt(0)
	s_barrier
	s_setprio 1
	v_mfma_f32_16x16x32_bf16 v[60:63], v[146:149], v[196:199], v[60:63]
	v_mfma_f32_16x16x32_bf16 v[56:59], v[172:175], v[196:199], v[56:59]
	v_mfma_f32_16x16x32_bf16 v[44:47], v[146:149], v[204:207], v[44:47]
	v_mfma_f32_16x16x32_bf16 v[40:43], v[172:175], v[204:207], v[40:43]
	v_mfma_f32_16x16x32_bf16 v[28:31], v[146:149], v[212:215], v[28:31]
	v_mfma_f32_16x16x32_bf16 v[24:27], v[172:175], v[212:215], v[24:27]
	v_mfma_f32_16x16x32_bf16 v[12:15], v[146:149], v[220:223], v[12:15]
	v_mfma_f32_16x16x32_bf16 v[8:11], v[172:175], v[220:223], v[8:11]
	v_mfma_f32_16x16x32_bf16 v[60:63], v[168:171], v[200:203], v[60:63]
	v_mfma_f32_16x16x32_bf16 v[56:59], v[176:179], v[200:203], v[56:59]
	v_mfma_f32_16x16x32_bf16 v[44:47], v[168:171], v[208:211], v[44:47]
	v_mfma_f32_16x16x32_bf16 v[40:43], v[176:179], v[208:211], v[40:43]
	v_mfma_f32_16x16x32_bf16 v[28:31], v[168:171], v[216:219], v[28:31]
	v_mfma_f32_16x16x32_bf16 v[24:27], v[176:179], v[216:219], v[24:27]
	v_mfma_f32_16x16x32_bf16 v[12:15], v[168:171], v[224:227], v[12:15]
	v_mfma_f32_16x16x32_bf16 v[8:11], v[176:179], v[224:227], v[8:11]
	s_setprio 0
	s_setprio 1
	v_mfma_f32_16x16x32_bf16 v[52:55], v[180:183], v[196:199], v[52:55]
	v_mfma_f32_16x16x32_bf16 v[48:51], v[188:191], v[196:199], v[48:51]
	v_mfma_f32_16x16x32_bf16 v[36:39], v[180:183], v[204:207], v[36:39]
	v_mfma_f32_16x16x32_bf16 v[32:35], v[188:191], v[204:207], v[32:35]
	v_mfma_f32_16x16x32_bf16 v[20:23], v[180:183], v[212:215], v[20:23]
	v_mfma_f32_16x16x32_bf16 v[16:19], v[188:191], v[212:215], v[16:19]
	v_mfma_f32_16x16x32_bf16 v[4:7], v[180:183], v[220:223], v[4:7]
	v_mfma_f32_16x16x32_bf16 v[0:3], v[188:191], v[220:223], v[0:3]
	v_mfma_f32_16x16x32_bf16 v[52:55], v[184:187], v[200:203], v[52:55]
	v_mfma_f32_16x16x32_bf16 v[48:51], v[192:195], v[200:203], v[48:51]
	v_mfma_f32_16x16x32_bf16 v[36:39], v[184:187], v[208:211], v[36:39]
	v_mfma_f32_16x16x32_bf16 v[32:35], v[192:195], v[208:211], v[32:35]
	v_mfma_f32_16x16x32_bf16 v[20:23], v[184:187], v[216:219], v[20:23]
	v_mfma_f32_16x16x32_bf16 v[16:19], v[192:195], v[216:219], v[16:19]
	v_mfma_f32_16x16x32_bf16 v[4:7], v[184:187], v[224:227], v[4:7]
	v_mfma_f32_16x16x32_bf16 v[0:3], v[192:195], v[224:227], v[0:3]
	s_setprio 0
	s_barrier
	s_add_i32 s87, s87, 2
	s_add_u32 s54, s54, 0x100
	s_addc_u32 s55, s55, 0
	s_add_u32 s85, s85, 0x100
	s_addc_u32 s86, s86, 0
	s_cmp_gt_u32 s87, 29
	s_cbranch_scc0 .LBB0_1440
	s_and_b64 vcc, exec, s[14:15]
	s_cbranch_vccz .LBB0_1443
	s_barrier

; #define PG8_STAGE(bufoff, gbase, voff) do { _Pragma("unroll") for (int _i = 0; _i < 2; ++_i) \
;         __builtin_amdgcn_global_load_lds((const unsigned*)((const char*)(gbase) + (voff)[_i]), (PG8_LAS unsigned*)(lds + (bufoff) + ldsw + _i * 8192), 16, 0, 0); } while (0)
; #define PG8_LDA(dst, b, h) do { _Pragma("unroll") for (int m = 0; m < 4; ++m) _Pragma("unroll") for (int k = 0; k < 2; ++k) dst[m][k] = *(const PG8_LAS bf16x8*)(lds + PG8_SA(b, h) + aoff + m * 2048 + k * 1024); } while (0)
; #define PG8_LDB(dst, b, h) do { _Pragma("unroll") for (int n = 0; n < 2; ++n) _Pragma("unroll") for (int k = 0; k < 2; ++k) dst[n][k] = *(const PG8_LAS bf16x8*)(lds + PG8_SB(b, h) + boff + n * 2048 + k * 1024); } while (0)
; #define PG8_WAIT_V(n) asm volatile("s_waitcnt vmcnt(" #n ")" ::: "memory")
; #define PG8_WAIT_L(n) asm volatile("s_waitcnt lgkmcnt(" #n ")" ::: "memory")
; #define PG8_BAR __builtin_amdgcn_s_barrier()
; #define PG8_SCHED __builtin_amdgcn_sched_barrier(0)
; template <class Epi, class Sched, bool ALIGN_EPI = false, bool SP2 = false>
; __device__ __forceinline__ void gemm_phase(PG8_LAS unsigned char* lds, const Gemm g, const Sched& S, const Epi& E) {
;     ...
;         const char* nA = has_next ? (const char*)g.A + (size_t)nxt.pm * tstep : cA; const char* nB = has_next ? (const char*)g.Bt + (size_t)nxt.pn * tstep : cB;
;         for (int t = 0; t < nt; t += 2) {
;             const bool last = (t == nt - 2);
;             const char* a1 = cA + (size_t)(t + 1) * kstep;
;             const char* a2 = last ? nA : cA + (size_t)(t + 2) * kstep; const char* b2 = last ? nB : cB + (size_t)(t + 2) * kstep;
;             const char* a3 = a2 + kstep; const char* b3 = b2 + kstep;
;             if (last && has_next) S.a_ready(nxt);
;             if constexpr (SP2) {
;             PG8_LDB(B0, 0, 0); PG8_LDB(B1, 0, 1); PG8_SCHED; PG8_LDA(At, 0, 0); PG8_STAGE(PG8_SA(1, 1), a1 + hstep, voffA);
;             PG8_WAIT_V(8); PG8_WAIT_L(0); PG8_BAR; PG8_MMA(0, 0, At, B0); PG8_MMA(0, 1, At, B1); PG8_BAR; PG8_SCHED;
;             PG8_LDA(At, 0, 1); PG8_STAGE(PG8_SB(0, 0), b2, voffB); PG8_STAGE(PG8_SB(0, 1), b2 + hstep, voffB); PG8_STAGE(PG8_SA(0, 0), a2, voffA);
;             PG8_WAIT_V(8); PG8_WAIT_L(0); PG8_BAR; PG8_MMA(1, 0, At, B0); PG8_MMA(1, 1, At, B1); PG8_BAR; PG8_SCHED;
.LBB0_1460:
	ds_read_b128 v[152:155], v147
	ds_read_b128 v[156:159], v147 offset:1024
	ds_read_b128 v[160:163], v147 offset:2048
	ds_read_b128 v[164:167], v147 offset:3072
	ds_read_b128 v[168:171], v148
	ds_read_b128 v[172:175], v148 offset:1024
	ds_read_b128 v[176:179], v148 offset:2048
	ds_read_b128 v[180:183], v148 offset:3072
	s_add_u32 s56, s54, 0xfffc0080
	s_addc_u32 s57, s55, -1
	s_cmp_eq_u32 s85, 12
	s_cselect_b32 s59, s47, s57
	s_cselect_b32 s58, s81, s56
	s_cselect_b32 s57, s45, s84
	s_cselect_b32 s56, s82, s83
	v_lshl_add_u64 v[216:217], s[54:55], 0, v[136:137]
	s_add_i32 m0, s43, 0xc000
	ds_read_b128 v[184:187], v149
	ds_read_b128 v[188:191], v149 offset:1024
	ds_read_b128 v[192:195], v149 offset:2048
	ds_read_b128 v[196:199], v149 offset:3072
	ds_read_b128 v[200:203], v149 offset:4096
	ds_read_b128 v[204:207], v149 offset:5120
	ds_read_b128 v[208:211], v149 offset:6144
	ds_read_b128 v[212:215], v149 offset:7168
	global_load_lds_dwordx4 v[216:217], off
	v_lshl_add_u64 v[216:217], s[54:55], 0, v[138:139]
	s_add_i32 m0, s43, 0xe000
	s_nop 0
	global_load_lds_dwordx4 v[216:217], off
	s_waitcnt vmcnt(8)
	s_waitcnt lgkmcnt(0)
	s_barrier
	s_setprio 1
	v_mfma_f32_16x16x32_bf16 v[124:127], v[152:155], v[184:187], v[124:127]
	v_mfma_f32_16x16x32_bf16 v[120:123], v[160:163], v[184:187], v[120:123]
	v_mfma_f32_16x16x32_bf16 v[116:119], v[152:155], v[192:195], v[116:119]
	v_mfma_f32_16x16x32_bf16 v[112:115], v[160:163], v[192:195], v[112:115]
	v_mfma_f32_16x16x32_bf16 v[100:103], v[152:155], v[200:203], v[100:103]
	v_mfma_f32_16x16x32_bf16 v[96:99], v[160:163], v[200:203], v[96:99]
	v_mfma_f32_16x16x32_bf16 v[84:87], v[152:155], v[208:211], v[84:87]
	v_mfma_f32_16x16x32_bf16 v[80:83], v[160:163], v[208:211], v[80:83]
	v_mfma_f32_16x16x32_bf16 v[124:127], v[156:159], v[188:191], v[124:127]
	v_mfma_f32_16x16x32_bf16 v[120:123], v[164:167], v[188:191], v[120:123]
	v_mfma_f32_16x16x32_bf16 v[116:119], v[156:159], v[196:199], v[116:119]
	v_mfma_f32_16x16x32_bf16 v[112:115], v[164:167], v[196:199], v[112:115]
	v_mfma_f32_16x16x32_bf16 v[100:103], v[156:159], v[204:207], v[100:103]
	v_mfma_f32_16x16x32_bf16 v[96:99], v[164:167], v[204:207], v[96:99]
	v_mfma_f32_16x16x32_bf16 v[84:87], v[156:159], v[212:215], v[84:87]
	v_mfma_f32_16x16x32_bf16 v[80:83], v[164:167], v[212:215], v[80:83]
	s_setprio 0
	s_setprio 1
	v_mfma_f32_16x16x32_bf16 v[108:111], v[168:171], v[184:187], v[108:111]
	v_mfma_f32_16x16x32_bf16 v[104:107], v[176:179], v[184:187], v[104:107]
	v_mfma_f32_16x16x32_bf16 v[92:95], v[168:171], v[192:195], v[92:95]
	v_mfma_f32_16x16x32_bf16 v[88:91], v[176:179], v[192:195], v[88:91]
	v_mfma_f32_16x16x32_bf16 v[76:79], v[168:171], v[200:203], v[76:79]
	v_mfma_f32_16x16x32_bf16 v[72:75], v[176:179], v[200:203], v[72:75]
	v_mfma_f32_16x16x32_bf16 v[68:71], v[168:171], v[208:211], v[68:71]
	v_mfma_f32_16x16x32_bf16 v[64:67], v[176:179], v[208:211], v[64:67]
	v_mfma_f32_16x16x32_bf16 v[108:111], v[172:175], v[188:191], v[108:111]
	v_mfma_f32_16x16x32_bf16 v[104:107], v[180:183], v[188:191], v[104:107]
	v_mfma_f32_16x16x32_bf16 v[92:95], v[172:175], v[196:199], v[92:95]
	v_mfma_f32_16x16x32_bf16 v[88:91], v[180:183], v[196:199], v[88:91]
	v_mfma_f32_16x16x32_bf16 v[76:79], v[172:175], v[204:207], v[76:79]
	v_mfma_f32_16x16x32_bf16 v[72:75], v[180:183], v[204:207], v[72:75]
	v_mfma_f32_16x16x32_bf16 v[68:71], v[172:175], v[212:215], v[68:71]
	v_mfma_f32_16x16x32_bf16 v[64:67], v[180:183], v[212:215], v[64:67]
	s_setprio 0
	s_barrier
	s_add_i32 s86, s72, s60
	v_lshl_add_u64 v[216:217], s[56:57], 0, v[130:131]
	s_mov_b32 m0, s86
	ds_read_b128 v[184:187], v149 offset:16384
	ds_read_b128 v[188:191], v149 offset:17408
	ds_read_b128 v[192:195], v149 offset:18432
	ds_read_b128 v[196:199], v149 offset:19456
	ds_read_b128 v[200:203], v149 offset:20480
	ds_read_b128 v[204:207], v149 offset:21504
	ds_read_b128 v[208:211], v149 offset:22528
	ds_read_b128 v[212:215], v149 offset:23552
	global_load_lds_dwordx4 v[216:217], off
	s_add_i32 m0, s86, 0x2000
	s_add_u32 s86, s56, 0x40000
	v_lshl_add_u64 v[218:219], s[56:57], 0, v[134:135]
	s_addc_u32 s87, s57, 0
	s_add_i32 s88, s73, s60
	global_load_lds_dwordx4 v[218:219], off
	v_lshl_add_u64 v[220:221], s[86:87], 0, v[130:131]
	s_mov_b32 m0, s88
	v_lshl_add_u64 v[222:223], s[58:59], 0, v[132:133]
	global_load_lds_dwordx4 v[220:221], off
	v_lshl_add_u64 v[220:221], s[86:87], 0, v[134:135]
	s_add_i32 m0, s88, 0x2000
	s_nop 0
	global_load_lds_dwordx4 v[220:221], off
	v_lshl_add_u64 v[220:221], s[58:59], 0, v[128:129]
	s_mov_b32 m0, s43
	s_nop 0
	global_load_lds_dwordx4 v[220:221], off
	s_mov_b32 m0, s50
	s_nop 0
	global_load_lds_dwordx4 v[222:223], off
	s_waitcnt vmcnt(8)
	s_waitcnt lgkmcnt(0)
	s_barrier
; #define PG8_STAGE(bufoff, gbase, voff) do { _Pragma("unroll") for (int _i = 0; _i < 2; ++_i) \
;         __builtin_amdgcn_global_load_lds((const unsigned*)((const char*)(gbase) + (voff)[_i]), (PG8_LAS unsigned*)(lds + (bufoff) + ldsw + _i * 8192), 16, 0, 0); } while (0)
; #define PG8_LDA(dst, b, h) do { _Pragma("unroll") for (int m = 0; m < 4; ++m) _Pragma("unroll") for (int k = 0; k < 2; ++k) dst[m][k] = *(const PG8_LAS bf16x8*)(lds + PG8_SA(b, h) + aoff + m * 2048 + k * 1024); } while (0)
; #define PG8_LDB(dst, b, h) do { _Pragma("unroll") for (int n = 0; n < 2; ++n) _Pragma("unroll") for (int k = 0; k < 2; ++k) dst[n][k] = *(const PG8_LAS bf16x8*)(lds + PG8_SB(b, h) + boff + n * 2048 + k * 1024); } while (0)
; #define PG8_MMA(ai, bj, At, Bt) do { __builtin_amdgcn_s_setprio(1); _Pragma("unroll") for (int m = 0; m < 4; ++m) _Pragma("unroll") for (int n = 0; n < 2; ++n) _Pragma("unroll") for (int k = 0; k < 2; ++k) \
;         acc[ai][bj][m][n] = __builtin_amdgcn_mfma_f32_16x16x32_bf16(Bt[n][k], At[m][k], acc[ai][bj][m][n], 0, 0, 0); __builtin_amdgcn_s_setprio(0); } while (0)
; #define PG8_WAIT_V(n) asm volatile("s_waitcnt vmcnt(" #n ")" ::: "memory")
; #define PG8_WAIT_L(n) asm volatile("s_waitcnt lgkmcnt(" #n ")" ::: "memory")
; #define PG8_BAR __builtin_amdgcn_s_barrier()
; #define PG8_SCHED __builtin_amdgcn_sched_barrier(0)
; template <class Epi, class Sched, bool ALIGN_EPI = false, bool SP2 = false>
; __device__ __forceinline__ void gemm_phase(PG8_LAS unsigned char* lds, const Gemm g, const Sched& S, const Epi& E) {
;     ...
;             PG8_WAIT_V(8); PG8_WAIT_L(0); PG8_BAR; PG8_MMA(1, 0, At, B0); PG8_MMA(1, 1, At, B1); PG8_BAR; PG8_SCHED;
;             PG8_LDB(B0, 1, 0); PG8_LDB(B1, 1, 1); PG8_SCHED; PG8_LDA(At, 1, 0); PG8_STAGE(PG8_SA(0, 1), a2 + hstep, voffA);
;             PG8_WAIT_V(8); PG8_WAIT_L(0); PG8_BAR; PG8_MMA(0, 0, At, B0); PG8_MMA(0, 1, At, B1); PG8_BAR; PG8_SCHED;
	s_setprio 1
	v_mfma_f32_16x16x32_bf16 v[60:63], v[152:155], v[184:187], v[60:63]
	v_mfma_f32_16x16x32_bf16 v[56:59], v[160:163], v[184:187], v[56:59]
	v_mfma_f32_16x16x32_bf16 v[52:55], v[152:155], v[192:195], v[52:55]
	v_mfma_f32_16x16x32_bf16 v[48:51], v[160:163], v[192:195], v[48:51]
	v_mfma_f32_16x16x32_bf16 v[36:39], v[152:155], v[200:203], v[36:39]
	v_mfma_f32_16x16x32_bf16 v[32:35], v[160:163], v[200:203], v[32:35]
	v_mfma_f32_16x16x32_bf16 v[20:23], v[152:155], v[208:211], v[20:23]
	v_mfma_f32_16x16x32_bf16 v[16:19], v[160:163], v[208:211], v[16:19]
	v_mfma_f32_16x16x32_bf16 v[60:63], v[156:159], v[188:191], v[60:63]
	v_mfma_f32_16x16x32_bf16 v[56:59], v[164:167], v[188:191], v[56:59]
	v_mfma_f32_16x16x32_bf16 v[52:55], v[156:159], v[196:199], v[52:55]
	v_mfma_f32_16x16x32_bf16 v[48:51], v[164:167], v[196:199], v[48:51]
	v_mfma_f32_16x16x32_bf16 v[36:39], v[156:159], v[204:207], v[36:39]
	v_mfma_f32_16x16x32_bf16 v[32:35], v[164:167], v[204:207], v[32:35]
	v_mfma_f32_16x16x32_bf16 v[20:23], v[156:159], v[212:215], v[20:23]
	v_mfma_f32_16x16x32_bf16 v[16:19], v[164:167], v[212:215], v[16:19]
	s_setprio 0
	s_setprio 1
	v_mfma_f32_16x16x32_bf16 v[44:47], v[168:171], v[184:187], v[44:47]
	v_mfma_f32_16x16x32_bf16 v[40:43], v[176:179], v[184:187], v[40:43]
	v_mfma_f32_16x16x32_bf16 v[28:31], v[168:171], v[192:195], v[28:31]
	v_mfma_f32_16x16x32_bf16 v[24:27], v[176:179], v[192:195], v[24:27]
	v_mfma_f32_16x16x32_bf16 v[12:15], v[168:171], v[200:203], v[12:15]
	v_mfma_f32_16x16x32_bf16 v[8:11], v[176:179], v[200:203], v[8:11]
	v_mfma_f32_16x16x32_bf16 v[4:7], v[168:171], v[208:211], v[4:7]
	v_mfma_f32_16x16x32_bf16 v[0:3], v[176:179], v[208:211], v[0:3]
	v_mfma_f32_16x16x32_bf16 v[44:47], v[172:175], v[188:191], v[44:47]
	v_mfma_f32_16x16x32_bf16 v[40:43], v[180:183], v[188:191], v[40:43]
	v_mfma_f32_16x16x32_bf16 v[28:31], v[172:175], v[196:199], v[28:31]
	v_mfma_f32_16x16x32_bf16 v[24:27], v[180:183], v[196:199], v[24:27]
	v_mfma_f32_16x16x32_bf16 v[12:15], v[172:175], v[204:207], v[12:15]
	v_mfma_f32_16x16x32_bf16 v[8:11], v[180:183], v[204:207], v[8:11]
	v_mfma_f32_16x16x32_bf16 v[4:7], v[172:175], v[212:215], v[4:7]
	v_mfma_f32_16x16x32_bf16 v[0:3], v[180:183], v[212:215], v[0:3]
	s_setprio 0
	s_barrier
	s_add_i32 s86, 0, 0x18000
	s_add_i32 s87, 0, 0x1c000
	v_add_u32_e32 v164, s86, v146
	v_add_u32_e32 v180, s87, v146
	ds_read_b128 v[152:155], v164
	ds_read_b128 v[156:159], v164 offset:1024
	ds_read_b128 v[160:163], v164 offset:2048
	ds_read_b128 v[164:167], v164 offset:3072
	ds_read_b128 v[168:171], v180
	ds_read_b128 v[172:175], v180 offset:1024
	ds_read_b128 v[176:179], v180 offset:2048
	ds_read_b128 v[180:183], v180 offset:3072
	s_add_u32 s58, s58, 0x40000
	s_addc_u32 s59, s59, 0
	s_mov_b32 m0, s51
	v_lshl_add_u64 v[224:225], s[58:59], 0, v[128:129]
	ds_read_b128 v[184:187], v149 offset:32768
	ds_read_b128 v[188:191], v149 offset:33792
	ds_read_b128 v[192:195], v149 offset:34816
	ds_read_b128 v[196:199], v149 offset:35840
	ds_read_b128 v[200:203], v149 offset:36864
	ds_read_b128 v[204:207], v149 offset:37888
	ds_read_b128 v[208:211], v149 offset:38912
	ds_read_b128 v[212:215], v149 offset:39936
	global_load_lds_dwordx4 v[224:225], off
	v_lshl_add_u64 v[224:225], s[58:59], 0, v[132:133]
	s_mov_b32 m0, s65
	s_nop 0
	global_load_lds_dwordx4 v[224:225], off
	s_waitcnt vmcnt(8)
	s_waitcnt lgkmcnt(0)
	s_barrier
	s_setprio 1
	v_mfma_f32_16x16x32_bf16 v[124:127], v[152:155], v[184:187], v[124:127]
	v_mfma_f32_16x16x32_bf16 v[120:123], v[160:163], v[184:187], v[120:123]
	v_mfma_f32_16x16x32_bf16 v[116:119], v[152:155], v[192:195], v[116:119]
	v_mfma_f32_16x16x32_bf16 v[112:115], v[160:163], v[192:195], v[112:115]
	v_mfma_f32_16x16x32_bf16 v[100:103], v[152:155], v[200:203], v[100:103]
	v_mfma_f32_16x16x32_bf16 v[96:99], v[160:163], v[200:203], v[96:99]
	v_mfma_f32_16x16x32_bf16 v[84:87], v[152:155], v[208:211], v[84:87]
	v_mfma_f32_16x16x32_bf16 v[80:83], v[160:163], v[208:211], v[80:83]
	v_mfma_f32_16x16x32_bf16 v[124:127], v[156:159], v[188:191], v[124:127]
	v_mfma_f32_16x16x32_bf16 v[120:123], v[164:167], v[188:191], v[120:123]
	v_mfma_f32_16x16x32_bf16 v[116:119], v[156:159], v[196:199], v[116:119]
	v_mfma_f32_16x16x32_bf16 v[112:115], v[164:167], v[196:199], v[112:115]
	v_mfma_f32_16x16x32_bf16 v[100:103], v[156:159], v[204:207], v[100:103]
	v_mfma_f32_16x16x32_bf16 v[96:99], v[164:167], v[204:207], v[96:99]
	v_mfma_f32_16x16x32_bf16 v[84:87], v[156:159], v[212:215], v[84:87]
	v_mfma_f32_16x16x32_bf16 v[80:83], v[164:167], v[212:215], v[80:83]
	s_setprio 0
	s_setprio 1
	v_mfma_f32_16x16x32_bf16 v[108:111], v[168:171], v[184:187], v[108:111]
	v_mfma_f32_16x16x32_bf16 v[104:107], v[176:179], v[184:187], v[104:107]
	v_mfma_f32_16x16x32_bf16 v[92:95], v[168:171], v[192:195], v[92:95]
	v_mfma_f32_16x16x32_bf16 v[88:91], v[176:179], v[192:195], v[88:91]
	v_mfma_f32_16x16x32_bf16 v[76:79], v[168:171], v[200:203], v[76:79]
	v_mfma_f32_16x16x32_bf16 v[72:75], v[176:179], v[200:203], v[72:75]
	v_mfma_f32_16x16x32_bf16 v[68:71], v[168:171], v[208:211], v[68:71]
	v_mfma_f32_16x16x32_bf16 v[64:67], v[176:179], v[208:211], v[64:67]
	v_mfma_f32_16x16x32_bf16 v[108:111], v[172:175], v[188:191], v[108:111]
	v_mfma_f32_16x16x32_bf16 v[104:107], v[180:183], v[188:191], v[104:107]
	v_mfma_f32_16x16x32_bf16 v[92:95], v[172:175], v[196:199], v[92:95]
	v_mfma_f32_16x16x32_bf16 v[88:91], v[180:183], v[196:199], v[88:91]
	v_mfma_f32_16x16x32_bf16 v[76:79], v[172:175], v[204:207], v[76:79]
	v_mfma_f32_16x16x32_bf16 v[72:75], v[180:183], v[204:207], v[72:75]
	v_mfma_f32_16x16x32_bf16 v[68:71], v[172:175], v[212:215], v[68:71]
	v_mfma_f32_16x16x32_bf16 v[64:67], v[180:183], v[212:215], v[64:67]
	s_setprio 0
	s_barrier
; #define PG8_STAGE(bufoff, gbase, voff) do { _Pragma("unroll") for (int _i = 0; _i < 2; ++_i) \
;         __builtin_amdgcn_global_load_lds((const unsigned*)((const char*)(gbase) + (voff)[_i]), (PG8_LAS unsigned*)(lds + (bufoff) + ldsw + _i * 8192), 16, 0, 0); } while (0)
; #define PG8_LDA(dst, b, h) do { _Pragma("unroll") for (int m = 0; m < 4; ++m) _Pragma("unroll") for (int k = 0; k < 2; ++k) dst[m][k] = *(const PG8_LAS bf16x8*)(lds + PG8_SA(b, h) + aoff + m * 2048 + k * 1024); } while (0)
; #define PG8_MMA(ai, bj, At, Bt) do { __builtin_amdgcn_s_setprio(1); _Pragma("unroll") for (int m = 0; m < 4; ++m) _Pragma("unroll") for (int n = 0; n < 2; ++n) _Pragma("unroll") for (int k = 0; k < 2; ++k) \
;         acc[ai][bj][m][n] = __builtin_amdgcn_mfma_f32_16x16x32_bf16(Bt[n][k], At[m][k], acc[ai][bj][m][n], 0, 0, 0); __builtin_amdgcn_s_setprio(0); } while (0)
; #define PG8_WAIT_V(n) asm volatile("s_waitcnt vmcnt(" #n ")" ::: "memory")
; #define PG8_WAIT_L(n) asm volatile("s_waitcnt lgkmcnt(" #n ")" ::: "memory")
; #define PG8_BAR __builtin_amdgcn_s_barrier()
; #define PG8_SCHED __builtin_amdgcn_sched_barrier(0)
; template <class Epi, class Sched, bool ALIGN_EPI = false, bool SP2 = false>
; __device__ __forceinline__ void gemm_phase(PG8_LAS unsigned char* lds, const Gemm g, const Sched& S, const Epi& E) {
;     ...
;             PG8_LDA(At, 1, 1); PG8_STAGE(PG8_SB(1, 0), b3, voffB); PG8_STAGE(PG8_SB(1, 1), b3 + hstep, voffB); PG8_STAGE(PG8_SA(1, 0), a3, voffA);
;             PG8_WAIT_V(8); PG8_WAIT_L(0); PG8_BAR; PG8_MMA(1, 0, At, B0); PG8_MMA(1, 1, At, B1); PG8_BAR; PG8_SCHED;
;     ...
;         if constexpr (ALIGN_EPI) { if (wr == 0) PG8_BAR; }
	s_add_i32 s58, s86, s60
	v_lshl_add_u64 v[216:217], v[216:217], 0, s[10:11]
	s_mov_b32 m0, s58
	ds_read_b128 v[184:187], v149 offset:49152
	ds_read_b128 v[188:191], v149 offset:50176
	ds_read_b128 v[192:195], v149 offset:51200
	ds_read_b128 v[196:199], v149 offset:52224
	ds_read_b128 v[200:203], v149 offset:53248
	ds_read_b128 v[204:207], v149 offset:54272
	ds_read_b128 v[208:211], v149 offset:55296
	ds_read_b128 v[212:215], v149 offset:56320
	global_load_lds_dwordx4 v[216:217], off
	s_add_i32 m0, s58, 0x2000
	s_add_u32 s56, s56, 0x40080
	v_lshl_add_u64 v[216:217], v[218:219], 0, s[10:11]
	s_addc_u32 s57, s57, 0
	s_add_i32 s58, s87, s60
	global_load_lds_dwordx4 v[216:217], off
	v_lshl_add_u64 v[216:217], s[56:57], 0, v[130:131]
	s_mov_b32 m0, s58
	s_nop 0
	global_load_lds_dwordx4 v[216:217], off
	v_lshl_add_u64 v[216:217], s[56:57], 0, v[134:135]
	s_add_i32 m0, s58, 0x2000
	s_nop 0
	global_load_lds_dwordx4 v[216:217], off
	v_lshl_add_u64 v[216:217], v[220:221], 0, s[10:11]
	s_mov_b32 m0, s70
	s_nop 0
	global_load_lds_dwordx4 v[216:217], off
	v_lshl_add_u64 v[216:217], v[222:223], 0, s[10:11]
	s_mov_b32 m0, s71
	s_nop 0
	global_load_lds_dwordx4 v[216:217], off
	s_waitcnt vmcnt(8)
	s_waitcnt lgkmcnt(0)
	s_barrier
	s_setprio 1
	v_mfma_f32_16x16x32_bf16 v[60:63], v[152:155], v[184:187], v[60:63]
	v_mfma_f32_16x16x32_bf16 v[56:59], v[160:163], v[184:187], v[56:59]
	v_mfma_f32_16x16x32_bf16 v[52:55], v[152:155], v[192:195], v[52:55]
	v_mfma_f32_16x16x32_bf16 v[48:51], v[160:163], v[192:195], v[48:51]
	v_mfma_f32_16x16x32_bf16 v[36:39], v[152:155], v[200:203], v[36:39]
	v_mfma_f32_16x16x32_bf16 v[32:35], v[160:163], v[200:203], v[32:35]
	v_mfma_f32_16x16x32_bf16 v[20:23], v[152:155], v[208:211], v[20:23]
	v_mfma_f32_16x16x32_bf16 v[16:19], v[160:163], v[208:211], v[16:19]
	v_mfma_f32_16x16x32_bf16 v[60:63], v[156:159], v[188:191], v[60:63]
	v_mfma_f32_16x16x32_bf16 v[56:59], v[164:167], v[188:191], v[56:59]
	v_mfma_f32_16x16x32_bf16 v[52:55], v[156:159], v[196:199], v[52:55]
	v_mfma_f32_16x16x32_bf16 v[48:51], v[164:167], v[196:199], v[48:51]
	v_mfma_f32_16x16x32_bf16 v[36:39], v[156:159], v[204:207], v[36:39]
	v_mfma_f32_16x16x32_bf16 v[32:35], v[164:167], v[204:207], v[32:35]
	v_mfma_f32_16x16x32_bf16 v[20:23], v[156:159], v[212:215], v[20:23]
	v_mfma_f32_16x16x32_bf16 v[16:19], v[164:167], v[212:215], v[16:19]
	s_setprio 0
	s_setprio 1
	v_mfma_f32_16x16x32_bf16 v[44:47], v[168:171], v[184:187], v[44:47]
	v_mfma_f32_16x16x32_bf16 v[40:43], v[176:179], v[184:187], v[40:43]
	v_mfma_f32_16x16x32_bf16 v[28:31], v[168:171], v[192:195], v[28:31]
	v_mfma_f32_16x16x32_bf16 v[24:27], v[176:179], v[192:195], v[24:27]
	v_mfma_f32_16x16x32_bf16 v[12:15], v[168:171], v[200:203], v[12:15]
	v_mfma_f32_16x16x32_bf16 v[8:11], v[176:179], v[200:203], v[8:11]
	v_mfma_f32_16x16x32_bf16 v[4:7], v[168:171], v[208:211], v[4:7]
	v_mfma_f32_16x16x32_bf16 v[0:3], v[176:179], v[208:211], v[0:3]
	v_mfma_f32_16x16x32_bf16 v[44:47], v[172:175], v[188:191], v[44:47]
	v_mfma_f32_16x16x32_bf16 v[40:43], v[180:183], v[188:191], v[40:43]
	v_mfma_f32_16x16x32_bf16 v[28:31], v[172:175], v[196:199], v[28:31]
	v_mfma_f32_16x16x32_bf16 v[24:27], v[180:183], v[196:199], v[24:27]
	v_mfma_f32_16x16x32_bf16 v[12:15], v[172:175], v[204:207], v[12:15]
	v_mfma_f32_16x16x32_bf16 v[8:11], v[180:183], v[204:207], v[8:11]
	v_mfma_f32_16x16x32_bf16 v[4:7], v[172:175], v[212:215], v[4:7]
	v_mfma_f32_16x16x32_bf16 v[0:3], v[180:183], v[212:215], v[0:3]
	s_setprio 0
	s_barrier
	s_add_i32 s85, s85, 2
	s_add_u32 s54, s54, 0x100
	s_addc_u32 s55, s55, 0
	s_add_u32 s83, s83, 0x100
	s_addc_u32 s84, s84, 0
	s_cmp_gt_u32 s85, 13
	s_cbranch_scc0 .LBB0_1460
	s_and_b64 vcc, exec, s[12:13]
	s_cbranch_vccz .LBB0_1463
	s_barrier

; #define PG8_STAGE(bufoff, gbase, voff) do { _Pragma("unroll") for (int _i = 0; _i < 2; ++_i) \
;         __builtin_amdgcn_global_load_lds((const unsigned*)((const char*)(gbase) + (voff)[_i]), (PG8_LAS unsigned*)(lds + (bufoff) + ldsw + _i * 8192), 16, 0, 0); } while (0)
; #define PG8_LDA(dst, b, h) do { _Pragma("unroll") for (int m = 0; m < 4; ++m) _Pragma("unroll") for (int k = 0; k < 2; ++k) dst[m][k] = *(const PG8_LAS bf16x8*)(lds + PG8_SA(b, h) + aoff + m * 2048 + k * 1024); } while (0)
; #define PG8_LDB(dst, b, h) do { _Pragma("unroll") for (int n = 0; n < 2; ++n) _Pragma("unroll") for (int k = 0; k < 2; ++k) dst[n][k] = *(const PG8_LAS bf16x8*)(lds + PG8_SB(b, h) + boff + n * 2048 + k * 1024); } while (0)
; #define PG8_WAIT_V(n) asm volatile("s_waitcnt vmcnt(" #n ")" ::: "memory")
; #define PG8_WAIT_L(n) asm volatile("s_waitcnt lgkmcnt(" #n ")" ::: "memory")
; #define PG8_BAR __builtin_amdgcn_s_barrier()
; #define PG8_SCHED __builtin_amdgcn_sched_barrier(0)
; template <class Epi, class Sched, bool ALIGN_EPI = false, bool SP2 = false>
; __device__ __forceinline__ void gemm_phase(PG8_LAS unsigned char* lds, const Gemm g, const Sched& S, const Epi& E) {
;     ...
;         const char* nA = has_next ? (const char*)g.A + (size_t)nxt.pm * tstep : cA; const char* nB = has_next ? (const char*)g.Bt + (size_t)nxt.pn * tstep : cB;
;         for (int t = 0; t < nt; t += 2) {
;             const bool last = (t == nt - 2);
;             const char* a1 = cA + (size_t)(t + 1) * kstep;
;             const char* a2 = last ? nA : cA + (size_t)(t + 2) * kstep; const char* b2 = last ? nB : cB + (size_t)(t + 2) * kstep;
;             const char* a3 = a2 + kstep; const char* b3 = b2 + kstep;
;             if (last && has_next) S.a_ready(nxt);
;             if constexpr (SP2) {
;             PG8_LDB(B0, 0, 0); PG8_LDB(B1, 0, 1); PG8_SCHED; PG8_LDA(At, 0, 0); PG8_STAGE(PG8_SA(1, 1), a1 + hstep, voffA);
;             PG8_WAIT_V(8); PG8_WAIT_L(0); PG8_BAR; PG8_MMA(0, 0, At, B0); PG8_MMA(0, 1, At, B1); PG8_BAR; PG8_SCHED;
;             PG8_LDA(At, 0, 1); PG8_STAGE(PG8_SB(0, 0), b2, voffB); PG8_STAGE(PG8_SB(0, 1), b2 + hstep, voffB); PG8_STAGE(PG8_SA(0, 0), a2, voffA);
;             PG8_WAIT_V(8); PG8_WAIT_L(0); PG8_BAR; PG8_MMA(1, 0, At, B0); PG8_MMA(1, 1, At, B1); PG8_BAR; PG8_SCHED;
.LBB0_1535:
	ds_read_b128 v[146:149], v153
	ds_read_b128 v[156:159], v153 offset:1024
	ds_read_b128 v[160:163], v153 offset:2048
	ds_read_b128 v[164:167], v153 offset:3072
	ds_read_b128 v[168:171], v154
	ds_read_b128 v[172:175], v154 offset:1024
	ds_read_b128 v[176:179], v154 offset:2048
	ds_read_b128 v[180:183], v154 offset:3072
	s_add_u32 s44, s42, 0xfffc0080
	s_addc_u32 s45, s43, -1
	s_cmp_eq_u32 s70, 12
	s_cselect_b32 s47, s23, s45
	s_cselect_b32 s46, s66, s44
	s_cselect_b32 s45, s19, s69
	s_cselect_b32 s44, s67, s68
	v_lshl_add_u64 v[216:217], s[42:43], 0, v[136:137]
	s_add_i32 m0, s41, 0xc000
	ds_read_b128 v[184:187], v155
	ds_read_b128 v[188:191], v155 offset:1024
	ds_read_b128 v[192:195], v155 offset:2048
	ds_read_b128 v[196:199], v155 offset:3072
	ds_read_b128 v[200:203], v155 offset:4096
	ds_read_b128 v[204:207], v155 offset:5120
	ds_read_b128 v[208:211], v155 offset:6144
	ds_read_b128 v[212:215], v155 offset:7168
	global_load_lds_dwordx4 v[216:217], off
	v_lshl_add_u64 v[216:217], s[42:43], 0, v[138:139]
	s_add_i32 m0, s41, 0xe000
	s_nop 0
	global_load_lds_dwordx4 v[216:217], off
	s_waitcnt vmcnt(8)
	s_waitcnt lgkmcnt(0)
	s_barrier
	s_setprio 1
	v_mfma_f32_16x16x32_bf16 v[124:127], v[146:149], v[184:187], v[124:127]
	v_mfma_f32_16x16x32_bf16 v[120:123], v[160:163], v[184:187], v[120:123]
	v_mfma_f32_16x16x32_bf16 v[108:111], v[146:149], v[192:195], v[108:111]
	v_mfma_f32_16x16x32_bf16 v[104:107], v[160:163], v[192:195], v[104:107]
	v_mfma_f32_16x16x32_bf16 v[92:95], v[146:149], v[200:203], v[92:95]
	v_mfma_f32_16x16x32_bf16 v[88:91], v[160:163], v[200:203], v[88:91]
	v_mfma_f32_16x16x32_bf16 v[76:79], v[146:149], v[208:211], v[76:79]
	v_mfma_f32_16x16x32_bf16 v[72:75], v[160:163], v[208:211], v[72:75]
	v_mfma_f32_16x16x32_bf16 v[124:127], v[156:159], v[188:191], v[124:127]
	v_mfma_f32_16x16x32_bf16 v[120:123], v[164:167], v[188:191], v[120:123]
	v_mfma_f32_16x16x32_bf16 v[108:111], v[156:159], v[196:199], v[108:111]
	v_mfma_f32_16x16x32_bf16 v[104:107], v[164:167], v[196:199], v[104:107]
	v_mfma_f32_16x16x32_bf16 v[92:95], v[156:159], v[204:207], v[92:95]
	v_mfma_f32_16x16x32_bf16 v[88:91], v[164:167], v[204:207], v[88:91]
	v_mfma_f32_16x16x32_bf16 v[76:79], v[156:159], v[212:215], v[76:79]
	v_mfma_f32_16x16x32_bf16 v[72:75], v[164:167], v[212:215], v[72:75]
	s_setprio 0
	s_setprio 1
	v_mfma_f32_16x16x32_bf16 v[116:119], v[168:171], v[184:187], v[116:119]
	v_mfma_f32_16x16x32_bf16 v[112:115], v[176:179], v[184:187], v[112:115]
	v_mfma_f32_16x16x32_bf16 v[100:103], v[168:171], v[192:195], v[100:103]
	v_mfma_f32_16x16x32_bf16 v[96:99], v[176:179], v[192:195], v[96:99]
	v_mfma_f32_16x16x32_bf16 v[84:87], v[168:171], v[200:203], v[84:87]
	v_mfma_f32_16x16x32_bf16 v[80:83], v[176:179], v[200:203], v[80:83]
	v_mfma_f32_16x16x32_bf16 v[68:71], v[168:171], v[208:211], v[68:71]
	v_mfma_f32_16x16x32_bf16 v[64:67], v[176:179], v[208:211], v[64:67]
	v_mfma_f32_16x16x32_bf16 v[116:119], v[172:175], v[188:191], v[116:119]
	v_mfma_f32_16x16x32_bf16 v[112:115], v[180:183], v[188:191], v[112:115]
	v_mfma_f32_16x16x32_bf16 v[100:103], v[172:175], v[196:199], v[100:103]
	v_mfma_f32_16x16x32_bf16 v[96:99], v[180:183], v[196:199], v[96:99]
	v_mfma_f32_16x16x32_bf16 v[84:87], v[172:175], v[204:207], v[84:87]
	v_mfma_f32_16x16x32_bf16 v[80:83], v[180:183], v[204:207], v[80:83]
	v_mfma_f32_16x16x32_bf16 v[68:71], v[172:175], v[212:215], v[68:71]
	v_mfma_f32_16x16x32_bf16 v[64:67], v[180:183], v[212:215], v[64:67]
	s_setprio 0
	s_barrier
	s_add_i32 s71, s62, s50
	v_lshl_add_u64 v[216:217], s[44:45], 0, v[130:131]
	s_mov_b32 m0, s71
	ds_read_b128 v[184:187], v155 offset:16384
	ds_read_b128 v[188:191], v155 offset:17408
	ds_read_b128 v[192:195], v155 offset:18432
	ds_read_b128 v[196:199], v155 offset:19456
	ds_read_b128 v[200:203], v155 offset:20480
	ds_read_b128 v[204:207], v155 offset:21504
	ds_read_b128 v[208:211], v155 offset:22528
	ds_read_b128 v[212:215], v155 offset:23552
	global_load_lds_dwordx4 v[216:217], off
	s_add_i32 m0, s71, 0x2000
	s_add_u32 s72, s44, 0x40000
	v_lshl_add_u64 v[218:219], s[44:45], 0, v[134:135]
	s_addc_u32 s73, s45, 0
	s_add_i32 s71, s63, s50
	global_load_lds_dwordx4 v[218:219], off
	v_lshl_add_u64 v[220:221], s[72:73], 0, v[130:131]
	s_mov_b32 m0, s71
	v_lshl_add_u64 v[222:223], s[46:47], 0, v[132:133]
	global_load_lds_dwordx4 v[220:221], off
	v_lshl_add_u64 v[220:221], s[72:73], 0, v[134:135]
	s_add_i32 m0, s71, 0x2000
	s_nop 0
	global_load_lds_dwordx4 v[220:221], off
	v_lshl_add_u64 v[220:221], s[46:47], 0, v[128:129]
	s_mov_b32 m0, s41
	s_nop 0
	global_load_lds_dwordx4 v[220:221], off
	s_mov_b32 m0, s52
	s_nop 0
	global_load_lds_dwordx4 v[222:223], off
	s_waitcnt vmcnt(8)
	s_waitcnt lgkmcnt(0)
	s_barrier
; #define PG8_STAGE(bufoff, gbase, voff) do { _Pragma("unroll") for (int _i = 0; _i < 2; ++_i) \
;         __builtin_amdgcn_global_load_lds((const unsigned*)((const char*)(gbase) + (voff)[_i]), (PG8_LAS unsigned*)(lds + (bufoff) + ldsw + _i * 8192), 16, 0, 0); } while (0)
; #define PG8_LDA(dst, b, h) do { _Pragma("unroll") for (int m = 0; m < 4; ++m) _Pragma("unroll") for (int k = 0; k < 2; ++k) dst[m][k] = *(const PG8_LAS bf16x8*)(lds + PG8_SA(b, h) + aoff + m * 2048 + k * 1024); } while (0)
; #define PG8_LDB(dst, b, h) do { _Pragma("unroll") for (int n = 0; n < 2; ++n) _Pragma("unroll") for (int k = 0; k < 2; ++k) dst[n][k] = *(const PG8_LAS bf16x8*)(lds + PG8_SB(b, h) + boff + n * 2048 + k * 1024); } while (0)
; #define PG8_MMA(ai, bj, At, Bt) do { __builtin_amdgcn_s_setprio(1); _Pragma("unroll") for (int m = 0; m < 4; ++m) _Pragma("unroll") for (int n = 0; n < 2; ++n) _Pragma("unroll") for (int k = 0; k < 2; ++k) \
;         acc[ai][bj][m][n] = __builtin_amdgcn_mfma_f32_16x16x32_bf16(Bt[n][k], At[m][k], acc[ai][bj][m][n], 0, 0, 0); __builtin_amdgcn_s_setprio(0); } while (0)
; #define PG8_WAIT_V(n) asm volatile("s_waitcnt vmcnt(" #n ")" ::: "memory")
; #define PG8_WAIT_L(n) asm volatile("s_waitcnt lgkmcnt(" #n ")" ::: "memory")
; #define PG8_BAR __builtin_amdgcn_s_barrier()
; #define PG8_SCHED __builtin_amdgcn_sched_barrier(0)
; template <class Epi, class Sched, bool ALIGN_EPI = false, bool SP2 = false>
; __device__ __forceinline__ void gemm_phase(PG8_LAS unsigned char* lds, const Gemm g, const Sched& S, const Epi& E) {
;     ...
;             PG8_WAIT_V(8); PG8_WAIT_L(0); PG8_BAR; PG8_MMA(1, 0, At, B0); PG8_MMA(1, 1, At, B1); PG8_BAR; PG8_SCHED;
;             PG8_LDB(B0, 1, 0); PG8_LDB(B1, 1, 1); PG8_SCHED; PG8_LDA(At, 1, 0); PG8_STAGE(PG8_SA(0, 1), a2 + hstep, voffA);
;             PG8_WAIT_V(8); PG8_WAIT_L(0); PG8_BAR; PG8_MMA(0, 0, At, B0); PG8_MMA(0, 1, At, B1); PG8_BAR; PG8_SCHED;
	s_setprio 1
	v_mfma_f32_16x16x32_bf16 v[60:63], v[146:149], v[184:187], v[60:63]
	v_mfma_f32_16x16x32_bf16 v[56:59], v[160:163], v[184:187], v[56:59]
	v_mfma_f32_16x16x32_bf16 v[44:47], v[146:149], v[192:195], v[44:47]
	v_mfma_f32_16x16x32_bf16 v[40:43], v[160:163], v[192:195], v[40:43]
	v_mfma_f32_16x16x32_bf16 v[28:31], v[146:149], v[200:203], v[28:31]
	v_mfma_f32_16x16x32_bf16 v[24:27], v[160:163], v[200:203], v[24:27]
	v_mfma_f32_16x16x32_bf16 v[12:15], v[146:149], v[208:211], v[12:15]
	v_mfma_f32_16x16x32_bf16 v[8:11], v[160:163], v[208:211], v[8:11]
	v_mfma_f32_16x16x32_bf16 v[60:63], v[156:159], v[188:191], v[60:63]
	v_mfma_f32_16x16x32_bf16 v[56:59], v[164:167], v[188:191], v[56:59]
	v_mfma_f32_16x16x32_bf16 v[44:47], v[156:159], v[196:199], v[44:47]
	v_mfma_f32_16x16x32_bf16 v[40:43], v[164:167], v[196:199], v[40:43]
	v_mfma_f32_16x16x32_bf16 v[28:31], v[156:159], v[204:207], v[28:31]
	v_mfma_f32_16x16x32_bf16 v[24:27], v[164:167], v[204:207], v[24:27]
	v_mfma_f32_16x16x32_bf16 v[12:15], v[156:159], v[212:215], v[12:15]
	v_mfma_f32_16x16x32_bf16 v[8:11], v[164:167], v[212:215], v[8:11]
	s_setprio 0
	s_setprio 1
	v_mfma_f32_16x16x32_bf16 v[52:55], v[168:171], v[184:187], v[52:55]
	v_mfma_f32_16x16x32_bf16 v[48:51], v[176:179], v[184:187], v[48:51]
	v_mfma_f32_16x16x32_bf16 v[36:39], v[168:171], v[192:195], v[36:39]
	v_mfma_f32_16x16x32_bf16 v[32:35], v[176:179], v[192:195], v[32:35]
	v_mfma_f32_16x16x32_bf16 v[20:23], v[168:171], v[200:203], v[20:23]
	v_mfma_f32_16x16x32_bf16 v[16:19], v[176:179], v[200:203], v[16:19]
	v_mfma_f32_16x16x32_bf16 v[4:7], v[168:171], v[208:211], v[4:7]
	v_mfma_f32_16x16x32_bf16 v[0:3], v[176:179], v[208:211], v[0:3]
	v_mfma_f32_16x16x32_bf16 v[52:55], v[172:175], v[188:191], v[52:55]
	v_mfma_f32_16x16x32_bf16 v[48:51], v[180:183], v[188:191], v[48:51]
	v_mfma_f32_16x16x32_bf16 v[36:39], v[172:175], v[196:199], v[36:39]
	v_mfma_f32_16x16x32_bf16 v[32:35], v[180:183], v[196:199], v[32:35]
	v_mfma_f32_16x16x32_bf16 v[20:23], v[172:175], v[204:207], v[20:23]
	v_mfma_f32_16x16x32_bf16 v[16:19], v[180:183], v[204:207], v[16:19]
	v_mfma_f32_16x16x32_bf16 v[4:7], v[172:175], v[212:215], v[4:7]
	v_mfma_f32_16x16x32_bf16 v[0:3], v[180:183], v[212:215], v[0:3]
	s_setprio 0
	s_barrier
	s_add_i32 s71, 0, 0x18000
	s_add_i32 s72, 0, 0x1c000
	v_add_u32_e32 v164, s71, v152
	v_add_u32_e32 v180, s72, v152
	ds_read_b128 v[146:149], v164
	ds_read_b128 v[156:159], v164 offset:1024
	ds_read_b128 v[160:163], v164 offset:2048
	ds_read_b128 v[164:167], v164 offset:3072
	ds_read_b128 v[168:171], v180
	ds_read_b128 v[172:175], v180 offset:1024
	ds_read_b128 v[176:179], v180 offset:2048
	ds_read_b128 v[180:183], v180 offset:3072
	s_add_u32 s46, s46, 0x40000
	s_addc_u32 s47, s47, 0
	s_mov_b32 m0, s53
	v_lshl_add_u64 v[224:225], s[46:47], 0, v[128:129]
	ds_read_b128 v[184:187], v155 offset:32768
	ds_read_b128 v[188:191], v155 offset:33792
	ds_read_b128 v[192:195], v155 offset:34816
	ds_read_b128 v[196:199], v155 offset:35840
	ds_read_b128 v[200:203], v155 offset:36864
	ds_read_b128 v[204:207], v155 offset:37888
	ds_read_b128 v[208:211], v155 offset:38912
	ds_read_b128 v[212:215], v155 offset:39936
	global_load_lds_dwordx4 v[224:225], off
	v_lshl_add_u64 v[224:225], s[46:47], 0, v[132:133]
	s_mov_b32 m0, s54
	s_nop 0
	global_load_lds_dwordx4 v[224:225], off
	s_waitcnt vmcnt(8)
	s_waitcnt lgkmcnt(0)
	s_barrier
	s_setprio 1
	v_mfma_f32_16x16x32_bf16 v[124:127], v[146:149], v[184:187], v[124:127]
	v_mfma_f32_16x16x32_bf16 v[120:123], v[160:163], v[184:187], v[120:123]
	v_mfma_f32_16x16x32_bf16 v[108:111], v[146:149], v[192:195], v[108:111]
	v_mfma_f32_16x16x32_bf16 v[104:107], v[160:163], v[192:195], v[104:107]
	v_mfma_f32_16x16x32_bf16 v[92:95], v[146:149], v[200:203], v[92:95]
	v_mfma_f32_16x16x32_bf16 v[88:91], v[160:163], v[200:203], v[88:91]
	v_mfma_f32_16x16x32_bf16 v[76:79], v[146:149], v[208:211], v[76:79]
	v_mfma_f32_16x16x32_bf16 v[72:75], v[160:163], v[208:211], v[72:75]
	v_mfma_f32_16x16x32_bf16 v[124:127], v[156:159], v[188:191], v[124:127]
	v_mfma_f32_16x16x32_bf16 v[120:123], v[164:167], v[188:191], v[120:123]
	v_mfma_f32_16x16x32_bf16 v[108:111], v[156:159], v[196:199], v[108:111]
	v_mfma_f32_16x16x32_bf16 v[104:107], v[164:167], v[196:199], v[104:107]
	v_mfma_f32_16x16x32_bf16 v[92:95], v[156:159], v[204:207], v[92:95]
	v_mfma_f32_16x16x32_bf16 v[88:91], v[164:167], v[204:207], v[88:91]
	v_mfma_f32_16x16x32_bf16 v[76:79], v[156:159], v[212:215], v[76:79]
	v_mfma_f32_16x16x32_bf16 v[72:75], v[164:167], v[212:215], v[72:75]
	s_setprio 0
	s_setprio 1
	v_mfma_f32_16x16x32_bf16 v[116:119], v[168:171], v[184:187], v[116:119]
	v_mfma_f32_16x16x32_bf16 v[112:115], v[176:179], v[184:187], v[112:115]
	v_mfma_f32_16x16x32_bf16 v[100:103], v[168:171], v[192:195], v[100:103]
	v_mfma_f32_16x16x32_bf16 v[96:99], v[176:179], v[192:195], v[96:99]
	v_mfma_f32_16x16x32_bf16 v[84:87], v[168:171], v[200:203], v[84:87]
	v_mfma_f32_16x16x32_bf16 v[80:83], v[176:179], v[200:203], v[80:83]
	v_mfma_f32_16x16x32_bf16 v[68:71], v[168:171], v[208:211], v[68:71]
	v_mfma_f32_16x16x32_bf16 v[64:67], v[176:179], v[208:211], v[64:67]
	v_mfma_f32_16x16x32_bf16 v[116:119], v[172:175], v[188:191], v[116:119]
	v_mfma_f32_16x16x32_bf16 v[112:115], v[180:183], v[188:191], v[112:115]
	v_mfma_f32_16x16x32_bf16 v[100:103], v[172:175], v[196:199], v[100:103]
	v_mfma_f32_16x16x32_bf16 v[96:99], v[180:183], v[196:199], v[96:99]
	v_mfma_f32_16x16x32_bf16 v[84:87], v[172:175], v[204:207], v[84:87]
	v_mfma_f32_16x16x32_bf16 v[80:83], v[180:183], v[204:207], v[80:83]
	v_mfma_f32_16x16x32_bf16 v[68:71], v[172:175], v[212:215], v[68:71]
	v_mfma_f32_16x16x32_bf16 v[64:67], v[180:183], v[212:215], v[64:67]
	s_setprio 0
	s_barrier
; #define PG8_STAGE(bufoff, gbase, voff) do { _Pragma("unroll") for (int _i = 0; _i < 2; ++_i) \
;         __builtin_amdgcn_global_load_lds((const unsigned*)((const char*)(gbase) + (voff)[_i]), (PG8_LAS unsigned*)(lds + (bufoff) + ldsw + _i * 8192), 16, 0, 0); } while (0)
; #define PG8_LDA(dst, b, h) do { _Pragma("unroll") for (int m = 0; m < 4; ++m) _Pragma("unroll") for (int k = 0; k < 2; ++k) dst[m][k] = *(const PG8_LAS bf16x8*)(lds + PG8_SA(b, h) + aoff + m * 2048 + k * 1024); } while (0)
; #define PG8_MMA(ai, bj, At, Bt) do { __builtin_amdgcn_s_setprio(1); _Pragma("unroll") for (int m = 0; m < 4; ++m) _Pragma("unroll") for (int n = 0; n < 2; ++n) _Pragma("unroll") for (int k = 0; k < 2; ++k) \
;         acc[ai][bj][m][n] = __builtin_amdgcn_mfma_f32_16x16x32_bf16(Bt[n][k], At[m][k], acc[ai][bj][m][n], 0, 0, 0); __builtin_amdgcn_s_setprio(0); } while (0)
; #define PG8_WAIT_V(n) asm volatile("s_waitcnt vmcnt(" #n ")" ::: "memory")
; #define PG8_WAIT_L(n) asm volatile("s_waitcnt lgkmcnt(" #n ")" ::: "memory")
; #define PG8_BAR __builtin_amdgcn_s_barrier()
; #define PG8_SCHED __builtin_amdgcn_sched_barrier(0)
; template <class Epi, class Sched, bool ALIGN_EPI = false, bool SP2 = false>
; __device__ __forceinline__ void gemm_phase(PG8_LAS unsigned char* lds, const Gemm g, const Sched& S, const Epi& E) {
;     ...
;             PG8_LDA(At, 1, 1); PG8_STAGE(PG8_SB(1, 0), b3, voffB); PG8_STAGE(PG8_SB(1, 1), b3 + hstep, voffB); PG8_STAGE(PG8_SA(1, 0), a3, voffA);
;             PG8_WAIT_V(8); PG8_WAIT_L(0); PG8_BAR; PG8_MMA(1, 0, At, B0); PG8_MMA(1, 1, At, B1); PG8_BAR; PG8_SCHED;
;     ...
;         if constexpr (ALIGN_EPI) { if (wr == 0) PG8_BAR; }
	s_add_i32 s46, s71, s50
	v_lshl_add_u64 v[216:217], v[216:217], 0, s[12:13]
	s_mov_b32 m0, s46
	ds_read_b128 v[184:187], v155 offset:49152
	ds_read_b128 v[188:191], v155 offset:50176
	ds_read_b128 v[192:195], v155 offset:51200
	ds_read_b128 v[196:199], v155 offset:52224
	ds_read_b128 v[200:203], v155 offset:53248
	ds_read_b128 v[204:207], v155 offset:54272
	ds_read_b128 v[208:211], v155 offset:55296
	ds_read_b128 v[212:215], v155 offset:56320
	global_load_lds_dwordx4 v[216:217], off
	s_add_i32 m0, s46, 0x2000
	s_add_u32 s44, s44, 0x40080
	v_lshl_add_u64 v[216:217], v[218:219], 0, s[12:13]
	s_addc_u32 s45, s45, 0
	s_add_i32 s46, s72, s50
	global_load_lds_dwordx4 v[216:217], off
	v_lshl_add_u64 v[216:217], s[44:45], 0, v[130:131]
	s_mov_b32 m0, s46
	s_nop 0
	global_load_lds_dwordx4 v[216:217], off
	v_lshl_add_u64 v[216:217], s[44:45], 0, v[134:135]
	s_add_i32 m0, s46, 0x2000
	s_nop 0
	global_load_lds_dwordx4 v[216:217], off
	v_lshl_add_u64 v[216:217], v[220:221], 0, s[12:13]
	s_mov_b32 m0, s59
	s_nop 0
	global_load_lds_dwordx4 v[216:217], off
	v_lshl_add_u64 v[216:217], v[222:223], 0, s[12:13]
	s_mov_b32 m0, s60
	s_nop 0
	global_load_lds_dwordx4 v[216:217], off
	s_waitcnt vmcnt(8)
	s_waitcnt lgkmcnt(0)
	s_barrier
	s_setprio 1
	v_mfma_f32_16x16x32_bf16 v[60:63], v[146:149], v[184:187], v[60:63]
	v_mfma_f32_16x16x32_bf16 v[56:59], v[160:163], v[184:187], v[56:59]
	v_mfma_f32_16x16x32_bf16 v[44:47], v[146:149], v[192:195], v[44:47]
	v_mfma_f32_16x16x32_bf16 v[40:43], v[160:163], v[192:195], v[40:43]
	v_mfma_f32_16x16x32_bf16 v[28:31], v[146:149], v[200:203], v[28:31]
	v_mfma_f32_16x16x32_bf16 v[24:27], v[160:163], v[200:203], v[24:27]
	v_mfma_f32_16x16x32_bf16 v[12:15], v[146:149], v[208:211], v[12:15]
	v_mfma_f32_16x16x32_bf16 v[8:11], v[160:163], v[208:211], v[8:11]
	v_mfma_f32_16x16x32_bf16 v[60:63], v[156:159], v[188:191], v[60:63]
	v_mfma_f32_16x16x32_bf16 v[56:59], v[164:167], v[188:191], v[56:59]
	v_mfma_f32_16x16x32_bf16 v[44:47], v[156:159], v[196:199], v[44:47]
	v_mfma_f32_16x16x32_bf16 v[40:43], v[164:167], v[196:199], v[40:43]
	v_mfma_f32_16x16x32_bf16 v[28:31], v[156:159], v[204:207], v[28:31]
	v_mfma_f32_16x16x32_bf16 v[24:27], v[164:167], v[204:207], v[24:27]
	v_mfma_f32_16x16x32_bf16 v[12:15], v[156:159], v[212:215], v[12:15]
	v_mfma_f32_16x16x32_bf16 v[8:11], v[164:167], v[212:215], v[8:11]
	s_setprio 0
	s_setprio 1
	v_mfma_f32_16x16x32_bf16 v[52:55], v[168:171], v[184:187], v[52:55]
	v_mfma_f32_16x16x32_bf16 v[48:51], v[176:179], v[184:187], v[48:51]
	v_mfma_f32_16x16x32_bf16 v[36:39], v[168:171], v[192:195], v[36:39]
	v_mfma_f32_16x16x32_bf16 v[32:35], v[176:179], v[192:195], v[32:35]
	v_mfma_f32_16x16x32_bf16 v[20:23], v[168:171], v[200:203], v[20:23]
	v_mfma_f32_16x16x32_bf16 v[16:19], v[176:179], v[200:203], v[16:19]
	v_mfma_f32_16x16x32_bf16 v[4:7], v[168:171], v[208:211], v[4:7]
	v_mfma_f32_16x16x32_bf16 v[0:3], v[176:179], v[208:211], v[0:3]
	v_mfma_f32_16x16x32_bf16 v[52:55], v[172:175], v[188:191], v[52:55]
	v_mfma_f32_16x16x32_bf16 v[48:51], v[180:183], v[188:191], v[48:51]
	v_mfma_f32_16x16x32_bf16 v[36:39], v[172:175], v[196:199], v[36:39]
	v_mfma_f32_16x16x32_bf16 v[32:35], v[180:183], v[196:199], v[32:35]
	v_mfma_f32_16x16x32_bf16 v[20:23], v[172:175], v[204:207], v[20:23]
	v_mfma_f32_16x16x32_bf16 v[16:19], v[180:183], v[204:207], v[16:19]
	v_mfma_f32_16x16x32_bf16 v[4:7], v[172:175], v[212:215], v[4:7]
	v_mfma_f32_16x16x32_bf16 v[0:3], v[180:183], v[212:215], v[0:3]
	s_setprio 0
	s_barrier
	s_add_i32 s70, s70, 2
	s_add_u32 s42, s42, 0x100
	s_addc_u32 s43, s43, 0
	s_add_u32 s68, s68, 0x100
	s_addc_u32 s69, s69, 0
	s_cmp_gt_u32 s70, 13
	s_cbranch_scc0 .LBB0_1535
	s_and_b64 vcc, exec, s[14:15]
	s_cbranch_vccz .LBB0_1538
	s_barrier

; #define PG8_STAGE(bufoff, gbase, voff) do { _Pragma("unroll") for (int _i = 0; _i < 2; ++_i) \
;         __builtin_amdgcn_global_load_lds((const unsigned*)((const char*)(gbase) + (voff)[_i]), (PG8_LAS unsigned*)(lds + (bufoff) + ldsw + _i * 8192), 16, 0, 0); } while (0)
; #define PG8_LDA(dst, b, h) do { _Pragma("unroll") for (int m = 0; m < 4; ++m) _Pragma("unroll") for (int k = 0; k < 2; ++k) dst[m][k] = *(const PG8_LAS bf16x8*)(lds + PG8_SA(b, h) + aoff + m * 2048 + k * 1024); } while (0)
; #define PG8_LDB(dst, b, h) do { _Pragma("unroll") for (int n = 0; n < 2; ++n) _Pragma("unroll") for (int k = 0; k < 2; ++k) dst[n][k] = *(const PG8_LAS bf16x8*)(lds + PG8_SB(b, h) + boff + n * 2048 + k * 1024); } while (0)
; #define PG8_WAIT_V(n) asm volatile("s_waitcnt vmcnt(" #n ")" ::: "memory")
; #define PG8_WAIT_L(n) asm volatile("s_waitcnt lgkmcnt(" #n ")" ::: "memory")
; #define PG8_BAR __builtin_amdgcn_s_barrier()
; #define PG8_SCHED __builtin_amdgcn_sched_barrier(0)
; template <class Epi, class Sched, bool ALIGN_EPI = false, bool SP2 = false>
; __device__ __forceinline__ void gemm_phase(PG8_LAS unsigned char* lds, const Gemm g, const Sched& S, const Epi& E) {
;     ...
;         const char* nA = has_next ? (const char*)g.A + (size_t)nxt.pm * tstep : cA; const char* nB = has_next ? (const char*)g.Bt + (size_t)nxt.pn * tstep : cB;
;         for (int t = 0; t < nt; t += 2) {
;             const bool last = (t == nt - 2);
;             const char* a1 = cA + (size_t)(t + 1) * kstep;
;             const char* a2 = last ? nA : cA + (size_t)(t + 2) * kstep; const char* b2 = last ? nB : cB + (size_t)(t + 2) * kstep;
;             const char* a3 = a2 + kstep; const char* b3 = b2 + kstep;
;             if (last && has_next) S.a_ready(nxt);
;             if constexpr (SP2) {
;             PG8_LDB(B0, 0, 0); PG8_LDB(B1, 0, 1); PG8_SCHED; PG8_LDA(At, 0, 0); PG8_STAGE(PG8_SA(1, 1), a1 + hstep, voffA);
;             PG8_WAIT_V(8); PG8_WAIT_L(0); PG8_BAR; PG8_MMA(0, 0, At, B0); PG8_MMA(0, 1, At, B1); PG8_BAR; PG8_SCHED;
;             PG8_LDA(At, 0, 1); PG8_STAGE(PG8_SB(0, 0), b2, voffB); PG8_STAGE(PG8_SB(0, 1), b2 + hstep, voffB); PG8_STAGE(PG8_SA(0, 0), a2, voffA);
;             PG8_WAIT_V(8); PG8_WAIT_L(0); PG8_BAR; PG8_MMA(1, 0, At, B0); PG8_MMA(1, 1, At, B1); PG8_BAR; PG8_SCHED;
.LBB0_1612:
	ds_read_b128 v[146:149], v153
	ds_read_b128 v[158:161], v153 offset:1024
	ds_read_b128 v[162:165], v153 offset:2048
	ds_read_b128 v[166:169], v153 offset:3072
	ds_read_b128 v[170:173], v154
	ds_read_b128 v[174:177], v154 offset:1024
	ds_read_b128 v[178:181], v154 offset:2048
	ds_read_b128 v[182:185], v154 offset:3072
	s_add_u32 s44, s42, 0xfff80080
	s_addc_u32 s45, s43, -1
	s_cmp_eq_u32 s69, 28
	s_cselect_b32 s47, s23, s45
	s_cselect_b32 s46, s41, s44
	s_cselect_b32 s45, s19, s68
	s_cselect_b32 s44, s66, s67
	v_lshl_add_u64 v[218:219], s[42:43], 0, v[136:137]
	s_add_i32 m0, s51, 0xc000
	ds_read_b128 v[186:189], v155
	ds_read_b128 v[190:193], v155 offset:1024
	ds_read_b128 v[194:197], v155 offset:2048
	ds_read_b128 v[198:201], v155 offset:3072
	ds_read_b128 v[202:205], v155 offset:4096
	ds_read_b128 v[206:209], v155 offset:5120
	ds_read_b128 v[210:213], v155 offset:6144
	ds_read_b128 v[214:217], v155 offset:7168
	global_load_lds_dwordx4 v[218:219], off
	v_lshl_add_u64 v[218:219], s[42:43], 0, v[138:139]
	s_add_i32 m0, s51, 0xe000
	s_nop 0
	global_load_lds_dwordx4 v[218:219], off
	s_waitcnt vmcnt(8)
	s_waitcnt lgkmcnt(0)
	s_barrier
	s_setprio 1
	v_mfma_f32_16x16x32_bf16 v[124:127], v[146:149], v[186:189], v[124:127]
	v_mfma_f32_16x16x32_bf16 v[120:123], v[162:165], v[186:189], v[120:123]
	v_mfma_f32_16x16x32_bf16 v[108:111], v[146:149], v[194:197], v[108:111]
	v_mfma_f32_16x16x32_bf16 v[104:107], v[162:165], v[194:197], v[104:107]
	v_mfma_f32_16x16x32_bf16 v[92:95], v[146:149], v[202:205], v[92:95]
	v_mfma_f32_16x16x32_bf16 v[88:91], v[162:165], v[202:205], v[88:91]
	v_mfma_f32_16x16x32_bf16 v[76:79], v[146:149], v[210:213], v[76:79]
	v_mfma_f32_16x16x32_bf16 v[72:75], v[162:165], v[210:213], v[72:75]
	v_mfma_f32_16x16x32_bf16 v[124:127], v[158:161], v[190:193], v[124:127]
	v_mfma_f32_16x16x32_bf16 v[120:123], v[166:169], v[190:193], v[120:123]
	v_mfma_f32_16x16x32_bf16 v[108:111], v[158:161], v[198:201], v[108:111]
	v_mfma_f32_16x16x32_bf16 v[104:107], v[166:169], v[198:201], v[104:107]
	v_mfma_f32_16x16x32_bf16 v[92:95], v[158:161], v[206:209], v[92:95]
	v_mfma_f32_16x16x32_bf16 v[88:91], v[166:169], v[206:209], v[88:91]
	v_mfma_f32_16x16x32_bf16 v[76:79], v[158:161], v[214:217], v[76:79]
	v_mfma_f32_16x16x32_bf16 v[72:75], v[166:169], v[214:217], v[72:75]
	s_setprio 0
	s_setprio 1
	v_mfma_f32_16x16x32_bf16 v[116:119], v[170:173], v[186:189], v[116:119]
	v_mfma_f32_16x16x32_bf16 v[112:115], v[178:181], v[186:189], v[112:115]
	v_mfma_f32_16x16x32_bf16 v[100:103], v[170:173], v[194:197], v[100:103]
	v_mfma_f32_16x16x32_bf16 v[96:99], v[178:181], v[194:197], v[96:99]
	v_mfma_f32_16x16x32_bf16 v[84:87], v[170:173], v[202:205], v[84:87]
	v_mfma_f32_16x16x32_bf16 v[80:83], v[178:181], v[202:205], v[80:83]
	v_mfma_f32_16x16x32_bf16 v[68:71], v[170:173], v[210:213], v[68:71]
	v_mfma_f32_16x16x32_bf16 v[64:67], v[178:181], v[210:213], v[64:67]
	v_mfma_f32_16x16x32_bf16 v[116:119], v[174:177], v[190:193], v[116:119]
	v_mfma_f32_16x16x32_bf16 v[112:115], v[182:185], v[190:193], v[112:115]
	v_mfma_f32_16x16x32_bf16 v[100:103], v[174:177], v[198:201], v[100:103]
	v_mfma_f32_16x16x32_bf16 v[96:99], v[182:185], v[198:201], v[96:99]
	v_mfma_f32_16x16x32_bf16 v[84:87], v[174:177], v[206:209], v[84:87]
	v_mfma_f32_16x16x32_bf16 v[80:83], v[182:185], v[206:209], v[80:83]
	v_mfma_f32_16x16x32_bf16 v[68:71], v[174:177], v[214:217], v[68:71]
	v_mfma_f32_16x16x32_bf16 v[64:67], v[182:185], v[214:217], v[64:67]
	s_setprio 0
	s_barrier
	s_add_i32 s70, s63, s50
	v_lshl_add_u64 v[218:219], s[44:45], 0, v[130:131]
	s_mov_b32 m0, s70
	ds_read_b128 v[186:189], v155 offset:16384
	ds_read_b128 v[190:193], v155 offset:17408
	ds_read_b128 v[194:197], v155 offset:18432
	ds_read_b128 v[198:201], v155 offset:19456
	ds_read_b128 v[202:205], v155 offset:20480
	ds_read_b128 v[206:209], v155 offset:21504
	ds_read_b128 v[210:213], v155 offset:22528
	ds_read_b128 v[214:217], v155 offset:23552
	global_load_lds_dwordx4 v[218:219], off
	s_add_i32 m0, s70, 0x2000
	s_add_u32 s70, s44, 0x80000
	v_lshl_add_u64 v[220:221], s[44:45], 0, v[134:135]
	s_addc_u32 s71, s45, 0
	s_add_i32 s72, s64, s50
	global_load_lds_dwordx4 v[220:221], off
	v_lshl_add_u64 v[222:223], s[70:71], 0, v[130:131]
	s_mov_b32 m0, s72
	v_lshl_add_u64 v[224:225], s[46:47], 0, v[132:133]
	global_load_lds_dwordx4 v[222:223], off
	v_lshl_add_u64 v[222:223], s[70:71], 0, v[134:135]
	s_add_i32 m0, s72, 0x2000
	s_nop 0
	global_load_lds_dwordx4 v[222:223], off
	v_lshl_add_u64 v[222:223], s[46:47], 0, v[128:129]
	s_mov_b32 m0, s51
	s_nop 0
	global_load_lds_dwordx4 v[222:223], off
	s_mov_b32 m0, s52
	s_nop 0
	global_load_lds_dwordx4 v[224:225], off
	s_waitcnt vmcnt(8)
	s_waitcnt lgkmcnt(0)
	s_barrier
; #define PG8_STAGE(bufoff, gbase, voff) do { _Pragma("unroll") for (int _i = 0; _i < 2; ++_i) \
;         __builtin_amdgcn_global_load_lds((const unsigned*)((const char*)(gbase) + (voff)[_i]), (PG8_LAS unsigned*)(lds + (bufoff) + ldsw + _i * 8192), 16, 0, 0); } while (0)
; #define PG8_LDA(dst, b, h) do { _Pragma("unroll") for (int m = 0; m < 4; ++m) _Pragma("unroll") for (int k = 0; k < 2; ++k) dst[m][k] = *(const PG8_LAS bf16x8*)(lds + PG8_SA(b, h) + aoff + m * 2048 + k * 1024); } while (0)
; #define PG8_LDB(dst, b, h) do { _Pragma("unroll") for (int n = 0; n < 2; ++n) _Pragma("unroll") for (int k = 0; k < 2; ++k) dst[n][k] = *(const PG8_LAS bf16x8*)(lds + PG8_SB(b, h) + boff + n * 2048 + k * 1024); } while (0)
; #define PG8_MMA(ai, bj, At, Bt) do { __builtin_amdgcn_s_setprio(1); _Pragma("unroll") for (int m = 0; m < 4; ++m) _Pragma("unroll") for (int n = 0; n < 2; ++n) _Pragma("unroll") for (int k = 0; k < 2; ++k) \
;         acc[ai][bj][m][n] = __builtin_amdgcn_mfma_f32_16x16x32_bf16(Bt[n][k], At[m][k], acc[ai][bj][m][n], 0, 0, 0); __builtin_amdgcn_s_setprio(0); } while (0)
; #define PG8_WAIT_V(n) asm volatile("s_waitcnt vmcnt(" #n ")" ::: "memory")
; #define PG8_WAIT_L(n) asm volatile("s_waitcnt lgkmcnt(" #n ")" ::: "memory")
; #define PG8_BAR __builtin_amdgcn_s_barrier()
; #define PG8_SCHED __builtin_amdgcn_sched_barrier(0)
; template <class Epi, class Sched, bool ALIGN_EPI = false, bool SP2 = false>
; __device__ __forceinline__ void gemm_phase(PG8_LAS unsigned char* lds, const Gemm g, const Sched& S, const Epi& E) {
;     ...
;             PG8_WAIT_V(8); PG8_WAIT_L(0); PG8_BAR; PG8_MMA(1, 0, At, B0); PG8_MMA(1, 1, At, B1); PG8_BAR; PG8_SCHED;
;             PG8_LDB(B0, 1, 0); PG8_LDB(B1, 1, 1); PG8_SCHED; PG8_LDA(At, 1, 0); PG8_STAGE(PG8_SA(0, 1), a2 + hstep, voffA);
;             PG8_WAIT_V(8); PG8_WAIT_L(0); PG8_BAR; PG8_MMA(0, 0, At, B0); PG8_MMA(0, 1, At, B1); PG8_BAR; PG8_SCHED;
	s_setprio 1
	v_mfma_f32_16x16x32_bf16 v[60:63], v[146:149], v[186:189], v[60:63]
	v_mfma_f32_16x16x32_bf16 v[56:59], v[162:165], v[186:189], v[56:59]
	v_mfma_f32_16x16x32_bf16 v[44:47], v[146:149], v[194:197], v[44:47]
	v_mfma_f32_16x16x32_bf16 v[40:43], v[162:165], v[194:197], v[40:43]
	v_mfma_f32_16x16x32_bf16 v[28:31], v[146:149], v[202:205], v[28:31]
	v_mfma_f32_16x16x32_bf16 v[24:27], v[162:165], v[202:205], v[24:27]
	v_mfma_f32_16x16x32_bf16 v[12:15], v[146:149], v[210:213], v[12:15]
	v_mfma_f32_16x16x32_bf16 v[8:11], v[162:165], v[210:213], v[8:11]
	v_mfma_f32_16x16x32_bf16 v[60:63], v[158:161], v[190:193], v[60:63]
	v_mfma_f32_16x16x32_bf16 v[56:59], v[166:169], v[190:193], v[56:59]
	v_mfma_f32_16x16x32_bf16 v[44:47], v[158:161], v[198:201], v[44:47]
	v_mfma_f32_16x16x32_bf16 v[40:43], v[166:169], v[198:201], v[40:43]
	v_mfma_f32_16x16x32_bf16 v[28:31], v[158:161], v[206:209], v[28:31]
	v_mfma_f32_16x16x32_bf16 v[24:27], v[166:169], v[206:209], v[24:27]
	v_mfma_f32_16x16x32_bf16 v[12:15], v[158:161], v[214:217], v[12:15]
	v_mfma_f32_16x16x32_bf16 v[8:11], v[166:169], v[214:217], v[8:11]
	s_setprio 0
	s_setprio 1
	v_mfma_f32_16x16x32_bf16 v[52:55], v[170:173], v[186:189], v[52:55]
	v_mfma_f32_16x16x32_bf16 v[48:51], v[178:181], v[186:189], v[48:51]
	v_mfma_f32_16x16x32_bf16 v[36:39], v[170:173], v[194:197], v[36:39]
	v_mfma_f32_16x16x32_bf16 v[32:35], v[178:181], v[194:197], v[32:35]
	v_mfma_f32_16x16x32_bf16 v[20:23], v[170:173], v[202:205], v[20:23]
	v_mfma_f32_16x16x32_bf16 v[16:19], v[178:181], v[202:205], v[16:19]
	v_mfma_f32_16x16x32_bf16 v[4:7], v[170:173], v[210:213], v[4:7]
	v_mfma_f32_16x16x32_bf16 v[0:3], v[178:181], v[210:213], v[0:3]
	v_mfma_f32_16x16x32_bf16 v[52:55], v[174:177], v[190:193], v[52:55]
	v_mfma_f32_16x16x32_bf16 v[48:51], v[182:185], v[190:193], v[48:51]
	v_mfma_f32_16x16x32_bf16 v[36:39], v[174:177], v[198:201], v[36:39]
	v_mfma_f32_16x16x32_bf16 v[32:35], v[182:185], v[198:201], v[32:35]
	v_mfma_f32_16x16x32_bf16 v[20:23], v[174:177], v[206:209], v[20:23]
	v_mfma_f32_16x16x32_bf16 v[16:19], v[182:185], v[206:209], v[16:19]
	v_mfma_f32_16x16x32_bf16 v[4:7], v[174:177], v[214:217], v[4:7]
	v_mfma_f32_16x16x32_bf16 v[0:3], v[182:185], v[214:217], v[0:3]
	s_setprio 0
	s_barrier
	s_add_i32 s70, 0, 0x18000
	v_add_u32_e32 v157, s70, v152
	s_add_i32 s71, 0, 0x1c000
	ds_read_b128 v[146:149], v157
	ds_read_b128 v[158:161], v157 offset:1024
	ds_read_b128 v[162:165], v157 offset:2048
	ds_read_b128 v[166:169], v157 offset:3072
	v_add_u32_e32 v157, s71, v152
	ds_read_b128 v[170:173], v157
	ds_read_b128 v[174:177], v157 offset:1024
	ds_read_b128 v[178:181], v157 offset:2048
	ds_read_b128 v[182:185], v157 offset:3072
	s_add_u32 s46, s46, 0x80000
	s_addc_u32 s47, s47, 0
	s_mov_b32 m0, s53
	v_lshl_add_u64 v[226:227], s[46:47], 0, v[128:129]
	ds_read_b128 v[186:189], v155 offset:32768
	ds_read_b128 v[190:193], v155 offset:33792
	ds_read_b128 v[194:197], v155 offset:34816
	ds_read_b128 v[198:201], v155 offset:35840
	ds_read_b128 v[202:205], v155 offset:36864
	ds_read_b128 v[206:209], v155 offset:37888
	ds_read_b128 v[210:213], v155 offset:38912
	ds_read_b128 v[214:217], v155 offset:39936
	global_load_lds_dwordx4 v[226:227], off
	v_lshl_add_u64 v[226:227], s[46:47], 0, v[132:133]
	s_mov_b32 m0, s54
	s_nop 0
	global_load_lds_dwordx4 v[226:227], off
	s_waitcnt vmcnt(8)
	s_waitcnt lgkmcnt(0)
	s_barrier
	s_setprio 1
	v_mfma_f32_16x16x32_bf16 v[124:127], v[146:149], v[186:189], v[124:127]
	v_mfma_f32_16x16x32_bf16 v[120:123], v[162:165], v[186:189], v[120:123]
	v_mfma_f32_16x16x32_bf16 v[108:111], v[146:149], v[194:197], v[108:111]
	v_mfma_f32_16x16x32_bf16 v[104:107], v[162:165], v[194:197], v[104:107]
	v_mfma_f32_16x16x32_bf16 v[92:95], v[146:149], v[202:205], v[92:95]
	v_mfma_f32_16x16x32_bf16 v[88:91], v[162:165], v[202:205], v[88:91]
	v_mfma_f32_16x16x32_bf16 v[76:79], v[146:149], v[210:213], v[76:79]
	v_mfma_f32_16x16x32_bf16 v[72:75], v[162:165], v[210:213], v[72:75]
	v_mfma_f32_16x16x32_bf16 v[124:127], v[158:161], v[190:193], v[124:127]
	v_mfma_f32_16x16x32_bf16 v[120:123], v[166:169], v[190:193], v[120:123]
	v_mfma_f32_16x16x32_bf16 v[108:111], v[158:161], v[198:201], v[108:111]
	v_mfma_f32_16x16x32_bf16 v[104:107], v[166:169], v[198:201], v[104:107]
	v_mfma_f32_16x16x32_bf16 v[92:95], v[158:161], v[206:209], v[92:95]
	v_mfma_f32_16x16x32_bf16 v[88:91], v[166:169], v[206:209], v[88:91]
	v_mfma_f32_16x16x32_bf16 v[76:79], v[158:161], v[214:217], v[76:79]
	v_mfma_f32_16x16x32_bf16 v[72:75], v[166:169], v[214:217], v[72:75]
	s_setprio 0
	s_setprio 1
	v_mfma_f32_16x16x32_bf16 v[116:119], v[170:173], v[186:189], v[116:119]
	v_mfma_f32_16x16x32_bf16 v[112:115], v[178:181], v[186:189], v[112:115]
	v_mfma_f32_16x16x32_bf16 v[100:103], v[170:173], v[194:197], v[100:103]
	v_mfma_f32_16x16x32_bf16 v[96:99], v[178:181], v[194:197], v[96:99]
	v_mfma_f32_16x16x32_bf16 v[84:87], v[170:173], v[202:205], v[84:87]
	v_mfma_f32_16x16x32_bf16 v[80:83], v[178:181], v[202:205], v[80:83]
	v_mfma_f32_16x16x32_bf16 v[68:71], v[170:173], v[210:213], v[68:71]
	v_mfma_f32_16x16x32_bf16 v[64:67], v[178:181], v[210:213], v[64:67]
	v_mfma_f32_16x16x32_bf16 v[116:119], v[174:177], v[190:193], v[116:119]
	v_mfma_f32_16x16x32_bf16 v[112:115], v[182:185], v[190:193], v[112:115]
	v_mfma_f32_16x16x32_bf16 v[100:103], v[174:177], v[198:201], v[100:103]
	v_mfma_f32_16x16x32_bf16 v[96:99], v[182:185], v[198:201], v[96:99]
	v_mfma_f32_16x16x32_bf16 v[84:87], v[174:177], v[206:209], v[84:87]
	v_mfma_f32_16x16x32_bf16 v[80:83], v[182:185], v[206:209], v[80:83]
	v_mfma_f32_16x16x32_bf16 v[68:71], v[174:177], v[214:217], v[68:71]
	v_mfma_f32_16x16x32_bf16 v[64:67], v[182:185], v[214:217], v[64:67]
	s_setprio 0
	s_barrier
; #define PG8_STAGE(bufoff, gbase, voff) do { _Pragma("unroll") for (int _i = 0; _i < 2; ++_i) \
;         __builtin_amdgcn_global_load_lds((const unsigned*)((const char*)(gbase) + (voff)[_i]), (PG8_LAS unsigned*)(lds + (bufoff) + ldsw + _i * 8192), 16, 0, 0); } while (0)
; #define PG8_LDA(dst, b, h) do { _Pragma("unroll") for (int m = 0; m < 4; ++m) _Pragma("unroll") for (int k = 0; k < 2; ++k) dst[m][k] = *(const PG8_LAS bf16x8*)(lds + PG8_SA(b, h) + aoff + m * 2048 + k * 1024); } while (0)
; #define PG8_MMA(ai, bj, At, Bt) do { __builtin_amdgcn_s_setprio(1); _Pragma("unroll") for (int m = 0; m < 4; ++m) _Pragma("unroll") for (int n = 0; n < 2; ++n) _Pragma("unroll") for (int k = 0; k < 2; ++k) \
;         acc[ai][bj][m][n] = __builtin_amdgcn_mfma_f32_16x16x32_bf16(Bt[n][k], At[m][k], acc[ai][bj][m][n], 0, 0, 0); __builtin_amdgcn_s_setprio(0); } while (0)
; #define PG8_WAIT_V(n) asm volatile("s_waitcnt vmcnt(" #n ")" ::: "memory")
; #define PG8_WAIT_L(n) asm volatile("s_waitcnt lgkmcnt(" #n ")" ::: "memory")
; #define PG8_BAR __builtin_amdgcn_s_barrier()
; #define PG8_SCHED __builtin_amdgcn_sched_barrier(0)
; template <class Epi, class Sched, bool ALIGN_EPI = false, bool SP2 = false>
; __device__ __forceinline__ void gemm_phase(PG8_LAS unsigned char* lds, const Gemm g, const Sched& S, const Epi& E) {
;     ...
;             PG8_LDA(At, 1, 1); PG8_STAGE(PG8_SB(1, 0), b3, voffB); PG8_STAGE(PG8_SB(1, 1), b3 + hstep, voffB); PG8_STAGE(PG8_SA(1, 0), a3, voffA);
;             PG8_WAIT_V(8); PG8_WAIT_L(0); PG8_BAR; PG8_MMA(1, 0, At, B0); PG8_MMA(1, 1, At, B1); PG8_BAR; PG8_SCHED;
;     ...
;         if constexpr (ALIGN_EPI) { if (wr == 0) PG8_BAR; }
	s_add_i32 s46, s70, s50
	v_lshl_add_u64 v[218:219], v[218:219], 0, s[14:15]
	s_mov_b32 m0, s46
	ds_read_b128 v[186:189], v155 offset:49152
	ds_read_b128 v[190:193], v155 offset:50176
	ds_read_b128 v[194:197], v155 offset:51200
	ds_read_b128 v[198:201], v155 offset:52224
	ds_read_b128 v[202:205], v155 offset:53248
	ds_read_b128 v[206:209], v155 offset:54272
	ds_read_b128 v[210:213], v155 offset:55296
	ds_read_b128 v[214:217], v155 offset:56320
	global_load_lds_dwordx4 v[218:219], off
	s_add_i32 m0, s46, 0x2000
	s_add_u32 s44, s44, 0x80080
	v_lshl_add_u64 v[218:219], v[220:221], 0, s[14:15]
	s_addc_u32 s45, s45, 0
	s_add_i32 s46, s71, s50
	global_load_lds_dwordx4 v[218:219], off
	v_lshl_add_u64 v[218:219], s[44:45], 0, v[130:131]
	s_mov_b32 m0, s46
	s_nop 0
	global_load_lds_dwordx4 v[218:219], off
	v_lshl_add_u64 v[218:219], s[44:45], 0, v[134:135]
	s_add_i32 m0, s46, 0x2000
	s_nop 0
	global_load_lds_dwordx4 v[218:219], off
	v_lshl_add_u64 v[218:219], v[222:223], 0, s[14:15]
	s_mov_b32 m0, s60
	s_nop 0
	global_load_lds_dwordx4 v[218:219], off
	v_lshl_add_u64 v[218:219], v[224:225], 0, s[14:15]
	s_mov_b32 m0, s61
	s_nop 0
	global_load_lds_dwordx4 v[218:219], off
	s_waitcnt vmcnt(8)
	s_waitcnt lgkmcnt(0)
	s_barrier
	s_setprio 1
	v_mfma_f32_16x16x32_bf16 v[60:63], v[146:149], v[186:189], v[60:63]
	v_mfma_f32_16x16x32_bf16 v[56:59], v[162:165], v[186:189], v[56:59]
	v_mfma_f32_16x16x32_bf16 v[44:47], v[146:149], v[194:197], v[44:47]
	v_mfma_f32_16x16x32_bf16 v[40:43], v[162:165], v[194:197], v[40:43]
	v_mfma_f32_16x16x32_bf16 v[28:31], v[146:149], v[202:205], v[28:31]
	v_mfma_f32_16x16x32_bf16 v[24:27], v[162:165], v[202:205], v[24:27]
	v_mfma_f32_16x16x32_bf16 v[12:15], v[146:149], v[210:213], v[12:15]
	v_mfma_f32_16x16x32_bf16 v[8:11], v[162:165], v[210:213], v[8:11]
	v_mfma_f32_16x16x32_bf16 v[60:63], v[158:161], v[190:193], v[60:63]
	v_mfma_f32_16x16x32_bf16 v[56:59], v[166:169], v[190:193], v[56:59]
	v_mfma_f32_16x16x32_bf16 v[44:47], v[158:161], v[198:201], v[44:47]
	v_mfma_f32_16x16x32_bf16 v[40:43], v[166:169], v[198:201], v[40:43]
	v_mfma_f32_16x16x32_bf16 v[28:31], v[158:161], v[206:209], v[28:31]
	v_mfma_f32_16x16x32_bf16 v[24:27], v[166:169], v[206:209], v[24:27]
	v_mfma_f32_16x16x32_bf16 v[12:15], v[158:161], v[214:217], v[12:15]
	v_mfma_f32_16x16x32_bf16 v[8:11], v[166:169], v[214:217], v[8:11]
	s_setprio 0
	s_setprio 1
	v_mfma_f32_16x16x32_bf16 v[52:55], v[170:173], v[186:189], v[52:55]
	v_mfma_f32_16x16x32_bf16 v[48:51], v[178:181], v[186:189], v[48:51]
	v_mfma_f32_16x16x32_bf16 v[36:39], v[170:173], v[194:197], v[36:39]
	v_mfma_f32_16x16x32_bf16 v[32:35], v[178:181], v[194:197], v[32:35]
	v_mfma_f32_16x16x32_bf16 v[20:23], v[170:173], v[202:205], v[20:23]
	v_mfma_f32_16x16x32_bf16 v[16:19], v[178:181], v[202:205], v[16:19]
	v_mfma_f32_16x16x32_bf16 v[4:7], v[170:173], v[210:213], v[4:7]
	v_mfma_f32_16x16x32_bf16 v[0:3], v[178:181], v[210:213], v[0:3]
	v_mfma_f32_16x16x32_bf16 v[52:55], v[174:177], v[190:193], v[52:55]
	v_mfma_f32_16x16x32_bf16 v[48:51], v[182:185], v[190:193], v[48:51]
	v_mfma_f32_16x16x32_bf16 v[36:39], v[174:177], v[198:201], v[36:39]
	v_mfma_f32_16x16x32_bf16 v[32:35], v[182:185], v[198:201], v[32:35]
	v_mfma_f32_16x16x32_bf16 v[20:23], v[174:177], v[206:209], v[20:23]
	v_mfma_f32_16x16x32_bf16 v[16:19], v[182:185], v[206:209], v[16:19]
	v_mfma_f32_16x16x32_bf16 v[4:7], v[174:177], v[214:217], v[4:7]
	v_mfma_f32_16x16x32_bf16 v[0:3], v[182:185], v[214:217], v[0:3]
	s_setprio 0
	s_barrier
	s_add_i32 s69, s69, 2
	s_add_u32 s42, s42, 0x100
	s_addc_u32 s43, s43, 0
	s_add_u32 s67, s67, 0x100
	s_addc_u32 s68, s68, 0
	s_cmp_gt_u32 s69, 29
	s_cbranch_scc0 .LBB0_1612
	s_and_b64 vcc, exec, s[16:17]
	s_cbranch_vccz .LBB0_1615
	s_barrier

; #define PG8_STAGE(bufoff, gbase, voff) do { _Pragma("unroll") for (int _i = 0; _i < 2; ++_i) \
;         __builtin_amdgcn_global_load_lds((const unsigned*)((const char*)(gbase) + (voff)[_i]), (PG8_LAS unsigned*)(lds + (bufoff) + ldsw + _i * 8192), 16, 0, 0); } while (0)
; #define PG8_LDA(dst, b, h) do { _Pragma("unroll") for (int m = 0; m < 4; ++m) _Pragma("unroll") for (int k = 0; k < 2; ++k) dst[m][k] = *(const PG8_LAS bf16x8*)(lds + PG8_SA(b, h) + aoff + m * 2048 + k * 1024); } while (0)
; #define PG8_LDB(dst, b, h) do { _Pragma("unroll") for (int n = 0; n < 2; ++n) _Pragma("unroll") for (int k = 0; k < 2; ++k) dst[n][k] = *(const PG8_LAS bf16x8*)(lds + PG8_SB(b, h) + boff + n * 2048 + k * 1024); } while (0)
; #define PG8_WAIT_V(n) asm volatile("s_waitcnt vmcnt(" #n ")" ::: "memory")
; #define PG8_WAIT_L(n) asm volatile("s_waitcnt lgkmcnt(" #n ")" ::: "memory")
; #define PG8_BAR __builtin_amdgcn_s_barrier()
; #define PG8_SCHED __builtin_amdgcn_sched_barrier(0)
; template <class Epi, class Sched, bool ALIGN_EPI = false, bool SP2 = false>
; __device__ __forceinline__ void gemm_phase(PG8_LAS unsigned char* lds, const Gemm g, const Sched& S, const Epi& E) {
;     ...
;         const char* nA = has_next ? (const char*)g.A + (size_t)nxt.pm * tstep : cA; const char* nB = has_next ? (const char*)g.Bt + (size_t)nxt.pn * tstep : cB;
;         for (int t = 0; t < nt; t += 2) {
;             const bool last = (t == nt - 2);
;             const char* a1 = cA + (size_t)(t + 1) * kstep;
;             const char* a2 = last ? nA : cA + (size_t)(t + 2) * kstep; const char* b2 = last ? nB : cB + (size_t)(t + 2) * kstep;
;             const char* a3 = a2 + kstep; const char* b3 = b2 + kstep;
;             if (last && has_next) S.a_ready(nxt);
;             if constexpr (SP2) {
;             PG8_LDB(B0, 0, 0); PG8_LDB(B1, 0, 1); PG8_SCHED; PG8_LDA(At, 0, 0); PG8_STAGE(PG8_SA(1, 1), a1 + hstep, voffA);
;             PG8_WAIT_V(8); PG8_WAIT_L(0); PG8_BAR; PG8_MMA(0, 0, At, B0); PG8_MMA(0, 1, At, B1); PG8_BAR; PG8_SCHED;
;             PG8_LDA(At, 0, 1); PG8_STAGE(PG8_SB(0, 0), b2, voffB); PG8_STAGE(PG8_SB(0, 1), b2 + hstep, voffB); PG8_STAGE(PG8_SA(0, 0), a2, voffA);
;             PG8_WAIT_V(8); PG8_WAIT_L(0); PG8_BAR; PG8_MMA(1, 0, At, B0); PG8_MMA(1, 1, At, B1); PG8_BAR; PG8_SCHED;
.LBB0_1701:
	ds_read_b128 v[128:131], v220
	ds_read_b128 v[132:135], v220 offset:1024
	ds_read_b128 v[136:139], v220 offset:2048
	ds_read_b128 v[140:143], v220 offset:3072
	ds_read_b128 v[164:167], v221
	ds_read_b128 v[168:171], v221 offset:1024
	ds_read_b128 v[172:175], v221 offset:2048
	ds_read_b128 v[176:179], v221 offset:3072
	s_add_u32 s8, s0, 0xfff80080
	s_addc_u32 s9, s1, -1
	s_cmp_eq_u32 s73, 28
	s_cselect_b32 s11, s7, s9
	s_cselect_b32 s10, s12, s8
	s_cselect_b32 s9, s13, s71
	s_cselect_b32 s8, s16, s37
	v_lshl_add_u64 v[212:213], s[0:1], 0, v[156:157]
	s_add_i32 m0, s61, 0xc000
	ds_read_b128 v[180:183], v222
	ds_read_b128 v[184:187], v222 offset:1024
	ds_read_b128 v[188:191], v222 offset:2048
	ds_read_b128 v[192:195], v222 offset:3072
	ds_read_b128 v[196:199], v222 offset:4096
	ds_read_b128 v[200:203], v222 offset:5120
	ds_read_b128 v[204:207], v222 offset:6144
	ds_read_b128 v[208:211], v222 offset:7168
	global_load_lds_dwordx4 v[212:213], off
	v_lshl_add_u64 v[212:213], s[0:1], 0, v[158:159]
	s_add_i32 m0, s61, 0xe000
	s_nop 0
	global_load_lds_dwordx4 v[212:213], off
	s_waitcnt vmcnt(8)
	s_waitcnt lgkmcnt(0)
	s_barrier
	s_setprio 1
	v_mfma_f32_16x16x32_bf16 v[124:127], v[128:131], v[180:183], v[124:127]
	v_mfma_f32_16x16x32_bf16 v[116:119], v[136:139], v[180:183], v[116:119]
	v_mfma_f32_16x16x32_bf16 v[120:123], v[128:131], v[188:191], v[120:123]
	v_mfma_f32_16x16x32_bf16 v[112:115], v[136:139], v[188:191], v[112:115]
	v_mfma_f32_16x16x32_bf16 v[104:107], v[128:131], v[196:199], v[104:107]
	v_mfma_f32_16x16x32_bf16 v[108:111], v[136:139], v[196:199], v[108:111]
	v_mfma_f32_16x16x32_bf16 v[80:83], v[128:131], v[204:207], v[80:83]
	v_mfma_f32_16x16x32_bf16 v[92:95], v[136:139], v[204:207], v[92:95]
	v_mfma_f32_16x16x32_bf16 v[124:127], v[132:135], v[184:187], v[124:127]
	v_mfma_f32_16x16x32_bf16 v[116:119], v[140:143], v[184:187], v[116:119]
	v_mfma_f32_16x16x32_bf16 v[120:123], v[132:135], v[192:195], v[120:123]
	v_mfma_f32_16x16x32_bf16 v[112:115], v[140:143], v[192:195], v[112:115]
	v_mfma_f32_16x16x32_bf16 v[104:107], v[132:135], v[200:203], v[104:107]
	v_mfma_f32_16x16x32_bf16 v[108:111], v[140:143], v[200:203], v[108:111]
	v_mfma_f32_16x16x32_bf16 v[80:83], v[132:135], v[208:211], v[80:83]
	v_mfma_f32_16x16x32_bf16 v[92:95], v[140:143], v[208:211], v[92:95]
	s_setprio 0
	s_setprio 1
	v_mfma_f32_16x16x32_bf16 v[100:103], v[164:167], v[180:183], v[100:103]
	v_mfma_f32_16x16x32_bf16 v[76:79], v[172:175], v[180:183], v[76:79]
	v_mfma_f32_16x16x32_bf16 v[96:99], v[164:167], v[188:191], v[96:99]
	v_mfma_f32_16x16x32_bf16 v[72:75], v[172:175], v[188:191], v[72:75]
	v_mfma_f32_16x16x32_bf16 v[88:91], v[164:167], v[196:199], v[88:91]
	v_mfma_f32_16x16x32_bf16 v[68:71], v[172:175], v[196:199], v[68:71]
	v_mfma_f32_16x16x32_bf16 v[84:87], v[164:167], v[204:207], v[84:87]
	v_mfma_f32_16x16x32_bf16 v[64:67], v[172:175], v[204:207], v[64:67]
	v_mfma_f32_16x16x32_bf16 v[100:103], v[168:171], v[184:187], v[100:103]
	v_mfma_f32_16x16x32_bf16 v[76:79], v[176:179], v[184:187], v[76:79]
	v_mfma_f32_16x16x32_bf16 v[96:99], v[168:171], v[192:195], v[96:99]
	v_mfma_f32_16x16x32_bf16 v[72:75], v[176:179], v[192:195], v[72:75]
	v_mfma_f32_16x16x32_bf16 v[88:91], v[168:171], v[200:203], v[88:91]
	v_mfma_f32_16x16x32_bf16 v[68:71], v[176:179], v[200:203], v[68:71]
	v_mfma_f32_16x16x32_bf16 v[84:87], v[168:171], v[208:211], v[84:87]
	v_mfma_f32_16x16x32_bf16 v[64:67], v[176:179], v[208:211], v[64:67]
	s_setprio 0
	s_barrier
	s_add_i32 s79, s15, s59
	v_lshl_add_u64 v[212:213], s[8:9], 0, v[148:149]
	s_mov_b32 m0, s79
	ds_read_b128 v[180:183], v222 offset:16384
	ds_read_b128 v[184:187], v222 offset:17408
	ds_read_b128 v[188:191], v222 offset:18432
	ds_read_b128 v[192:195], v222 offset:19456
	ds_read_b128 v[196:199], v222 offset:20480
	ds_read_b128 v[200:203], v222 offset:21504
	ds_read_b128 v[204:207], v222 offset:22528
	ds_read_b128 v[208:211], v222 offset:23552
	global_load_lds_dwordx4 v[212:213], off
	s_add_i32 m0, s79, 0x2000
	s_add_u32 vcc_lo, s8, 0x80000
	v_lshl_add_u64 v[214:215], s[8:9], 0, v[152:153]
	s_addc_u32 vcc_hi, s9, 0
	s_add_i32 s79, s87, s59
	global_load_lds_dwordx4 v[214:215], off
	v_lshl_add_u64 v[226:227], vcc, 0, v[148:149]
	s_mov_b32 m0, s79
	v_lshl_add_u64 v[228:229], s[10:11], 0, v[150:151]
	global_load_lds_dwordx4 v[226:227], off
	v_lshl_add_u64 v[226:227], vcc, 0, v[152:153]
	s_add_i32 m0, s79, 0x2000
	s_nop 0
	global_load_lds_dwordx4 v[226:227], off
	v_lshl_add_u64 v[226:227], s[10:11], 0, v[146:147]
	s_mov_b32 m0, s61
	s_nop 0
	global_load_lds_dwordx4 v[226:227], off
	s_mov_b32 m0, s63
	s_nop 0
	global_load_lds_dwordx4 v[228:229], off
	s_waitcnt vmcnt(8)
	s_waitcnt lgkmcnt(0)
	s_barrier
; #define PG8_STAGE(bufoff, gbase, voff) do { _Pragma("unroll") for (int _i = 0; _i < 2; ++_i) \
;         __builtin_amdgcn_global_load_lds((const unsigned*)((const char*)(gbase) + (voff)[_i]), (PG8_LAS unsigned*)(lds + (bufoff) + ldsw + _i * 8192), 16, 0, 0); } while (0)
; #define PG8_LDA(dst, b, h) do { _Pragma("unroll") for (int m = 0; m < 4; ++m) _Pragma("unroll") for (int k = 0; k < 2; ++k) dst[m][k] = *(const PG8_LAS bf16x8*)(lds + PG8_SA(b, h) + aoff + m * 2048 + k * 1024); } while (0)
; #define PG8_LDB(dst, b, h) do { _Pragma("unroll") for (int n = 0; n < 2; ++n) _Pragma("unroll") for (int k = 0; k < 2; ++k) dst[n][k] = *(const PG8_LAS bf16x8*)(lds + PG8_SB(b, h) + boff + n * 2048 + k * 1024); } while (0)
; #define PG8_MMA(ai, bj, At, Bt) do { __builtin_amdgcn_s_setprio(1); _Pragma("unroll") for (int m = 0; m < 4; ++m) _Pragma("unroll") for (int n = 0; n < 2; ++n) _Pragma("unroll") for (int k = 0; k < 2; ++k) \
;         acc[ai][bj][m][n] = __builtin_amdgcn_mfma_f32_16x16x32_bf16(Bt[n][k], At[m][k], acc[ai][bj][m][n], 0, 0, 0); __builtin_amdgcn_s_setprio(0); } while (0)
; #define PG8_WAIT_V(n) asm volatile("s_waitcnt vmcnt(" #n ")" ::: "memory")
; #define PG8_WAIT_L(n) asm volatile("s_waitcnt lgkmcnt(" #n ")" ::: "memory")
; #define PG8_BAR __builtin_amdgcn_s_barrier()
; #define PG8_SCHED __builtin_amdgcn_sched_barrier(0)
; template <class Epi, class Sched, bool ALIGN_EPI = false, bool SP2 = false>
; __device__ __forceinline__ void gemm_phase(PG8_LAS unsigned char* lds, const Gemm g, const Sched& S, const Epi& E) {
;     ...
;             PG8_WAIT_V(8); PG8_WAIT_L(0); PG8_BAR; PG8_MMA(1, 0, At, B0); PG8_MMA(1, 1, At, B1); PG8_BAR; PG8_SCHED;
;             PG8_LDB(B0, 1, 0); PG8_LDB(B1, 1, 1); PG8_SCHED; PG8_LDA(At, 1, 0); PG8_STAGE(PG8_SA(0, 1), a2 + hstep, voffA);
;             PG8_WAIT_V(8); PG8_WAIT_L(0); PG8_BAR; PG8_MMA(0, 0, At, B0); PG8_MMA(0, 1, At, B1); PG8_BAR; PG8_SCHED;
	s_setprio 1
	v_mfma_f32_16x16x32_bf16 v[60:63], v[128:131], v[180:183], v[60:63]
	v_mfma_f32_16x16x32_bf16 v[44:47], v[136:139], v[180:183], v[44:47]
	v_mfma_f32_16x16x32_bf16 v[56:59], v[128:131], v[188:191], v[56:59]
	v_mfma_f32_16x16x32_bf16 v[40:43], v[136:139], v[188:191], v[40:43]
	v_mfma_f32_16x16x32_bf16 v[52:55], v[128:131], v[196:199], v[52:55]
	v_mfma_f32_16x16x32_bf16 v[36:39], v[136:139], v[196:199], v[36:39]
	v_mfma_f32_16x16x32_bf16 v[48:51], v[128:131], v[204:207], v[48:51]
	v_mfma_f32_16x16x32_bf16 v[32:35], v[136:139], v[204:207], v[32:35]
	v_mfma_f32_16x16x32_bf16 v[60:63], v[132:135], v[184:187], v[60:63]
	v_mfma_f32_16x16x32_bf16 v[44:47], v[140:143], v[184:187], v[44:47]
	v_mfma_f32_16x16x32_bf16 v[56:59], v[132:135], v[192:195], v[56:59]
	v_mfma_f32_16x16x32_bf16 v[40:43], v[140:143], v[192:195], v[40:43]
	v_mfma_f32_16x16x32_bf16 v[52:55], v[132:135], v[200:203], v[52:55]
	v_mfma_f32_16x16x32_bf16 v[36:39], v[140:143], v[200:203], v[36:39]
	v_mfma_f32_16x16x32_bf16 v[48:51], v[132:135], v[208:211], v[48:51]
	v_mfma_f32_16x16x32_bf16 v[32:35], v[140:143], v[208:211], v[32:35]
	s_setprio 0
	s_setprio 1
	v_mfma_f32_16x16x32_bf16 v[28:31], v[164:167], v[180:183], v[28:31]
	v_mfma_f32_16x16x32_bf16 v[12:15], v[172:175], v[180:183], v[12:15]
	v_mfma_f32_16x16x32_bf16 v[24:27], v[164:167], v[188:191], v[24:27]
	v_mfma_f32_16x16x32_bf16 v[8:11], v[172:175], v[188:191], v[8:11]
	v_mfma_f32_16x16x32_bf16 v[20:23], v[164:167], v[196:199], v[20:23]
	v_mfma_f32_16x16x32_bf16 v[4:7], v[172:175], v[196:199], v[4:7]
	v_mfma_f32_16x16x32_bf16 v[16:19], v[164:167], v[204:207], v[16:19]
	v_mfma_f32_16x16x32_bf16 v[0:3], v[172:175], v[204:207], v[0:3]
	v_mfma_f32_16x16x32_bf16 v[28:31], v[168:171], v[184:187], v[28:31]
	v_mfma_f32_16x16x32_bf16 v[12:15], v[176:179], v[184:187], v[12:15]
	v_mfma_f32_16x16x32_bf16 v[24:27], v[168:171], v[192:195], v[24:27]
	v_mfma_f32_16x16x32_bf16 v[8:11], v[176:179], v[192:195], v[8:11]
	v_mfma_f32_16x16x32_bf16 v[20:23], v[168:171], v[200:203], v[20:23]
	v_mfma_f32_16x16x32_bf16 v[4:7], v[176:179], v[200:203], v[4:7]
	v_mfma_f32_16x16x32_bf16 v[16:19], v[168:171], v[208:211], v[16:19]
	v_mfma_f32_16x16x32_bf16 v[0:3], v[176:179], v[208:211], v[0:3]
	s_setprio 0
	s_barrier
	s_add_i32 s79, 0, 0x18000
	s_add_i32 vcc_lo, 0, 0x1c000
	v_add_u32_e32 v140, s79, v219
	v_add_u32_e32 v154, vcc_lo, v219
	ds_read_b128 v[128:131], v140
	ds_read_b128 v[132:135], v140 offset:1024
	ds_read_b128 v[136:139], v140 offset:2048
	ds_read_b128 v[140:143], v140 offset:3072
	ds_read_b128 v[164:167], v154
	ds_read_b128 v[168:171], v154 offset:1024
	ds_read_b128 v[172:175], v154 offset:2048
	ds_read_b128 v[176:179], v154 offset:3072
	s_add_u32 s10, s10, 0x80000
	s_addc_u32 s11, s11, 0
	s_mov_b32 m0, s65
	v_lshl_add_u64 v[230:231], s[10:11], 0, v[146:147]
	ds_read_b128 v[180:183], v222 offset:32768
	ds_read_b128 v[184:187], v222 offset:33792
	ds_read_b128 v[188:191], v222 offset:34816
	ds_read_b128 v[192:195], v222 offset:35840
	ds_read_b128 v[196:199], v222 offset:36864
	ds_read_b128 v[200:203], v222 offset:37888
	ds_read_b128 v[204:207], v222 offset:38912
	ds_read_b128 v[208:211], v222 offset:39936
	global_load_lds_dwordx4 v[230:231], off
	v_lshl_add_u64 v[230:231], s[10:11], 0, v[150:151]
	s_mov_b32 m0, s67
	s_nop 0
	global_load_lds_dwordx4 v[230:231], off
	s_waitcnt vmcnt(8)
	s_waitcnt lgkmcnt(0)
	s_barrier
	s_setprio 1
	v_mfma_f32_16x16x32_bf16 v[124:127], v[128:131], v[180:183], v[124:127]
	v_mfma_f32_16x16x32_bf16 v[116:119], v[136:139], v[180:183], v[116:119]
	v_mfma_f32_16x16x32_bf16 v[120:123], v[128:131], v[188:191], v[120:123]
	v_mfma_f32_16x16x32_bf16 v[112:115], v[136:139], v[188:191], v[112:115]
	v_mfma_f32_16x16x32_bf16 v[104:107], v[128:131], v[196:199], v[104:107]
	v_mfma_f32_16x16x32_bf16 v[108:111], v[136:139], v[196:199], v[108:111]
	v_mfma_f32_16x16x32_bf16 v[80:83], v[128:131], v[204:207], v[80:83]
	v_mfma_f32_16x16x32_bf16 v[92:95], v[136:139], v[204:207], v[92:95]
	v_mfma_f32_16x16x32_bf16 v[124:127], v[132:135], v[184:187], v[124:127]
	v_mfma_f32_16x16x32_bf16 v[116:119], v[140:143], v[184:187], v[116:119]
	v_mfma_f32_16x16x32_bf16 v[120:123], v[132:135], v[192:195], v[120:123]
	v_mfma_f32_16x16x32_bf16 v[112:115], v[140:143], v[192:195], v[112:115]
	v_mfma_f32_16x16x32_bf16 v[104:107], v[132:135], v[200:203], v[104:107]
	v_mfma_f32_16x16x32_bf16 v[108:111], v[140:143], v[200:203], v[108:111]
	v_mfma_f32_16x16x32_bf16 v[80:83], v[132:135], v[208:211], v[80:83]
	v_mfma_f32_16x16x32_bf16 v[92:95], v[140:143], v[208:211], v[92:95]
	s_setprio 0
	s_setprio 1
	v_mfma_f32_16x16x32_bf16 v[100:103], v[164:167], v[180:183], v[100:103]
	v_mfma_f32_16x16x32_bf16 v[76:79], v[172:175], v[180:183], v[76:79]
	v_mfma_f32_16x16x32_bf16 v[96:99], v[164:167], v[188:191], v[96:99]
	v_mfma_f32_16x16x32_bf16 v[72:75], v[172:175], v[188:191], v[72:75]
	v_mfma_f32_16x16x32_bf16 v[88:91], v[164:167], v[196:199], v[88:91]
	v_mfma_f32_16x16x32_bf16 v[68:71], v[172:175], v[196:199], v[68:71]
	v_mfma_f32_16x16x32_bf16 v[84:87], v[164:167], v[204:207], v[84:87]
	v_mfma_f32_16x16x32_bf16 v[64:67], v[172:175], v[204:207], v[64:67]
	v_mfma_f32_16x16x32_bf16 v[100:103], v[168:171], v[184:187], v[100:103]
	v_mfma_f32_16x16x32_bf16 v[76:79], v[176:179], v[184:187], v[76:79]
	v_mfma_f32_16x16x32_bf16 v[96:99], v[168:171], v[192:195], v[96:99]
	v_mfma_f32_16x16x32_bf16 v[72:75], v[176:179], v[192:195], v[72:75]
	v_mfma_f32_16x16x32_bf16 v[88:91], v[168:171], v[200:203], v[88:91]
	v_mfma_f32_16x16x32_bf16 v[68:71], v[176:179], v[200:203], v[68:71]
	v_mfma_f32_16x16x32_bf16 v[84:87], v[168:171], v[208:211], v[84:87]
	v_mfma_f32_16x16x32_bf16 v[64:67], v[176:179], v[208:211], v[64:67]
	s_setprio 0
	s_barrier
; #define PG8_STAGE(bufoff, gbase, voff) do { _Pragma("unroll") for (int _i = 0; _i < 2; ++_i) \
;         __builtin_amdgcn_global_load_lds((const unsigned*)((const char*)(gbase) + (voff)[_i]), (PG8_LAS unsigned*)(lds + (bufoff) + ldsw + _i * 8192), 16, 0, 0); } while (0)
; #define PG8_LDA(dst, b, h) do { _Pragma("unroll") for (int m = 0; m < 4; ++m) _Pragma("unroll") for (int k = 0; k < 2; ++k) dst[m][k] = *(const PG8_LAS bf16x8*)(lds + PG8_SA(b, h) + aoff + m * 2048 + k * 1024); } while (0)
; #define PG8_MMA(ai, bj, At, Bt) do { __builtin_amdgcn_s_setprio(1); _Pragma("unroll") for (int m = 0; m < 4; ++m) _Pragma("unroll") for (int n = 0; n < 2; ++n) _Pragma("unroll") for (int k = 0; k < 2; ++k) \
;         acc[ai][bj][m][n] = __builtin_amdgcn_mfma_f32_16x16x32_bf16(Bt[n][k], At[m][k], acc[ai][bj][m][n], 0, 0, 0); __builtin_amdgcn_s_setprio(0); } while (0)
; #define PG8_WAIT_V(n) asm volatile("s_waitcnt vmcnt(" #n ")" ::: "memory")
; #define PG8_WAIT_L(n) asm volatile("s_waitcnt lgkmcnt(" #n ")" ::: "memory")
; #define PG8_BAR __builtin_amdgcn_s_barrier()
; #define PG8_SCHED __builtin_amdgcn_sched_barrier(0)
; template <class Epi, class Sched, bool ALIGN_EPI = false, bool SP2 = false>
; __device__ __forceinline__ void gemm_phase(PG8_LAS unsigned char* lds, const Gemm g, const Sched& S, const Epi& E) {
;     ...
;             PG8_LDA(At, 1, 1); PG8_STAGE(PG8_SB(1, 0), b3, voffB); PG8_STAGE(PG8_SB(1, 1), b3 + hstep, voffB); PG8_STAGE(PG8_SA(1, 0), a3, voffA);
;             PG8_WAIT_V(8); PG8_WAIT_L(0); PG8_BAR; PG8_MMA(1, 0, At, B0); PG8_MMA(1, 1, At, B1); PG8_BAR; PG8_SCHED;
;     ...
;         if constexpr (ALIGN_EPI) { if (wr == 0) PG8_BAR; }
	s_add_i32 s10, s79, s59
	v_lshl_add_u64 v[212:213], v[212:213], 0, s[46:47]
	s_mov_b32 m0, s10
	ds_read_b128 v[180:183], v222 offset:49152
	ds_read_b128 v[184:187], v222 offset:50176
	ds_read_b128 v[188:191], v222 offset:51200
	ds_read_b128 v[192:195], v222 offset:52224
	ds_read_b128 v[196:199], v222 offset:53248
	ds_read_b128 v[200:203], v222 offset:54272
	ds_read_b128 v[204:207], v222 offset:55296
	ds_read_b128 v[208:211], v222 offset:56320
	global_load_lds_dwordx4 v[212:213], off
	s_add_i32 m0, s10, 0x2000
	s_add_u32 s8, s8, 0x80080
	v_lshl_add_u64 v[212:213], v[214:215], 0, s[46:47]
	s_addc_u32 s9, s9, 0
	s_add_i32 s10, vcc_lo, s59
	global_load_lds_dwordx4 v[212:213], off
	v_lshl_add_u64 v[212:213], s[8:9], 0, v[148:149]
	s_mov_b32 m0, s10
	s_nop 0
	global_load_lds_dwordx4 v[212:213], off
	v_lshl_add_u64 v[212:213], s[8:9], 0, v[152:153]
	s_add_i32 m0, s10, 0x2000
	s_nop 0
	global_load_lds_dwordx4 v[212:213], off
	v_lshl_add_u64 v[212:213], v[226:227], 0, s[46:47]
	s_mov_b32 m0, s84
	s_nop 0
	global_load_lds_dwordx4 v[212:213], off
	v_lshl_add_u64 v[212:213], v[228:229], 0, s[46:47]
	s_mov_b32 m0, s85
	s_nop 0
	global_load_lds_dwordx4 v[212:213], off
	s_waitcnt vmcnt(8)
	s_waitcnt lgkmcnt(0)
	s_barrier
	s_setprio 1
	v_mfma_f32_16x16x32_bf16 v[60:63], v[128:131], v[180:183], v[60:63]
	v_mfma_f32_16x16x32_bf16 v[44:47], v[136:139], v[180:183], v[44:47]
	v_mfma_f32_16x16x32_bf16 v[56:59], v[128:131], v[188:191], v[56:59]
	v_mfma_f32_16x16x32_bf16 v[40:43], v[136:139], v[188:191], v[40:43]
	v_mfma_f32_16x16x32_bf16 v[52:55], v[128:131], v[196:199], v[52:55]
	v_mfma_f32_16x16x32_bf16 v[36:39], v[136:139], v[196:199], v[36:39]
	v_mfma_f32_16x16x32_bf16 v[48:51], v[128:131], v[204:207], v[48:51]
	v_mfma_f32_16x16x32_bf16 v[32:35], v[136:139], v[204:207], v[32:35]
	v_mfma_f32_16x16x32_bf16 v[60:63], v[132:135], v[184:187], v[60:63]
	v_mfma_f32_16x16x32_bf16 v[44:47], v[140:143], v[184:187], v[44:47]
	v_mfma_f32_16x16x32_bf16 v[56:59], v[132:135], v[192:195], v[56:59]
	v_mfma_f32_16x16x32_bf16 v[40:43], v[140:143], v[192:195], v[40:43]
	v_mfma_f32_16x16x32_bf16 v[52:55], v[132:135], v[200:203], v[52:55]
	v_mfma_f32_16x16x32_bf16 v[36:39], v[140:143], v[200:203], v[36:39]
	v_mfma_f32_16x16x32_bf16 v[48:51], v[132:135], v[208:211], v[48:51]
	v_mfma_f32_16x16x32_bf16 v[32:35], v[140:143], v[208:211], v[32:35]
	s_setprio 0
	s_setprio 1
	v_mfma_f32_16x16x32_bf16 v[28:31], v[164:167], v[180:183], v[28:31]
	v_mfma_f32_16x16x32_bf16 v[12:15], v[172:175], v[180:183], v[12:15]
	v_mfma_f32_16x16x32_bf16 v[24:27], v[164:167], v[188:191], v[24:27]
	v_mfma_f32_16x16x32_bf16 v[8:11], v[172:175], v[188:191], v[8:11]
	v_mfma_f32_16x16x32_bf16 v[20:23], v[164:167], v[196:199], v[20:23]
	v_mfma_f32_16x16x32_bf16 v[4:7], v[172:175], v[196:199], v[4:7]
	v_mfma_f32_16x16x32_bf16 v[16:19], v[164:167], v[204:207], v[16:19]
	v_mfma_f32_16x16x32_bf16 v[0:3], v[172:175], v[204:207], v[0:3]
	v_mfma_f32_16x16x32_bf16 v[28:31], v[168:171], v[184:187], v[28:31]
	v_mfma_f32_16x16x32_bf16 v[12:15], v[176:179], v[184:187], v[12:15]
	v_mfma_f32_16x16x32_bf16 v[24:27], v[168:171], v[192:195], v[24:27]
	v_mfma_f32_16x16x32_bf16 v[8:11], v[176:179], v[192:195], v[8:11]
	v_mfma_f32_16x16x32_bf16 v[20:23], v[168:171], v[200:203], v[20:23]
	v_mfma_f32_16x16x32_bf16 v[4:7], v[176:179], v[200:203], v[4:7]
	v_mfma_f32_16x16x32_bf16 v[16:19], v[168:171], v[208:211], v[16:19]
	v_mfma_f32_16x16x32_bf16 v[0:3], v[176:179], v[208:211], v[0:3]
	s_setprio 0
	s_barrier
	s_add_i32 s73, s73, 2
	s_add_u32 s0, s0, 0x100
	s_addc_u32 s1, s1, 0
	s_add_u32 s37, s37, 0x100
	s_addc_u32 s71, s71, 0
	s_cmp_gt_u32 s73, 29
	s_cbranch_scc0 .LBB0_1701
	v_readlane_b32 s0, v244, 56
	v_readlane_b32 s1, v244, 57
	s_and_b64 vcc, exec, s[0:1]
	s_cbranch_vccz .LBB0_1704
	s_barrier

; #define PG8_STAGE(bufoff, gbase, voff) do { _Pragma("unroll") for (int _i = 0; _i < 2; ++_i) \
;         __builtin_amdgcn_global_load_lds((const unsigned*)((const char*)(gbase) + (voff)[_i]), (PG8_LAS unsigned*)(lds + (bufoff) + ldsw + _i * 8192), 16, 0, 0); } while (0)
; #define PG8_LDA(dst, b, h) do { _Pragma("unroll") for (int m = 0; m < 4; ++m) _Pragma("unroll") for (int k = 0; k < 2; ++k) dst[m][k] = *(const PG8_LAS bf16x8*)(lds + PG8_SA(b, h) + aoff + m * 2048 + k * 1024); } while (0)
; #define PG8_LDB(dst, b, h) do { _Pragma("unroll") for (int n = 0; n < 2; ++n) _Pragma("unroll") for (int k = 0; k < 2; ++k) dst[n][k] = *(const PG8_LAS bf16x8*)(lds + PG8_SB(b, h) + boff + n * 2048 + k * 1024); } while (0)
; #define PG8_WAIT_V(n) asm volatile("s_waitcnt vmcnt(" #n ")" ::: "memory")
; #define PG8_WAIT_L(n) asm volatile("s_waitcnt lgkmcnt(" #n ")" ::: "memory")
; #define PG8_BAR __builtin_amdgcn_s_barrier()
; #define PG8_SCHED __builtin_amdgcn_sched_barrier(0)
; template <class Epi, class Sched, bool ALIGN_EPI = false, bool SP2 = false>
; __device__ __forceinline__ void gemm_phase(PG8_LAS unsigned char* lds, const Gemm g, const Sched& S, const Epi& E) {
;     ...
;         const char* nA = has_next ? (const char*)g.A + (size_t)nxt.pm * tstep : cA; const char* nB = has_next ? (const char*)g.Bt + (size_t)nxt.pn * tstep : cB;
;         for (int t = 0; t < nt; t += 2) {
;             const bool last = (t == nt - 2);
;             const char* a1 = cA + (size_t)(t + 1) * kstep;
;             const char* a2 = last ? nA : cA + (size_t)(t + 2) * kstep; const char* b2 = last ? nB : cB + (size_t)(t + 2) * kstep;
;             const char* a3 = a2 + kstep; const char* b3 = b2 + kstep;
;             if (last && has_next) S.a_ready(nxt);
;             if constexpr (SP2) {
;             PG8_LDB(B0, 0, 0); PG8_LDB(B1, 0, 1); PG8_SCHED; PG8_LDA(At, 0, 0); PG8_STAGE(PG8_SA(1, 1), a1 + hstep, voffA);
;             PG8_WAIT_V(8); PG8_WAIT_L(0); PG8_BAR; PG8_MMA(0, 0, At, B0); PG8_MMA(0, 1, At, B1); PG8_BAR; PG8_SCHED;
;             PG8_LDA(At, 0, 1); PG8_STAGE(PG8_SB(0, 0), b2, voffB); PG8_STAGE(PG8_SB(0, 1), b2 + hstep, voffB); PG8_STAGE(PG8_SA(0, 0), a2, voffA);
;             PG8_WAIT_V(8); PG8_WAIT_L(0); PG8_BAR; PG8_MMA(1, 0, At, B0); PG8_MMA(1, 1, At, B1); PG8_BAR; PG8_SCHED;
.LBB0_1924:
	ds_read_b128 v[146:149], v153
	ds_read_b128 v[158:161], v153 offset:1024
	ds_read_b128 v[162:165], v153 offset:2048
	ds_read_b128 v[166:169], v153 offset:3072
	ds_read_b128 v[170:173], v154
	ds_read_b128 v[174:177], v154 offset:1024
	ds_read_b128 v[178:181], v154 offset:2048
	ds_read_b128 v[182:185], v154 offset:3072
	s_add_u32 s36, s22, 0xffea0080
	s_addc_u32 s37, s23, -1
	s_cmpk_eq_i32 s63, 0x54
	s_cselect_b32 s39, s5, s37
	s_cselect_b32 s38, s4, s36
	s_cselect_b32 s37, s21, s62
	s_cselect_b32 s36, s20, s61
	v_lshl_add_u64 v[218:219], s[22:23], 0, v[136:137]
	s_add_i32 m0, s43, 0xc000
	ds_read_b128 v[186:189], v155
	ds_read_b128 v[190:193], v155 offset:1024
	ds_read_b128 v[194:197], v155 offset:2048
	ds_read_b128 v[198:201], v155 offset:3072
	ds_read_b128 v[202:205], v155 offset:4096
	ds_read_b128 v[206:209], v155 offset:5120
	ds_read_b128 v[210:213], v155 offset:6144
	ds_read_b128 v[214:217], v155 offset:7168
	global_load_lds_dwordx4 v[218:219], off
	v_lshl_add_u64 v[218:219], s[22:23], 0, v[138:139]
	s_add_i32 m0, s43, 0xe000
	s_nop 0
	global_load_lds_dwordx4 v[218:219], off
	s_waitcnt vmcnt(8)
	s_waitcnt lgkmcnt(0)
	s_barrier
	s_setprio 1
	v_mfma_f32_16x16x32_bf16 v[124:127], v[146:149], v[186:189], v[124:127]
	v_mfma_f32_16x16x32_bf16 v[120:123], v[162:165], v[186:189], v[120:123]
	v_mfma_f32_16x16x32_bf16 v[108:111], v[146:149], v[194:197], v[108:111]
	v_mfma_f32_16x16x32_bf16 v[104:107], v[162:165], v[194:197], v[104:107]
	v_mfma_f32_16x16x32_bf16 v[92:95], v[146:149], v[202:205], v[92:95]
	v_mfma_f32_16x16x32_bf16 v[88:91], v[162:165], v[202:205], v[88:91]
	v_mfma_f32_16x16x32_bf16 v[76:79], v[146:149], v[210:213], v[76:79]
	v_mfma_f32_16x16x32_bf16 v[72:75], v[162:165], v[210:213], v[72:75]
	v_mfma_f32_16x16x32_bf16 v[124:127], v[158:161], v[190:193], v[124:127]
	v_mfma_f32_16x16x32_bf16 v[120:123], v[166:169], v[190:193], v[120:123]
	v_mfma_f32_16x16x32_bf16 v[108:111], v[158:161], v[198:201], v[108:111]
	v_mfma_f32_16x16x32_bf16 v[104:107], v[166:169], v[198:201], v[104:107]
	v_mfma_f32_16x16x32_bf16 v[92:95], v[158:161], v[206:209], v[92:95]
	v_mfma_f32_16x16x32_bf16 v[88:91], v[166:169], v[206:209], v[88:91]
	v_mfma_f32_16x16x32_bf16 v[76:79], v[158:161], v[214:217], v[76:79]
	v_mfma_f32_16x16x32_bf16 v[72:75], v[166:169], v[214:217], v[72:75]
	s_setprio 0
	s_setprio 1
	v_mfma_f32_16x16x32_bf16 v[116:119], v[170:173], v[186:189], v[116:119]
	v_mfma_f32_16x16x32_bf16 v[112:115], v[178:181], v[186:189], v[112:115]
	v_mfma_f32_16x16x32_bf16 v[100:103], v[170:173], v[194:197], v[100:103]
	v_mfma_f32_16x16x32_bf16 v[96:99], v[178:181], v[194:197], v[96:99]
	v_mfma_f32_16x16x32_bf16 v[84:87], v[170:173], v[202:205], v[84:87]
	v_mfma_f32_16x16x32_bf16 v[80:83], v[178:181], v[202:205], v[80:83]
	v_mfma_f32_16x16x32_bf16 v[68:71], v[170:173], v[210:213], v[68:71]
	v_mfma_f32_16x16x32_bf16 v[64:67], v[178:181], v[210:213], v[64:67]
	v_mfma_f32_16x16x32_bf16 v[116:119], v[174:177], v[190:193], v[116:119]
	v_mfma_f32_16x16x32_bf16 v[112:115], v[182:185], v[190:193], v[112:115]
	v_mfma_f32_16x16x32_bf16 v[100:103], v[174:177], v[198:201], v[100:103]
	v_mfma_f32_16x16x32_bf16 v[96:99], v[182:185], v[198:201], v[96:99]
	v_mfma_f32_16x16x32_bf16 v[84:87], v[174:177], v[206:209], v[84:87]
	v_mfma_f32_16x16x32_bf16 v[80:83], v[182:185], v[206:209], v[80:83]
	v_mfma_f32_16x16x32_bf16 v[68:71], v[174:177], v[214:217], v[68:71]
	v_mfma_f32_16x16x32_bf16 v[64:67], v[182:185], v[214:217], v[64:67]
	s_setprio 0
	s_barrier
	s_add_i32 s64, s55, s42
	v_lshl_add_u64 v[218:219], s[36:37], 0, v[130:131]
	s_mov_b32 m0, s64
	ds_read_b128 v[186:189], v155 offset:16384
	ds_read_b128 v[190:193], v155 offset:17408
	ds_read_b128 v[194:197], v155 offset:18432
	ds_read_b128 v[198:201], v155 offset:19456
	ds_read_b128 v[202:205], v155 offset:20480
	ds_read_b128 v[206:209], v155 offset:21504
	ds_read_b128 v[210:213], v155 offset:22528
	ds_read_b128 v[214:217], v155 offset:23552
	global_load_lds_dwordx4 v[218:219], off
	s_add_i32 m0, s64, 0x2000
	s_add_u32 s64, s36, 0x160000
	v_lshl_add_u64 v[220:221], s[36:37], 0, v[134:135]
	s_addc_u32 s65, s37, 0
	s_add_i32 s66, s56, s42
	global_load_lds_dwordx4 v[220:221], off
	v_lshl_add_u64 v[222:223], s[64:65], 0, v[130:131]
	s_mov_b32 m0, s66
	v_lshl_add_u64 v[224:225], s[38:39], 0, v[132:133]
	global_load_lds_dwordx4 v[222:223], off
	v_lshl_add_u64 v[222:223], s[64:65], 0, v[134:135]
	s_add_i32 m0, s66, 0x2000
	s_nop 0
	global_load_lds_dwordx4 v[222:223], off
	v_lshl_add_u64 v[222:223], s[38:39], 0, v[128:129]
	s_mov_b32 m0, s43
	s_nop 0
	global_load_lds_dwordx4 v[222:223], off
	s_mov_b32 m0, s44
	s_nop 0
	global_load_lds_dwordx4 v[224:225], off
	s_waitcnt vmcnt(8)
	s_waitcnt lgkmcnt(0)
	s_barrier
; #define PG8_STAGE(bufoff, gbase, voff) do { _Pragma("unroll") for (int _i = 0; _i < 2; ++_i) \
;         __builtin_amdgcn_global_load_lds((const unsigned*)((const char*)(gbase) + (voff)[_i]), (PG8_LAS unsigned*)(lds + (bufoff) + ldsw + _i * 8192), 16, 0, 0); } while (0)
; #define PG8_LDA(dst, b, h) do { _Pragma("unroll") for (int m = 0; m < 4; ++m) _Pragma("unroll") for (int k = 0; k < 2; ++k) dst[m][k] = *(const PG8_LAS bf16x8*)(lds + PG8_SA(b, h) + aoff + m * 2048 + k * 1024); } while (0)
; #define PG8_LDB(dst, b, h) do { _Pragma("unroll") for (int n = 0; n < 2; ++n) _Pragma("unroll") for (int k = 0; k < 2; ++k) dst[n][k] = *(const PG8_LAS bf16x8*)(lds + PG8_SB(b, h) + boff + n * 2048 + k * 1024); } while (0)
; #define PG8_MMA(ai, bj, At, Bt) do { __builtin_amdgcn_s_setprio(1); _Pragma("unroll") for (int m = 0; m < 4; ++m) _Pragma("unroll") for (int n = 0; n < 2; ++n) _Pragma("unroll") for (int k = 0; k < 2; ++k) \
;         acc[ai][bj][m][n] = __builtin_amdgcn_mfma_f32_16x16x32_bf16(Bt[n][k], At[m][k], acc[ai][bj][m][n], 0, 0, 0); __builtin_amdgcn_s_setprio(0); } while (0)
; #define PG8_WAIT_V(n) asm volatile("s_waitcnt vmcnt(" #n ")" ::: "memory")
; #define PG8_WAIT_L(n) asm volatile("s_waitcnt lgkmcnt(" #n ")" ::: "memory")
; #define PG8_BAR __builtin_amdgcn_s_barrier()
; #define PG8_SCHED __builtin_amdgcn_sched_barrier(0)
; template <class Epi, class Sched, bool ALIGN_EPI = false, bool SP2 = false>
; __device__ __forceinline__ void gemm_phase(PG8_LAS unsigned char* lds, const Gemm g, const Sched& S, const Epi& E) {
;     ...
;             PG8_WAIT_V(8); PG8_WAIT_L(0); PG8_BAR; PG8_MMA(1, 0, At, B0); PG8_MMA(1, 1, At, B1); PG8_BAR; PG8_SCHED;
;             PG8_LDB(B0, 1, 0); PG8_LDB(B1, 1, 1); PG8_SCHED; PG8_LDA(At, 1, 0); PG8_STAGE(PG8_SA(0, 1), a2 + hstep, voffA);
;             PG8_WAIT_V(8); PG8_WAIT_L(0); PG8_BAR; PG8_MMA(0, 0, At, B0); PG8_MMA(0, 1, At, B1); PG8_BAR; PG8_SCHED;
	s_setprio 1
	v_mfma_f32_16x16x32_bf16 v[60:63], v[146:149], v[186:189], v[60:63]
	v_mfma_f32_16x16x32_bf16 v[56:59], v[162:165], v[186:189], v[56:59]
	v_mfma_f32_16x16x32_bf16 v[44:47], v[146:149], v[194:197], v[44:47]
	v_mfma_f32_16x16x32_bf16 v[40:43], v[162:165], v[194:197], v[40:43]
	v_mfma_f32_16x16x32_bf16 v[28:31], v[146:149], v[202:205], v[28:31]
	v_mfma_f32_16x16x32_bf16 v[24:27], v[162:165], v[202:205], v[24:27]
	v_mfma_f32_16x16x32_bf16 v[12:15], v[146:149], v[210:213], v[12:15]
	v_mfma_f32_16x16x32_bf16 v[8:11], v[162:165], v[210:213], v[8:11]
	v_mfma_f32_16x16x32_bf16 v[60:63], v[158:161], v[190:193], v[60:63]
	v_mfma_f32_16x16x32_bf16 v[56:59], v[166:169], v[190:193], v[56:59]
	v_mfma_f32_16x16x32_bf16 v[44:47], v[158:161], v[198:201], v[44:47]
	v_mfma_f32_16x16x32_bf16 v[40:43], v[166:169], v[198:201], v[40:43]
	v_mfma_f32_16x16x32_bf16 v[28:31], v[158:161], v[206:209], v[28:31]
	v_mfma_f32_16x16x32_bf16 v[24:27], v[166:169], v[206:209], v[24:27]
	v_mfma_f32_16x16x32_bf16 v[12:15], v[158:161], v[214:217], v[12:15]
	v_mfma_f32_16x16x32_bf16 v[8:11], v[166:169], v[214:217], v[8:11]
	s_setprio 0
	s_setprio 1
	v_mfma_f32_16x16x32_bf16 v[52:55], v[170:173], v[186:189], v[52:55]
	v_mfma_f32_16x16x32_bf16 v[48:51], v[178:181], v[186:189], v[48:51]
	v_mfma_f32_16x16x32_bf16 v[36:39], v[170:173], v[194:197], v[36:39]
	v_mfma_f32_16x16x32_bf16 v[32:35], v[178:181], v[194:197], v[32:35]
	v_mfma_f32_16x16x32_bf16 v[20:23], v[170:173], v[202:205], v[20:23]
	v_mfma_f32_16x16x32_bf16 v[16:19], v[178:181], v[202:205], v[16:19]
	v_mfma_f32_16x16x32_bf16 v[4:7], v[170:173], v[210:213], v[4:7]
	v_mfma_f32_16x16x32_bf16 v[0:3], v[178:181], v[210:213], v[0:3]
	v_mfma_f32_16x16x32_bf16 v[52:55], v[174:177], v[190:193], v[52:55]
	v_mfma_f32_16x16x32_bf16 v[48:51], v[182:185], v[190:193], v[48:51]
	v_mfma_f32_16x16x32_bf16 v[36:39], v[174:177], v[198:201], v[36:39]
	v_mfma_f32_16x16x32_bf16 v[32:35], v[182:185], v[198:201], v[32:35]
	v_mfma_f32_16x16x32_bf16 v[20:23], v[174:177], v[206:209], v[20:23]
	v_mfma_f32_16x16x32_bf16 v[16:19], v[182:185], v[206:209], v[16:19]
	v_mfma_f32_16x16x32_bf16 v[4:7], v[174:177], v[214:217], v[4:7]
	v_mfma_f32_16x16x32_bf16 v[0:3], v[182:185], v[214:217], v[0:3]
	s_setprio 0
	s_barrier
	s_add_i32 s64, 0, 0x18000
	v_add_u32_e32 v157, s64, v152
	s_add_i32 s65, 0, 0x1c000
	ds_read_b128 v[146:149], v157
	ds_read_b128 v[158:161], v157 offset:1024
	ds_read_b128 v[162:165], v157 offset:2048
	ds_read_b128 v[166:169], v157 offset:3072
	v_add_u32_e32 v157, s65, v152
	ds_read_b128 v[170:173], v157
	ds_read_b128 v[174:177], v157 offset:1024
	ds_read_b128 v[178:181], v157 offset:2048
	ds_read_b128 v[182:185], v157 offset:3072
	s_add_u32 s38, s38, 0x160000
	s_addc_u32 s39, s39, 0
	s_mov_b32 m0, s45
	v_lshl_add_u64 v[226:227], s[38:39], 0, v[128:129]
	ds_read_b128 v[186:189], v155 offset:32768
	ds_read_b128 v[190:193], v155 offset:33792
	ds_read_b128 v[194:197], v155 offset:34816
	ds_read_b128 v[198:201], v155 offset:35840
	ds_read_b128 v[202:205], v155 offset:36864
	ds_read_b128 v[206:209], v155 offset:37888
	ds_read_b128 v[210:213], v155 offset:38912
	ds_read_b128 v[214:217], v155 offset:39936
	global_load_lds_dwordx4 v[226:227], off
	v_lshl_add_u64 v[226:227], s[38:39], 0, v[132:133]
	s_mov_b32 m0, s46
	s_nop 0
	global_load_lds_dwordx4 v[226:227], off
	s_waitcnt vmcnt(8)
	s_waitcnt lgkmcnt(0)
	s_barrier
	s_setprio 1
	v_mfma_f32_16x16x32_bf16 v[124:127], v[146:149], v[186:189], v[124:127]
	v_mfma_f32_16x16x32_bf16 v[120:123], v[162:165], v[186:189], v[120:123]
	v_mfma_f32_16x16x32_bf16 v[108:111], v[146:149], v[194:197], v[108:111]
	v_mfma_f32_16x16x32_bf16 v[104:107], v[162:165], v[194:197], v[104:107]
	v_mfma_f32_16x16x32_bf16 v[92:95], v[146:149], v[202:205], v[92:95]
	v_mfma_f32_16x16x32_bf16 v[88:91], v[162:165], v[202:205], v[88:91]
	v_mfma_f32_16x16x32_bf16 v[76:79], v[146:149], v[210:213], v[76:79]
	v_mfma_f32_16x16x32_bf16 v[72:75], v[162:165], v[210:213], v[72:75]
	v_mfma_f32_16x16x32_bf16 v[124:127], v[158:161], v[190:193], v[124:127]
	v_mfma_f32_16x16x32_bf16 v[120:123], v[166:169], v[190:193], v[120:123]
	v_mfma_f32_16x16x32_bf16 v[108:111], v[158:161], v[198:201], v[108:111]
	v_mfma_f32_16x16x32_bf16 v[104:107], v[166:169], v[198:201], v[104:107]
	v_mfma_f32_16x16x32_bf16 v[92:95], v[158:161], v[206:209], v[92:95]
	v_mfma_f32_16x16x32_bf16 v[88:91], v[166:169], v[206:209], v[88:91]
	v_mfma_f32_16x16x32_bf16 v[76:79], v[158:161], v[214:217], v[76:79]
	v_mfma_f32_16x16x32_bf16 v[72:75], v[166:169], v[214:217], v[72:75]
	s_setprio 0
	s_setprio 1
	v_mfma_f32_16x16x32_bf16 v[116:119], v[170:173], v[186:189], v[116:119]
	v_mfma_f32_16x16x32_bf16 v[112:115], v[178:181], v[186:189], v[112:115]
	v_mfma_f32_16x16x32_bf16 v[100:103], v[170:173], v[194:197], v[100:103]
	v_mfma_f32_16x16x32_bf16 v[96:99], v[178:181], v[194:197], v[96:99]
	v_mfma_f32_16x16x32_bf16 v[84:87], v[170:173], v[202:205], v[84:87]
	v_mfma_f32_16x16x32_bf16 v[80:83], v[178:181], v[202:205], v[80:83]
	v_mfma_f32_16x16x32_bf16 v[68:71], v[170:173], v[210:213], v[68:71]
	v_mfma_f32_16x16x32_bf16 v[64:67], v[178:181], v[210:213], v[64:67]
	v_mfma_f32_16x16x32_bf16 v[116:119], v[174:177], v[190:193], v[116:119]
	v_mfma_f32_16x16x32_bf16 v[112:115], v[182:185], v[190:193], v[112:115]
	v_mfma_f32_16x16x32_bf16 v[100:103], v[174:177], v[198:201], v[100:103]
	v_mfma_f32_16x16x32_bf16 v[96:99], v[182:185], v[198:201], v[96:99]
	v_mfma_f32_16x16x32_bf16 v[84:87], v[174:177], v[206:209], v[84:87]
	v_mfma_f32_16x16x32_bf16 v[80:83], v[182:185], v[206:209], v[80:83]
	v_mfma_f32_16x16x32_bf16 v[68:71], v[174:177], v[214:217], v[68:71]
	v_mfma_f32_16x16x32_bf16 v[64:67], v[182:185], v[214:217], v[64:67]
	s_setprio 0
	s_barrier
; #define PG8_STAGE(bufoff, gbase, voff) do { _Pragma("unroll") for (int _i = 0; _i < 2; ++_i) \
;         __builtin_amdgcn_global_load_lds((const unsigned*)((const char*)(gbase) + (voff)[_i]), (PG8_LAS unsigned*)(lds + (bufoff) + ldsw + _i * 8192), 16, 0, 0); } while (0)
; #define PG8_LDA(dst, b, h) do { _Pragma("unroll") for (int m = 0; m < 4; ++m) _Pragma("unroll") for (int k = 0; k < 2; ++k) dst[m][k] = *(const PG8_LAS bf16x8*)(lds + PG8_SA(b, h) + aoff + m * 2048 + k * 1024); } while (0)
; #define PG8_MMA(ai, bj, At, Bt) do { __builtin_amdgcn_s_setprio(1); _Pragma("unroll") for (int m = 0; m < 4; ++m) _Pragma("unroll") for (int n = 0; n < 2; ++n) _Pragma("unroll") for (int k = 0; k < 2; ++k) \
;         acc[ai][bj][m][n] = __builtin_amdgcn_mfma_f32_16x16x32_bf16(Bt[n][k], At[m][k], acc[ai][bj][m][n], 0, 0, 0); __builtin_amdgcn_s_setprio(0); } while (0)
; #define PG8_WAIT_V(n) asm volatile("s_waitcnt vmcnt(" #n ")" ::: "memory")
; #define PG8_WAIT_L(n) asm volatile("s_waitcnt lgkmcnt(" #n ")" ::: "memory")
; #define PG8_BAR __builtin_amdgcn_s_barrier()
; #define PG8_SCHED __builtin_amdgcn_sched_barrier(0)
; template <class Epi, class Sched, bool ALIGN_EPI = false, bool SP2 = false>
; __device__ __forceinline__ void gemm_phase(PG8_LAS unsigned char* lds, const Gemm g, const Sched& S, const Epi& E) {
;     ...
;             PG8_LDA(At, 1, 1); PG8_STAGE(PG8_SB(1, 0), b3, voffB); PG8_STAGE(PG8_SB(1, 1), b3 + hstep, voffB); PG8_STAGE(PG8_SA(1, 0), a3, voffA);
;             PG8_WAIT_V(8); PG8_WAIT_L(0); PG8_BAR; PG8_MMA(1, 0, At, B0); PG8_MMA(1, 1, At, B1); PG8_BAR; PG8_SCHED;
;     ...
;         if constexpr (ALIGN_EPI) { if (wr == 0) PG8_BAR; }
	s_add_i32 s38, s64, s42
	v_lshl_add_u64 v[218:219], v[218:219], 0, s[16:17]
	s_mov_b32 m0, s38
	ds_read_b128 v[186:189], v155 offset:49152
	ds_read_b128 v[190:193], v155 offset:50176
	ds_read_b128 v[194:197], v155 offset:51200
	ds_read_b128 v[198:201], v155 offset:52224
	ds_read_b128 v[202:205], v155 offset:53248
	ds_read_b128 v[206:209], v155 offset:54272
	ds_read_b128 v[210:213], v155 offset:55296
	ds_read_b128 v[214:217], v155 offset:56320
	global_load_lds_dwordx4 v[218:219], off
	s_add_i32 m0, s38, 0x2000
	s_add_u32 s36, s36, 0x160080
	v_lshl_add_u64 v[218:219], v[220:221], 0, s[16:17]
	s_addc_u32 s37, s37, 0
	s_add_i32 s38, s65, s42
	global_load_lds_dwordx4 v[218:219], off
	v_lshl_add_u64 v[218:219], s[36:37], 0, v[130:131]
	s_mov_b32 m0, s38
	s_nop 0
	global_load_lds_dwordx4 v[218:219], off
	v_lshl_add_u64 v[218:219], s[36:37], 0, v[134:135]
	s_add_i32 m0, s38, 0x2000
	s_nop 0
	global_load_lds_dwordx4 v[218:219], off
	v_lshl_add_u64 v[218:219], v[222:223], 0, s[16:17]
	s_mov_b32 m0, s52
	s_nop 0
	global_load_lds_dwordx4 v[218:219], off
	v_lshl_add_u64 v[218:219], v[224:225], 0, s[16:17]
	s_mov_b32 m0, s53
	s_nop 0
	global_load_lds_dwordx4 v[218:219], off
	s_waitcnt vmcnt(8)
	s_waitcnt lgkmcnt(0)
	s_barrier
	s_setprio 1
	v_mfma_f32_16x16x32_bf16 v[60:63], v[146:149], v[186:189], v[60:63]
	v_mfma_f32_16x16x32_bf16 v[56:59], v[162:165], v[186:189], v[56:59]
	v_mfma_f32_16x16x32_bf16 v[44:47], v[146:149], v[194:197], v[44:47]
	v_mfma_f32_16x16x32_bf16 v[40:43], v[162:165], v[194:197], v[40:43]
	v_mfma_f32_16x16x32_bf16 v[28:31], v[146:149], v[202:205], v[28:31]
	v_mfma_f32_16x16x32_bf16 v[24:27], v[162:165], v[202:205], v[24:27]
	v_mfma_f32_16x16x32_bf16 v[12:15], v[146:149], v[210:213], v[12:15]
	v_mfma_f32_16x16x32_bf16 v[8:11], v[162:165], v[210:213], v[8:11]
	v_mfma_f32_16x16x32_bf16 v[60:63], v[158:161], v[190:193], v[60:63]
	v_mfma_f32_16x16x32_bf16 v[56:59], v[166:169], v[190:193], v[56:59]
	v_mfma_f32_16x16x32_bf16 v[44:47], v[158:161], v[198:201], v[44:47]
	v_mfma_f32_16x16x32_bf16 v[40:43], v[166:169], v[198:201], v[40:43]
	v_mfma_f32_16x16x32_bf16 v[28:31], v[158:161], v[206:209], v[28:31]
	v_mfma_f32_16x16x32_bf16 v[24:27], v[166:169], v[206:209], v[24:27]
	v_mfma_f32_16x16x32_bf16 v[12:15], v[158:161], v[214:217], v[12:15]
	v_mfma_f32_16x16x32_bf16 v[8:11], v[166:169], v[214:217], v[8:11]
	s_setprio 0
	s_setprio 1
	v_mfma_f32_16x16x32_bf16 v[52:55], v[170:173], v[186:189], v[52:55]
	v_mfma_f32_16x16x32_bf16 v[48:51], v[178:181], v[186:189], v[48:51]
	v_mfma_f32_16x16x32_bf16 v[36:39], v[170:173], v[194:197], v[36:39]
	v_mfma_f32_16x16x32_bf16 v[32:35], v[178:181], v[194:197], v[32:35]
	v_mfma_f32_16x16x32_bf16 v[20:23], v[170:173], v[202:205], v[20:23]
	v_mfma_f32_16x16x32_bf16 v[16:19], v[178:181], v[202:205], v[16:19]
	v_mfma_f32_16x16x32_bf16 v[4:7], v[170:173], v[210:213], v[4:7]
	v_mfma_f32_16x16x32_bf16 v[0:3], v[178:181], v[210:213], v[0:3]
	v_mfma_f32_16x16x32_bf16 v[52:55], v[174:177], v[190:193], v[52:55]
	v_mfma_f32_16x16x32_bf16 v[48:51], v[182:185], v[190:193], v[48:51]
	v_mfma_f32_16x16x32_bf16 v[36:39], v[174:177], v[198:201], v[36:39]
	v_mfma_f32_16x16x32_bf16 v[32:35], v[182:185], v[198:201], v[32:35]
	v_mfma_f32_16x16x32_bf16 v[20:23], v[174:177], v[206:209], v[20:23]
	v_mfma_f32_16x16x32_bf16 v[16:19], v[182:185], v[206:209], v[16:19]
	v_mfma_f32_16x16x32_bf16 v[4:7], v[174:177], v[214:217], v[4:7]
	v_mfma_f32_16x16x32_bf16 v[0:3], v[182:185], v[214:217], v[0:3]
	s_setprio 0
	s_barrier
	s_add_i32 s63, s63, 2
	s_add_u32 s22, s22, 0x100
	s_addc_u32 s23, s23, 0
	s_add_u32 s61, s61, 0x100
	s_addc_u32 s62, s62, 0
	s_cmpk_gt_u32 s63, 0x55
	s_cbranch_scc0 .LBB0_1924
	s_and_b64 vcc, exec, s[18:19]
	s_cbranch_vccz .LBB0_1927
	s_barrier
